# batched widen gate flush + batched ple epilogue + NORM GEMM loops (in-proj, MLP-up) rescheduled: ssq VALU interleaved under LDS latency, B/A prefetch loads issued earlier
# speedup vs baseline: 1.5706x; 1.0780x over previous
; #define EPI_BEGIN(accv) EPI_BEGINM(accv, 2)
; DI float sigmoidf_(float v) { return 1.f / (1.f + __expf(-v)); }
; DI void phase_ple(const Params& p, int L, char* smem) {
;     ...
;     gemm_core<true>(p.xb, D, p.wt_pg, D, D, m0, n0, gt, smem);
;     EPI_BEGIN(gt) gt[mt][nt][i] = sigmoidf_(v * rstd_s[rl]); EPI_END
.LBB0_11:
	s_or_b64 exec, exec, s[2:3]
	s_waitcnt lgkmcnt(0)
	s_barrier
	ds_read_b128 v[68:71], v158 offset:55296
	ds_read_b128 v[64:67], v158 offset:55328
	v_readlane_b32 s16, v253, 48
	v_mov_b32_e32 v105, v189
	v_readlane_b32 s30, v253, 62
	s_waitcnt lgkmcnt(1)
	v_mul_f32_e32 v48, v48, v68
	v_mul_f32_e32 v48, 0xbfb8aa3b, v48
	v_exp_f32_e32 v48, v48
	v_mul_f32_e32 v32, v32, v68
	v_mul_f32_e32 v32, 0xbfb8aa3b, v32
	v_exp_f32_e32 v32, v32
	v_add_f32_e32 v48, 1.0, v48
	s_waitcnt vmcnt(3)
	v_div_scale_f32 v72, s[2:3], v48, v48, 1.0
	v_rcp_f32_e32 v73, v72
	v_add_f32_e32 v32, 1.0, v32
	v_readlane_b32 s31, v253, 63
	s_mov_b32 s7, 0xfffffc0
	v_fma_f32 v74, -v72, v73, 1.0
	v_fmac_f32_e32 v73, v74, v73
	v_div_scale_f32 v74, vcc, 1.0, v48, 1.0
	v_mul_f32_e32 v75, v74, v73
	s_waitcnt vmcnt(2)
	v_fma_f32 v76, -v72, v75, v74
	v_fmac_f32_e32 v75, v76, v73
	v_fma_f32 v72, -v72, v75, v74
	v_div_fmas_f32 v72, v72, v73, v75
	v_div_fixup_f32 v110, v72, v48, 1.0
	v_mul_f32_e32 v48, v49, v69
	v_mul_f32_e32 v48, 0xbfb8aa3b, v48
	v_exp_f32_e32 v48, v48
	s_movk_i32 s6, 0x90
	v_readlane_b32 s52, v253, 32
	v_readlane_b32 s64, v253, 44
	v_add_f32_e32 v48, 1.0, v48
	v_div_scale_f32 v49, s[2:3], v48, v48, 1.0
	v_rcp_f32_e32 v72, v49
	v_readlane_b32 s65, v253, 45
	v_readlane_b32 s28, v253, 60
	v_readlane_b32 s29, v253, 61
	v_fma_f32 v73, -v49, v72, 1.0
	v_fmac_f32_e32 v72, v73, v72
	v_div_scale_f32 v73, vcc, 1.0, v48, 1.0
	v_mul_f32_e32 v74, v73, v72
	v_fma_f32 v75, -v49, v74, v73
	v_fmac_f32_e32 v74, v75, v72
	v_fma_f32 v49, -v49, v74, v73
	v_div_fmas_f32 v49, v49, v72, v74
	v_div_fixup_f32 v114, v49, v48, 1.0
	v_mul_f32_e32 v48, v50, v70
	v_mul_f32_e32 v48, 0xbfb8aa3b, v48
	v_exp_f32_e32 v48, v48
	v_readlane_b32 s17, v253, 49
	v_readlane_b32 s18, v253, 50
	v_readlane_b32 s19, v253, 51
	v_add_f32_e32 v48, 1.0, v48
	v_div_scale_f32 v49, s[2:3], v48, v48, 1.0
	v_rcp_f32_e32 v50, v49
	v_readlane_b32 s20, v253, 52
	v_readlane_b32 s21, v253, 53
	v_readlane_b32 s22, v253, 54
	v_fma_f32 v72, -v49, v50, 1.0
	v_fmac_f32_e32 v50, v72, v50
	v_div_scale_f32 v72, vcc, 1.0, v48, 1.0
	v_mul_f32_e32 v73, v72, v50
	v_fma_f32 v74, -v49, v73, v72
	v_fmac_f32_e32 v73, v74, v50
	v_fma_f32 v49, -v49, v73, v72
	v_div_fmas_f32 v49, v49, v50, v73
	v_div_fixup_f32 v118, v49, v48, 1.0
	v_mul_f32_e32 v48, v51, v71
	v_mul_f32_e32 v48, 0xbfb8aa3b, v48
	v_exp_f32_e32 v48, v48
	v_readlane_b32 s23, v253, 55
	v_readlane_b32 s24, v253, 56
	v_readlane_b32 s25, v253, 57
	v_add_f32_e32 v48, 1.0, v48
	v_div_scale_f32 v49, s[2:3], v48, v48, 1.0
	v_rcp_f32_e32 v50, v49
	v_readlane_b32 s26, v253, 58
	v_readlane_b32 s27, v253, 59
	v_readlane_b32 s53, v253, 33
	v_fma_f32 v51, -v49, v50, 1.0
	v_fmac_f32_e32 v50, v51, v50
	v_div_scale_f32 v51, vcc, 1.0, v48, 1.0
	v_mul_f32_e32 v72, v51, v50
	v_fma_f32 v73, -v49, v72, v51
	v_fmac_f32_e32 v72, v73, v50
	v_fma_f32 v49, -v49, v72, v51
	v_div_fmas_f32 v49, v49, v50, v72
	v_div_fixup_f32 v117, v49, v48, 1.0
	s_waitcnt lgkmcnt(0)
	v_mul_f32_e32 v48, v52, v64
	v_mul_f32_e32 v48, 0xbfb8aa3b, v48
	v_exp_f32_e32 v48, v48
	v_readlane_b32 s54, v253, 34
	v_readlane_b32 s55, v253, 35
	v_readlane_b32 s56, v253, 36
	v_add_f32_e32 v48, 1.0, v48
	v_div_scale_f32 v49, s[2:3], v48, v48, 1.0
	v_rcp_f32_e32 v50, v49
	v_readlane_b32 s57, v253, 37
	v_readlane_b32 s58, v253, 38
	v_readlane_b32 s59, v253, 39
	v_fma_f32 v51, -v49, v50, 1.0
	v_fmac_f32_e32 v50, v51, v50
	v_div_scale_f32 v51, vcc, 1.0, v48, 1.0
	v_mul_f32_e32 v52, v51, v50
	v_fma_f32 v72, -v49, v52, v51
	v_fmac_f32_e32 v52, v72, v50
	v_fma_f32 v49, -v49, v52, v51
	v_div_fmas_f32 v49, v49, v50, v52
	v_div_fixup_f32 v119, v49, v48, 1.0
	v_mul_f32_e32 v48, v53, v65
	v_mul_f32_e32 v48, 0xbfb8aa3b, v48
	v_exp_f32_e32 v48, v48
	v_readlane_b32 s60, v253, 40
	v_readlane_b32 s61, v253, 41
	v_readlane_b32 s62, v253, 42
	v_add_f32_e32 v48, 1.0, v48
	v_div_scale_f32 v49, s[2:3], v48, v48, 1.0
	v_rcp_f32_e32 v50, v49
	v_readlane_b32 s63, v253, 43
	v_readlane_b32 s66, v253, 46
	v_readlane_b32 s67, v253, 47
	v_fma_f32 v51, -v49, v50, 1.0
	v_fmac_f32_e32 v50, v51, v50
	v_div_scale_f32 v51, vcc, 1.0, v48, 1.0
	v_mul_f32_e32 v52, v51, v50
	v_fma_f32 v53, -v49, v52, v51
	v_fmac_f32_e32 v52, v53, v50
	v_fma_f32 v49, -v49, v52, v51
	v_div_fmas_f32 v49, v49, v50, v52
	v_div_fixup_f32 v123, v49, v48, 1.0
	v_mul_f32_e32 v48, v54, v66
	v_mul_f32_e32 v48, 0xbfb8aa3b, v48
	v_exp_f32_e32 v48, v48
	s_nop 0
	v_add_f32_e32 v48, 1.0, v48
	v_div_scale_f32 v49, s[2:3], v48, v48, 1.0
	v_rcp_f32_e32 v50, v49
	s_nop 0
	v_fma_f32 v51, -v49, v50, 1.0
	v_fmac_f32_e32 v50, v51, v50
	v_div_scale_f32 v51, vcc, 1.0, v48, 1.0
	v_mul_f32_e32 v52, v51, v50
	v_fma_f32 v53, -v49, v52, v51
	v_fmac_f32_e32 v52, v53, v50
	v_fma_f32 v49, -v49, v52, v51
	v_div_fmas_f32 v49, v49, v50, v52
	v_div_fixup_f32 v125, v49, v48, 1.0
	v_mul_f32_e32 v48, v55, v67
	v_mul_f32_e32 v48, 0xbfb8aa3b, v48
	v_exp_f32_e32 v48, v48
	s_nop 0
	v_add_f32_e32 v48, 1.0, v48
	v_div_scale_f32 v49, s[2:3], v48, v48, 1.0
	v_rcp_f32_e32 v50, v49
	s_nop 0
	v_fma_f32 v51, -v49, v50, 1.0
	v_fmac_f32_e32 v50, v51, v50
	v_div_scale_f32 v51, vcc, 1.0, v48, 1.0
	v_mul_f32_e32 v52, v51, v50
	v_fma_f32 v53, -v49, v52, v51
	v_fmac_f32_e32 v52, v53, v50
	v_fma_f32 v49, -v49, v52, v51
	v_div_fmas_f32 v49, v49, v50, v52
	v_div_fixup_f32 v128, v49, v48, 1.0
	ds_read_b128 v[48:51], v158 offset:55360
	s_waitcnt lgkmcnt(0)
; #define EPI_BEGIN(accv) EPI_BEGINM(accv, 2)
; DI float sigmoidf_(float v) { return 1.f / (1.f + __expf(-v)); }
; DI void phase_ple(const Params& p, int L, char* smem) {
;     ...
;     EPI_BEGIN(gt) gt[mt][nt][i] = sigmoidf_(v * rstd_s[rl]); EPI_END
	v_mul_f32_e32 v52, v56, v48
	v_mul_f32_e32 v52, 0xbfb8aa3b, v52
	v_exp_f32_e32 v52, v52
	s_nop 0
	v_add_f32_e32 v52, 1.0, v52
	v_div_scale_f32 v53, s[2:3], v52, v52, 1.0
	v_rcp_f32_e32 v54, v53
	s_nop 0
	v_fma_f32 v55, -v53, v54, 1.0
	v_fmac_f32_e32 v54, v55, v54
	v_div_scale_f32 v55, vcc, 1.0, v52, 1.0
	v_mul_f32_e32 v56, v55, v54
	v_fma_f32 v72, -v53, v56, v55
	v_fmac_f32_e32 v56, v72, v54
	v_fma_f32 v53, -v53, v56, v55
	v_div_fmas_f32 v53, v53, v54, v56
	v_div_fixup_f32 v132, v53, v52, 1.0
	v_mul_f32_e32 v52, v57, v49
	v_mul_f32_e32 v52, 0xbfb8aa3b, v52
	v_exp_f32_e32 v52, v52
	s_nop 0
	v_add_f32_e32 v52, 1.0, v52
	v_div_scale_f32 v53, s[2:3], v52, v52, 1.0
	v_rcp_f32_e32 v54, v53
	s_nop 0
	v_fma_f32 v55, -v53, v54, 1.0
	v_fmac_f32_e32 v54, v55, v54
	v_div_scale_f32 v55, vcc, 1.0, v52, 1.0
	v_mul_f32_e32 v56, v55, v54
	v_fma_f32 v57, -v53, v56, v55
	v_fmac_f32_e32 v56, v57, v54
	v_fma_f32 v53, -v53, v56, v55
	v_div_fmas_f32 v53, v53, v54, v56
	v_div_fixup_f32 v133, v53, v52, 1.0
	v_mul_f32_e32 v52, v58, v50
	v_mul_f32_e32 v52, 0xbfb8aa3b, v52
	v_exp_f32_e32 v52, v52
	s_nop 0
	v_add_f32_e32 v52, 1.0, v52
	v_div_scale_f32 v53, s[2:3], v52, v52, 1.0
	v_rcp_f32_e32 v54, v53
	s_nop 0
	v_fma_f32 v55, -v53, v54, 1.0
	v_fmac_f32_e32 v54, v55, v54
	v_div_scale_f32 v55, vcc, 1.0, v52, 1.0
	v_mul_f32_e32 v56, v55, v54
	v_fma_f32 v57, -v53, v56, v55
	v_fmac_f32_e32 v56, v57, v54
	v_fma_f32 v53, -v53, v56, v55
	v_div_fmas_f32 v53, v53, v54, v56
	v_div_fixup_f32 v134, v53, v52, 1.0
	v_mul_f32_e32 v52, v59, v51
	v_mul_f32_e32 v52, 0xbfb8aa3b, v52
	v_exp_f32_e32 v52, v52
	s_nop 0
	v_add_f32_e32 v52, 1.0, v52
	v_div_scale_f32 v53, s[2:3], v52, v52, 1.0
	v_rcp_f32_e32 v54, v53
	s_nop 0
	v_fma_f32 v55, -v53, v54, 1.0
	v_fmac_f32_e32 v54, v55, v54
	v_div_scale_f32 v55, vcc, 1.0, v52, 1.0
	v_mul_f32_e32 v56, v55, v54
	v_fma_f32 v57, -v53, v56, v55
	v_fmac_f32_e32 v56, v57, v54
	v_fma_f32 v53, -v53, v56, v55
	v_div_fmas_f32 v53, v53, v54, v56
	v_div_fixup_f32 v135, v53, v52, 1.0
	ds_read_b128 v[52:55], v158 offset:55392
	s_waitcnt lgkmcnt(0)
	v_mul_f32_e32 v56, v60, v52
	v_mul_f32_e32 v56, 0xbfb8aa3b, v56
	v_exp_f32_e32 v56, v56
	s_nop 0
	v_add_f32_e32 v56, 1.0, v56
	v_div_scale_f32 v57, s[2:3], v56, v56, 1.0
	v_rcp_f32_e32 v58, v57
	s_nop 0
	v_fma_f32 v59, -v57, v58, 1.0
	v_fmac_f32_e32 v58, v59, v58
	v_div_scale_f32 v59, vcc, 1.0, v56, 1.0
	v_mul_f32_e32 v60, v59, v58
	v_fma_f32 v72, -v57, v60, v59
	v_fmac_f32_e32 v60, v72, v58
	v_fma_f32 v57, -v57, v60, v59
	v_div_fmas_f32 v57, v57, v58, v60
	v_div_fixup_f32 v161, v57, v56, 1.0
	v_mul_f32_e32 v56, v61, v53
	v_mul_f32_e32 v56, 0xbfb8aa3b, v56
	v_exp_f32_e32 v56, v56
	s_nop 0
	v_add_f32_e32 v56, 1.0, v56
	v_div_scale_f32 v57, s[2:3], v56, v56, 1.0
	v_rcp_f32_e32 v58, v57
	s_nop 0
	v_fma_f32 v59, -v57, v58, 1.0
	v_fmac_f32_e32 v58, v59, v58
	v_div_scale_f32 v59, vcc, 1.0, v56, 1.0
	v_mul_f32_e32 v60, v59, v58
	v_fma_f32 v61, -v57, v60, v59
	v_fmac_f32_e32 v60, v61, v58
	v_fma_f32 v57, -v57, v60, v59
	v_div_fmas_f32 v57, v57, v58, v60
	v_div_fixup_f32 v163, v57, v56, 1.0
	v_mul_f32_e32 v56, v62, v54
	v_mul_f32_e32 v56, 0xbfb8aa3b, v56
	v_exp_f32_e32 v56, v56
	s_nop 0
	v_add_f32_e32 v56, 1.0, v56
	v_div_scale_f32 v57, s[2:3], v56, v56, 1.0
	v_rcp_f32_e32 v58, v57
	s_nop 0
	v_fma_f32 v59, -v57, v58, 1.0
	v_fmac_f32_e32 v58, v59, v58
	v_div_scale_f32 v59, vcc, 1.0, v56, 1.0
	v_mul_f32_e32 v60, v59, v58
	v_fma_f32 v61, -v57, v60, v59
	v_fmac_f32_e32 v60, v61, v58
	v_fma_f32 v57, -v57, v60, v59
	v_div_fmas_f32 v57, v57, v58, v60
	v_div_fixup_f32 v165, v57, v56, 1.0
	v_mul_f32_e32 v56, v63, v55
	v_mul_f32_e32 v56, 0xbfb8aa3b, v56
	v_exp_f32_e32 v56, v56
	s_nop 0
	v_add_f32_e32 v56, 1.0, v56
	v_div_scale_f32 v57, s[2:3], v56, v56, 1.0
	v_rcp_f32_e32 v58, v57
	s_nop 0
	v_fma_f32 v59, -v57, v58, 1.0
	v_fmac_f32_e32 v58, v59, v58
	v_div_scale_f32 v59, vcc, 1.0, v56, 1.0
	v_mul_f32_e32 v60, v59, v58
	v_fma_f32 v61, -v57, v60, v59
	v_fmac_f32_e32 v60, v61, v58
	v_fma_f32 v57, -v57, v60, v59
	v_div_fmas_f32 v57, v57, v58, v60
	v_div_fixup_f32 v170, v57, v56, 1.0
	v_div_scale_f32 v56, s[2:3], v32, v32, 1.0
	v_rcp_f32_e32 v57, v56
	s_nop 0
	v_fma_f32 v58, -v56, v57, 1.0
	v_fmac_f32_e32 v57, v58, v57
	v_div_scale_f32 v58, vcc, 1.0, v32, 1.0
	v_mul_f32_e32 v59, v58, v57
	v_fma_f32 v60, -v56, v59, v58
	v_fmac_f32_e32 v59, v60, v57
	v_fma_f32 v56, -v56, v59, v58
	v_div_fmas_f32 v56, v56, v57, v59
	v_div_fixup_f32 v171, v56, v32, 1.0
	v_mul_f32_e32 v32, v33, v69
	v_mul_f32_e32 v32, 0xbfb8aa3b, v32
	v_exp_f32_e32 v32, v32
	s_nop 0
	v_add_f32_e32 v32, 1.0, v32
	v_div_scale_f32 v33, s[2:3], v32, v32, 1.0
	v_rcp_f32_e32 v56, v33
	s_nop 0
	v_fma_f32 v57, -v33, v56, 1.0
	v_fmac_f32_e32 v56, v57, v56
	v_div_scale_f32 v57, vcc, 1.0, v32, 1.0
	v_mul_f32_e32 v58, v57, v56
	v_fma_f32 v59, -v33, v58, v57
	v_fmac_f32_e32 v58, v59, v56
	v_fma_f32 v33, -v33, v58, v57
	v_div_fmas_f32 v33, v33, v56, v58
	v_div_fixup_f32 v172, v33, v32, 1.0
	v_mul_f32_e32 v32, v34, v70
	v_mul_f32_e32 v32, 0xbfb8aa3b, v32
	v_exp_f32_e32 v32, v32
	s_nop 0
	v_add_f32_e32 v32, 1.0, v32
	v_div_scale_f32 v33, s[2:3], v32, v32, 1.0
	v_rcp_f32_e32 v34, v33
	s_nop 0
	v_fma_f32 v56, -v33, v34, 1.0
	v_fmac_f32_e32 v34, v56, v34
	v_div_scale_f32 v56, vcc, 1.0, v32, 1.0
	v_mul_f32_e32 v57, v56, v34
	v_fma_f32 v58, -v33, v57, v56
	v_fmac_f32_e32 v57, v58, v34
	v_fma_f32 v33, -v33, v57, v56
	v_div_fmas_f32 v33, v33, v34, v57
	v_div_fixup_f32 v173, v33, v32, 1.0
	v_mul_f32_e32 v32, v35, v71
	v_mul_f32_e32 v32, 0xbfb8aa3b, v32
	v_exp_f32_e32 v32, v32
	s_nop 0
	v_add_f32_e32 v32, 1.0, v32
	v_div_scale_f32 v33, s[2:3], v32, v32, 1.0
	v_rcp_f32_e32 v34, v33
	s_nop 0
; #define EPI_BEGIN(accv) EPI_BEGINM(accv, 2)
; DI float sigmoidf_(float v) { return 1.f / (1.f + __expf(-v)); }
; DI void phase_ple(const Params& p, int L, char* smem) {
;     ...
;     EPI_BEGIN(gt) gt[mt][nt][i] = sigmoidf_(v * rstd_s[rl]); EPI_END
	v_fma_f32 v35, -v33, v34, 1.0
	v_fmac_f32_e32 v34, v35, v34
	v_div_scale_f32 v35, vcc, 1.0, v32, 1.0
	v_mul_f32_e32 v56, v35, v34
	v_fma_f32 v57, -v33, v56, v35
	v_fmac_f32_e32 v56, v57, v34
	v_fma_f32 v33, -v33, v56, v35
	v_div_fmas_f32 v33, v33, v34, v56
	v_div_fixup_f32 v142, v33, v32, 1.0
	v_mul_f32_e32 v32, v36, v64
	v_mul_f32_e32 v32, 0xbfb8aa3b, v32
	v_exp_f32_e32 v32, v32
	s_nop 0
	v_add_f32_e32 v32, 1.0, v32
	v_div_scale_f32 v33, s[2:3], v32, v32, 1.0
	v_rcp_f32_e32 v34, v33
	s_nop 0
	v_fma_f32 v35, -v33, v34, 1.0
	v_fmac_f32_e32 v34, v35, v34
	v_div_scale_f32 v35, vcc, 1.0, v32, 1.0
	v_mul_f32_e32 v36, v35, v34
	v_fma_f32 v56, -v33, v36, v35
	v_fmac_f32_e32 v36, v56, v34
	v_fma_f32 v33, -v33, v36, v35
	v_div_fmas_f32 v33, v33, v34, v36
	v_div_fixup_f32 v148, v33, v32, 1.0
	v_mul_f32_e32 v32, v37, v65
	v_mul_f32_e32 v32, 0xbfb8aa3b, v32
	v_exp_f32_e32 v32, v32
	s_nop 0
	v_add_f32_e32 v32, 1.0, v32
	v_div_scale_f32 v33, s[2:3], v32, v32, 1.0
	v_rcp_f32_e32 v34, v33
	s_nop 0
	v_fma_f32 v35, -v33, v34, 1.0
	v_fmac_f32_e32 v34, v35, v34
	v_div_scale_f32 v35, vcc, 1.0, v32, 1.0
	v_mul_f32_e32 v36, v35, v34
	v_fma_f32 v37, -v33, v36, v35
	v_fmac_f32_e32 v36, v37, v34
	v_fma_f32 v33, -v33, v36, v35
	v_div_fmas_f32 v33, v33, v34, v36
	v_div_fixup_f32 v153, v33, v32, 1.0
	v_mul_f32_e32 v32, v38, v66
	v_mul_f32_e32 v32, 0xbfb8aa3b, v32
	v_exp_f32_e32 v32, v32
	s_nop 0
	v_add_f32_e32 v32, 1.0, v32
	v_div_scale_f32 v33, s[2:3], v32, v32, 1.0
	v_rcp_f32_e32 v34, v33
	s_nop 0
	v_fma_f32 v35, -v33, v34, 1.0
	v_fmac_f32_e32 v34, v35, v34
	v_div_scale_f32 v35, vcc, 1.0, v32, 1.0
	v_mul_f32_e32 v36, v35, v34
	v_fma_f32 v37, -v33, v36, v35
	v_fmac_f32_e32 v36, v37, v34
	v_fma_f32 v33, -v33, v36, v35
	v_div_fmas_f32 v33, v33, v34, v36
	v_div_fixup_f32 v155, v33, v32, 1.0
	v_mul_f32_e32 v32, v39, v67
	v_mul_f32_e32 v32, 0xbfb8aa3b, v32
	v_exp_f32_e32 v32, v32
	s_nop 0
	v_add_f32_e32 v32, 1.0, v32
	v_div_scale_f32 v33, s[2:3], v32, v32, 1.0
	v_rcp_f32_e32 v34, v33
	s_nop 0
	v_fma_f32 v35, -v33, v34, 1.0
	v_fmac_f32_e32 v34, v35, v34
	v_div_scale_f32 v35, vcc, 1.0, v32, 1.0
	v_mul_f32_e32 v36, v35, v34
	v_fma_f32 v37, -v33, v36, v35
	v_fmac_f32_e32 v36, v37, v34
	v_fma_f32 v33, -v33, v36, v35
	v_div_fmas_f32 v33, v33, v34, v36
	v_div_fixup_f32 v138, v33, v32, 1.0
	v_mul_f32_e32 v32, v40, v48
	v_mul_f32_e32 v32, 0xbfb8aa3b, v32
	v_exp_f32_e32 v32, v32
	s_nop 0
	v_add_f32_e32 v32, 1.0, v32
	v_div_scale_f32 v33, s[2:3], v32, v32, 1.0
	v_rcp_f32_e32 v34, v33
	s_nop 0
	v_fma_f32 v35, -v33, v34, 1.0
	v_fmac_f32_e32 v34, v35, v34
	v_div_scale_f32 v35, vcc, 1.0, v32, 1.0
	v_mul_f32_e32 v36, v35, v34
	v_fma_f32 v37, -v33, v36, v35
	v_fmac_f32_e32 v36, v37, v34
	v_fma_f32 v33, -v33, v36, v35
	v_div_fmas_f32 v33, v33, v34, v36
	v_div_fixup_f32 v139, v33, v32, 1.0
	v_mul_f32_e32 v32, v41, v49
	v_mul_f32_e32 v32, 0xbfb8aa3b, v32
	v_exp_f32_e32 v32, v32
	s_nop 0
	v_add_f32_e32 v32, 1.0, v32
	v_div_scale_f32 v33, s[2:3], v32, v32, 1.0
	v_rcp_f32_e32 v34, v33
	s_nop 0
	v_fma_f32 v35, -v33, v34, 1.0
	v_fmac_f32_e32 v34, v35, v34
	v_div_scale_f32 v35, vcc, 1.0, v32, 1.0
	v_mul_f32_e32 v36, v35, v34
	v_fma_f32 v37, -v33, v36, v35
	v_fmac_f32_e32 v36, v37, v34
	v_fma_f32 v33, -v33, v36, v35
	v_div_fmas_f32 v33, v33, v34, v36
	v_div_fixup_f32 v143, v33, v32, 1.0
	v_mul_f32_e32 v32, v42, v50
	v_mul_f32_e32 v32, 0xbfb8aa3b, v32
	v_exp_f32_e32 v32, v32
	s_nop 0
	v_add_f32_e32 v32, 1.0, v32
	v_div_scale_f32 v33, s[2:3], v32, v32, 1.0
	v_rcp_f32_e32 v34, v33
	s_nop 0
	v_fma_f32 v35, -v33, v34, 1.0
	v_fmac_f32_e32 v34, v35, v34
	v_div_scale_f32 v35, vcc, 1.0, v32, 1.0
	v_mul_f32_e32 v36, v35, v34
	v_fma_f32 v37, -v33, v36, v35
	v_fmac_f32_e32 v36, v37, v34
	v_fma_f32 v33, -v33, v36, v35
	v_div_fmas_f32 v33, v33, v34, v36
	v_div_fixup_f32 v149, v33, v32, 1.0
	v_mul_f32_e32 v32, v43, v51
	v_mul_f32_e32 v32, 0xbfb8aa3b, v32
	v_exp_f32_e32 v32, v32
	s_nop 0
	v_add_f32_e32 v32, 1.0, v32
	v_div_scale_f32 v33, s[2:3], v32, v32, 1.0
	v_rcp_f32_e32 v34, v33
	s_nop 0
	v_fma_f32 v35, -v33, v34, 1.0
	v_fmac_f32_e32 v34, v35, v34
	v_div_scale_f32 v35, vcc, 1.0, v32, 1.0
	v_mul_f32_e32 v36, v35, v34
	v_fma_f32 v37, -v33, v36, v35
	v_fmac_f32_e32 v36, v37, v34
	v_fma_f32 v33, -v33, v36, v35
	v_div_fmas_f32 v33, v33, v34, v36
	v_div_fixup_f32 v140, v33, v32, 1.0
	v_mul_f32_e32 v32, v44, v52
	v_mul_f32_e32 v32, 0xbfb8aa3b, v32
	v_exp_f32_e32 v32, v32
	s_nop 0
	v_add_f32_e32 v32, 1.0, v32
	v_div_scale_f32 v33, s[2:3], v32, v32, 1.0
	v_rcp_f32_e32 v34, v33
	s_nop 0
	v_fma_f32 v35, -v33, v34, 1.0
	v_fmac_f32_e32 v34, v35, v34
	v_div_scale_f32 v35, vcc, 1.0, v32, 1.0
	v_mul_f32_e32 v36, v35, v34
	v_fma_f32 v37, -v33, v36, v35
	v_fmac_f32_e32 v36, v37, v34
	v_fma_f32 v33, -v33, v36, v35
	v_div_fmas_f32 v33, v33, v34, v36
	v_div_fixup_f32 v144, v33, v32, 1.0
	v_mul_f32_e32 v32, v45, v53
	v_mul_f32_e32 v32, 0xbfb8aa3b, v32
	v_exp_f32_e32 v32, v32
	s_nop 0
	v_add_f32_e32 v32, 1.0, v32
	v_div_scale_f32 v33, s[2:3], v32, v32, 1.0
	v_rcp_f32_e32 v34, v33
	s_nop 0
	v_fma_f32 v35, -v33, v34, 1.0
	v_fmac_f32_e32 v34, v35, v34
	v_div_scale_f32 v35, vcc, 1.0, v32, 1.0
	v_mul_f32_e32 v36, v35, v34
	v_fma_f32 v37, -v33, v36, v35
	v_fmac_f32_e32 v36, v37, v34
	v_fma_f32 v33, -v33, v36, v35
	v_div_fmas_f32 v33, v33, v34, v36
	v_div_fixup_f32 v151, v33, v32, 1.0
	v_mul_f32_e32 v32, v46, v54
	v_mul_f32_e32 v32, 0xbfb8aa3b, v32
	v_exp_f32_e32 v32, v32
	s_nop 0
	v_add_f32_e32 v32, 1.0, v32
	v_div_scale_f32 v33, s[2:3], v32, v32, 1.0
	v_rcp_f32_e32 v34, v33
	s_nop 0
	v_fma_f32 v35, -v33, v34, 1.0
	v_fmac_f32_e32 v34, v35, v34
	v_div_scale_f32 v35, vcc, 1.0, v32, 1.0
	v_mul_f32_e32 v36, v35, v34
	v_fma_f32 v37, -v33, v36, v35
	v_fmac_f32_e32 v36, v37, v34
	v_fma_f32 v33, -v33, v36, v35
	v_div_fmas_f32 v33, v33, v34, v36
	v_div_fixup_f32 v154, v33, v32, 1.0
	v_mul_f32_e32 v32, v47, v55
	v_mul_f32_e32 v32, 0xbfb8aa3b, v32
	v_exp_f32_e32 v32, v32
	s_nop 0
	v_add_f32_e32 v32, 1.0, v32
	v_div_scale_f32 v33, s[2:3], v32, v32, 1.0
	v_rcp_f32_e32 v34, v33
	s_nop 0
	v_fma_f32 v35, -v33, v34, 1.0
	v_fmac_f32_e32 v34, v35, v34
	v_div_scale_f32 v35, vcc, 1.0, v32, 1.0
	v_mul_f32_e32 v36, v35, v34
	v_fma_f32 v37, -v33, v36, v35
	v_fmac_f32_e32 v36, v37, v34
	v_fma_f32 v33, -v33, v36, v35
	v_div_fmas_f32 v33, v33, v34, v36
	v_div_fixup_f32 v145, v33, v32, 1.0
	ds_read_b128 v[32:35], v158 offset:55424
	s_waitcnt lgkmcnt(0)
; #define EPI_BEGIN(accv) EPI_BEGINM(accv, 2)
; DI float sigmoidf_(float v) { return 1.f / (1.f + __expf(-v)); }
; DI void phase_ple(const Params& p, int L, char* smem) {
;     ...
;     EPI_BEGIN(gt) gt[mt][nt][i] = sigmoidf_(v * rstd_s[rl]); EPI_END
	v_mul_f32_e32 v16, v16, v32
	v_mul_f32_e32 v16, 0xbfb8aa3b, v16
	v_exp_f32_e32 v16, v16
	v_mul_f32_e32 v0, v0, v32
	v_mul_f32_e32 v0, 0xbfb8aa3b, v0
	v_exp_f32_e32 v0, v0
	v_add_f32_e32 v16, 1.0, v16
	v_div_scale_f32 v36, s[2:3], v16, v16, 1.0
	v_rcp_f32_e32 v37, v36
	v_add_f32_e32 v0, 1.0, v0
	v_fma_f32 v38, -v36, v37, 1.0
	v_fmac_f32_e32 v37, v38, v37
	v_div_scale_f32 v38, vcc, 1.0, v16, 1.0
	v_mul_f32_e32 v39, v38, v37
	v_fma_f32 v40, -v36, v39, v38
	v_fmac_f32_e32 v39, v40, v37
	v_fma_f32 v36, -v36, v39, v38
	v_div_fmas_f32 v36, v36, v37, v39
	v_div_fixup_f32 v141, v36, v16, 1.0
	v_mul_f32_e32 v16, v17, v33
	v_mul_f32_e32 v16, 0xbfb8aa3b, v16
	v_exp_f32_e32 v16, v16
	s_nop 0
	v_add_f32_e32 v16, 1.0, v16
	v_div_scale_f32 v17, s[2:3], v16, v16, 1.0
	v_rcp_f32_e32 v36, v17
	s_nop 0
	v_fma_f32 v37, -v17, v36, 1.0
	v_fmac_f32_e32 v36, v37, v36
	v_div_scale_f32 v37, vcc, 1.0, v16, 1.0
	v_mul_f32_e32 v38, v37, v36
	v_fma_f32 v39, -v17, v38, v37
	v_fmac_f32_e32 v38, v39, v36
	v_fma_f32 v17, -v17, v38, v37
	v_div_fmas_f32 v17, v17, v36, v38
	v_div_fixup_f32 v137, v17, v16, 1.0
	v_mul_f32_e32 v16, v18, v34
	v_mul_f32_e32 v16, 0xbfb8aa3b, v16
	v_exp_f32_e32 v16, v16
	s_nop 0
	v_add_f32_e32 v16, 1.0, v16
	v_div_scale_f32 v17, s[2:3], v16, v16, 1.0
	v_rcp_f32_e32 v18, v17
	s_nop 0
	v_fma_f32 v36, -v17, v18, 1.0
	v_fmac_f32_e32 v18, v36, v18
	v_div_scale_f32 v36, vcc, 1.0, v16, 1.0
	v_mul_f32_e32 v37, v36, v18
	v_fma_f32 v38, -v17, v37, v36
	v_fmac_f32_e32 v37, v38, v18
	v_fma_f32 v17, -v17, v37, v36
	v_div_fmas_f32 v17, v17, v18, v37
	v_div_fixup_f32 v136, v17, v16, 1.0
	v_mul_f32_e32 v16, v19, v35
	v_mul_f32_e32 v16, 0xbfb8aa3b, v16
	v_exp_f32_e32 v16, v16
	s_nop 0
	v_add_f32_e32 v16, 1.0, v16
	v_div_scale_f32 v17, s[2:3], v16, v16, 1.0
	v_rcp_f32_e32 v18, v17
	s_nop 0
	v_fma_f32 v19, -v17, v18, 1.0
	v_fmac_f32_e32 v18, v19, v18
	v_div_scale_f32 v19, vcc, 1.0, v16, 1.0
	v_mul_f32_e32 v36, v19, v18
	v_fma_f32 v37, -v17, v36, v19
	v_fmac_f32_e32 v36, v37, v18
	v_fma_f32 v17, -v17, v36, v19
	v_div_fmas_f32 v17, v17, v18, v36
	v_div_fixup_f32 v126, v17, v16, 1.0
	ds_read_b128 v[16:19], v158 offset:55456
	s_waitcnt lgkmcnt(0)
	v_mul_f32_e32 v20, v20, v16
	v_mul_f32_e32 v20, 0xbfb8aa3b, v20
	v_exp_f32_e32 v20, v20
	s_nop 0
	v_add_f32_e32 v20, 1.0, v20
	v_div_scale_f32 v36, s[2:3], v20, v20, 1.0
	v_rcp_f32_e32 v37, v36
	s_nop 0
	v_fma_f32 v38, -v36, v37, 1.0
	v_fmac_f32_e32 v37, v38, v37
	v_div_scale_f32 v38, vcc, 1.0, v20, 1.0
	v_mul_f32_e32 v39, v38, v37
	v_fma_f32 v40, -v36, v39, v38
	v_fmac_f32_e32 v39, v40, v37
	v_fma_f32 v36, -v36, v39, v38
	v_div_fmas_f32 v36, v36, v37, v39
	v_div_fixup_f32 v159, v36, v20, 1.0
	v_mul_f32_e32 v20, v21, v17
	v_mul_f32_e32 v20, 0xbfb8aa3b, v20
	v_exp_f32_e32 v20, v20
	s_nop 0
	v_add_f32_e32 v20, 1.0, v20
	v_div_scale_f32 v21, s[2:3], v20, v20, 1.0
	v_rcp_f32_e32 v36, v21
	s_nop 0
	v_fma_f32 v37, -v21, v36, 1.0
	v_fmac_f32_e32 v36, v37, v36
	v_div_scale_f32 v37, vcc, 1.0, v20, 1.0
	v_mul_f32_e32 v38, v37, v36
	v_fma_f32 v39, -v21, v38, v37
	v_fmac_f32_e32 v38, v39, v36
	v_fma_f32 v21, -v21, v38, v37
	v_div_fmas_f32 v21, v21, v36, v38
	v_div_fixup_f32 v160, v21, v20, 1.0
	v_mul_f32_e32 v20, v22, v18
	v_mul_f32_e32 v20, 0xbfb8aa3b, v20
	v_exp_f32_e32 v20, v20
	s_nop 0
	v_add_f32_e32 v20, 1.0, v20
	v_div_scale_f32 v21, s[2:3], v20, v20, 1.0
	v_rcp_f32_e32 v22, v21
	s_nop 0
	v_fma_f32 v36, -v21, v22, 1.0
	v_fmac_f32_e32 v22, v36, v22
	v_div_scale_f32 v36, vcc, 1.0, v20, 1.0
	v_mul_f32_e32 v37, v36, v22
	v_fma_f32 v38, -v21, v37, v36
	v_fmac_f32_e32 v37, v38, v22
	v_fma_f32 v21, -v21, v37, v36
	v_div_fmas_f32 v21, v21, v22, v37
	v_div_fixup_f32 v162, v21, v20, 1.0
	v_mul_f32_e32 v20, v23, v19
	v_mul_f32_e32 v20, 0xbfb8aa3b, v20
	v_exp_f32_e32 v20, v20
	s_nop 0
	v_add_f32_e32 v20, 1.0, v20
	v_div_scale_f32 v21, s[2:3], v20, v20, 1.0
	v_rcp_f32_e32 v22, v21
	s_nop 0
	v_fma_f32 v23, -v21, v22, 1.0
	v_fmac_f32_e32 v22, v23, v22
	v_div_scale_f32 v23, vcc, 1.0, v20, 1.0
	v_mul_f32_e32 v36, v23, v22
	v_fma_f32 v37, -v21, v36, v23
	v_fmac_f32_e32 v36, v37, v22
	v_fma_f32 v21, -v21, v36, v23
	v_div_fmas_f32 v21, v21, v22, v36
	v_div_fixup_f32 v164, v21, v20, 1.0
	ds_read_b128 v[20:23], v158 offset:55488
	s_waitcnt lgkmcnt(0)
	v_mul_f32_e32 v24, v24, v20
	v_mul_f32_e32 v24, 0xbfb8aa3b, v24
	v_exp_f32_e32 v24, v24
	s_nop 0
	v_add_f32_e32 v24, 1.0, v24
	v_div_scale_f32 v36, s[2:3], v24, v24, 1.0
	v_rcp_f32_e32 v37, v36
	s_nop 0
	v_fma_f32 v38, -v36, v37, 1.0
	v_fmac_f32_e32 v37, v38, v37
	v_div_scale_f32 v38, vcc, 1.0, v24, 1.0
	v_mul_f32_e32 v39, v38, v37
	v_fma_f32 v40, -v36, v39, v38
	v_fmac_f32_e32 v39, v40, v37
	v_fma_f32 v36, -v36, v39, v38
	v_div_fmas_f32 v36, v36, v37, v39
	v_div_fixup_f32 v166, v36, v24, 1.0
	v_mul_f32_e32 v24, v25, v21
	v_mul_f32_e32 v24, 0xbfb8aa3b, v24
	v_exp_f32_e32 v24, v24
	s_nop 0
	v_add_f32_e32 v24, 1.0, v24
	v_div_scale_f32 v25, s[2:3], v24, v24, 1.0
	v_rcp_f32_e32 v36, v25
	s_nop 0
	v_fma_f32 v37, -v25, v36, 1.0
	v_fmac_f32_e32 v36, v37, v36
	v_div_scale_f32 v37, vcc, 1.0, v24, 1.0
	v_mul_f32_e32 v38, v37, v36
	v_fma_f32 v39, -v25, v38, v37
	v_fmac_f32_e32 v38, v39, v36
	v_fma_f32 v25, -v25, v38, v37
	v_div_fmas_f32 v25, v25, v36, v38
	v_div_fixup_f32 v167, v25, v24, 1.0
	v_mul_f32_e32 v24, v26, v22
	v_mul_f32_e32 v24, 0xbfb8aa3b, v24
	v_exp_f32_e32 v24, v24
	s_nop 0
	v_add_f32_e32 v24, 1.0, v24
	v_div_scale_f32 v25, s[2:3], v24, v24, 1.0
	v_rcp_f32_e32 v26, v25
	s_nop 0
	v_fma_f32 v36, -v25, v26, 1.0
	v_fmac_f32_e32 v26, v36, v26
	v_div_scale_f32 v36, vcc, 1.0, v24, 1.0
	v_mul_f32_e32 v37, v36, v26
	v_fma_f32 v38, -v25, v37, v36
	v_fmac_f32_e32 v37, v38, v26
	v_fma_f32 v25, -v25, v37, v36
	v_div_fmas_f32 v25, v25, v26, v37
	v_div_fixup_f32 v168, v25, v24, 1.0
	v_mul_f32_e32 v24, v27, v23
	v_mul_f32_e32 v24, 0xbfb8aa3b, v24
	v_exp_f32_e32 v24, v24
	s_nop 0
	v_add_f32_e32 v24, 1.0, v24
	v_div_scale_f32 v25, s[2:3], v24, v24, 1.0
	v_rcp_f32_e32 v26, v25
	s_nop 0
	v_fma_f32 v27, -v25, v26, 1.0
	v_fmac_f32_e32 v26, v27, v26
	v_div_scale_f32 v27, vcc, 1.0, v24, 1.0
	v_mul_f32_e32 v36, v27, v26
	v_fma_f32 v37, -v25, v36, v27
	v_fmac_f32_e32 v36, v37, v26
	v_fma_f32 v25, -v25, v36, v27
	v_div_fmas_f32 v25, v25, v26, v36
	v_div_fixup_f32 v169, v25, v24, 1.0
	ds_read_b128 v[24:27], v158 offset:55520
	s_waitcnt lgkmcnt(0)
; DI int TID() { int t = threadIdx.x; asm volatile("" : "+v"(t)); return t; }
; #define EPI_BEGIN(accv) EPI_BEGINM(accv, 2)
; DI float sigmoidf_(float v) { return 1.f / (1.f + __expf(-v)); }
; template <bool NORM, bool DEEP, int MTW, int KSEG, class HOOK>
; DI void gemm_core_h(const bfu* __restrict__ A, int lda, const bfu* __restrict__ Bt, int ldb, int K, int m0, int n0,
;                     f32x16 (&acc)[MTW][2], char* smem, HOOK hook) {
;     ...
;   const int tid = TID(), lane = tid & 63, w = tid >> 6, r = lane & 31, hh = lane >> 5;
;   const int wm = w >> 1, wn = w & 1;
;   const int lrow = tid >> 3, lkc = tid & 7;
;   const unsigned aoff = (unsigned)((m0 + lrow) * lda + lkc * 8);
;   const unsigned boff = (unsigned)((n0 + lrow) * ldb + lkc * 8);
; DI void phase_ple(const Params& p, int L, char* smem) {
;     ...
;     EPI_BEGIN(gt) gt[mt][nt][i] = sigmoidf_(v * rstd_s[rl]); EPI_END
	v_mul_f32_e32 v28, v28, v24
	v_mul_f32_e32 v28, 0xbfb8aa3b, v28
	v_exp_f32_e32 v28, v28
	s_nop 0
	v_add_f32_e32 v28, 1.0, v28
	v_div_scale_f32 v36, s[2:3], v28, v28, 1.0
	v_rcp_f32_e32 v37, v36
	s_nop 0
	v_fma_f32 v38, -v36, v37, 1.0
	v_fmac_f32_e32 v37, v38, v37
	v_div_scale_f32 v38, vcc, 1.0, v28, 1.0
	v_mul_f32_e32 v39, v38, v37
	v_fma_f32 v40, -v36, v39, v38
	v_fmac_f32_e32 v39, v40, v37
	v_fma_f32 v36, -v36, v39, v38
	v_div_fmas_f32 v36, v36, v37, v39
	v_div_fixup_f32 v174, v36, v28, 1.0
	v_mul_f32_e32 v28, v29, v25
	v_mul_f32_e32 v28, 0xbfb8aa3b, v28
	v_exp_f32_e32 v28, v28
	s_nop 0
	v_add_f32_e32 v28, 1.0, v28
	v_div_scale_f32 v29, s[2:3], v28, v28, 1.0
	v_rcp_f32_e32 v36, v29
	s_nop 0
	v_fma_f32 v37, -v29, v36, 1.0
	v_fmac_f32_e32 v36, v37, v36
	v_div_scale_f32 v37, vcc, 1.0, v28, 1.0
	v_mul_f32_e32 v38, v37, v36
	v_fma_f32 v39, -v29, v38, v37
	v_fmac_f32_e32 v38, v39, v36
	v_fma_f32 v29, -v29, v38, v37
	v_div_fmas_f32 v29, v29, v36, v38
	v_div_fixup_f32 v175, v29, v28, 1.0
	v_mul_f32_e32 v28, v30, v26
	v_mul_f32_e32 v28, 0xbfb8aa3b, v28
	v_exp_f32_e32 v28, v28
	s_nop 0
	v_add_f32_e32 v28, 1.0, v28
	v_div_scale_f32 v29, s[2:3], v28, v28, 1.0
	v_rcp_f32_e32 v30, v29
	s_nop 0
	v_fma_f32 v36, -v29, v30, 1.0
	v_fmac_f32_e32 v30, v36, v30
	v_div_scale_f32 v36, vcc, 1.0, v28, 1.0
	v_mul_f32_e32 v37, v36, v30
	v_fma_f32 v38, -v29, v37, v36
	v_fmac_f32_e32 v37, v38, v30
	v_fma_f32 v29, -v29, v37, v36
	v_div_fmas_f32 v29, v29, v30, v37
	v_div_fixup_f32 v176, v29, v28, 1.0
	v_mul_f32_e32 v28, v31, v27
	v_mul_f32_e32 v28, 0xbfb8aa3b, v28
	v_exp_f32_e32 v28, v28
	s_nop 0
	v_add_f32_e32 v28, 1.0, v28
	v_div_scale_f32 v29, s[2:3], v28, v28, 1.0
	v_rcp_f32_e32 v30, v29
	s_nop 0
	v_fma_f32 v31, -v29, v30, 1.0
	v_fmac_f32_e32 v30, v31, v30
	v_div_scale_f32 v31, vcc, 1.0, v28, 1.0
	v_mul_f32_e32 v36, v31, v30
	v_fma_f32 v37, -v29, v36, v31
	v_fmac_f32_e32 v36, v37, v30
	v_fma_f32 v29, -v29, v36, v31
	v_div_fmas_f32 v29, v29, v30, v36
	v_div_fixup_f32 v177, v29, v28, 1.0
	v_div_scale_f32 v28, s[2:3], v0, v0, 1.0
	v_rcp_f32_e32 v29, v28
	s_nop 0
	v_fma_f32 v30, -v28, v29, 1.0
	v_fmac_f32_e32 v29, v30, v29
	v_div_scale_f32 v30, vcc, 1.0, v0, 1.0
	v_mul_f32_e32 v31, v30, v29
	v_fma_f32 v32, -v28, v31, v30
	v_fmac_f32_e32 v31, v32, v29
	v_fma_f32 v28, -v28, v31, v30
	v_div_fmas_f32 v28, v28, v29, v31
	v_div_fixup_f32 v178, v28, v0, 1.0
	v_mul_f32_e32 v0, v1, v33
	v_mul_f32_e32 v0, 0xbfb8aa3b, v0
	v_exp_f32_e32 v0, v0
	v_mov_b32_e32 v32, v224
	v_add_f32_e32 v0, 1.0, v0
	v_div_scale_f32 v1, s[2:3], v0, v0, 1.0
	v_rcp_f32_e32 v28, v1
	v_ashrrev_i32_e32 v33, 3, v32
	v_lshrrev_b32_e32 v37, 1, v32
	v_and_b32_e32 v36, 0x5f, v32
	v_fma_f32 v29, -v1, v28, 1.0
	v_fmac_f32_e32 v28, v29, v28
	v_div_scale_f32 v29, vcc, 1.0, v0, 1.0
	v_mul_f32_e32 v30, v29, v28
	v_fma_f32 v31, -v1, v30, v29
	v_fmac_f32_e32 v30, v31, v28
	v_fma_f32 v1, -v1, v30, v29
	v_div_fmas_f32 v1, v1, v28, v30
	v_div_fixup_f32 v179, v1, v0, 1.0
	v_mul_f32_e32 v0, v2, v34
	v_mul_f32_e32 v0, 0xbfb8aa3b, v0
	v_exp_f32_e32 v0, v0
	s_nop 0
	v_add_f32_e32 v0, 1.0, v0
	v_div_scale_f32 v1, s[2:3], v0, v0, 1.0
	v_rcp_f32_e32 v2, v1
	s_nop 0
	v_fma_f32 v28, -v1, v2, 1.0
	v_fmac_f32_e32 v2, v28, v2
	v_div_scale_f32 v28, vcc, 1.0, v0, 1.0
	v_mul_f32_e32 v29, v28, v2
	v_fma_f32 v30, -v1, v29, v28
	v_fmac_f32_e32 v29, v30, v2
	v_fma_f32 v1, -v1, v29, v28
	v_div_fmas_f32 v1, v1, v2, v29
	v_div_fixup_f32 v180, v1, v0, 1.0
	v_mul_f32_e32 v0, v3, v35
	v_mul_f32_e32 v0, 0xbfb8aa3b, v0
	v_exp_f32_e32 v0, v0
	v_and_b32_e32 v35, 31, v32
	v_and_or_b32 v35, v37, s7, v35
	v_add_f32_e32 v0, 1.0, v0
	v_div_scale_f32 v1, s[2:3], v0, v0, 1.0
	v_rcp_f32_e32 v2, v1
	s_nop 0
	v_fma_f32 v3, -v1, v2, 1.0
	v_fmac_f32_e32 v2, v3, v2
	v_div_scale_f32 v3, vcc, 1.0, v0, 1.0
	v_mul_f32_e32 v28, v3, v2
	v_fma_f32 v29, -v1, v28, v3
	v_fmac_f32_e32 v28, v29, v2
	v_fma_f32 v1, -v1, v28, v3
	v_div_fmas_f32 v1, v1, v2, v28
	v_div_fixup_f32 v146, v1, v0, 1.0
	v_mul_f32_e32 v0, v4, v16
	v_mul_f32_e32 v0, 0xbfb8aa3b, v0
	v_exp_f32_e32 v0, v0
	v_mov_b32_e32 v29, v189
	v_add_f32_e32 v0, 1.0, v0
	v_div_scale_f32 v1, s[2:3], v0, v0, 1.0
	v_rcp_f32_e32 v2, v1
	s_nop 0
	v_fma_f32 v3, -v1, v2, 1.0
	v_fmac_f32_e32 v2, v3, v2
	v_div_scale_f32 v3, vcc, 1.0, v0, 1.0
	v_mul_f32_e32 v4, v3, v2
	v_fma_f32 v16, -v1, v4, v3
	v_fmac_f32_e32 v4, v16, v2
	v_fma_f32 v1, -v1, v4, v3
	v_div_fmas_f32 v1, v1, v2, v4
	v_div_fixup_f32 v147, v1, v0, 1.0
	v_mul_f32_e32 v0, v5, v17
	v_mul_f32_e32 v0, 0xbfb8aa3b, v0
	v_exp_f32_e32 v0, v0
	v_add_u32_e32 v16, s10, v33
	v_add_f32_e32 v0, 1.0, v0
	v_div_scale_f32 v1, s[2:3], v0, v0, 1.0
	v_rcp_f32_e32 v2, v1
	s_nop 0
	v_fma_f32 v3, -v1, v2, 1.0
	v_fmac_f32_e32 v2, v3, v2
	v_div_scale_f32 v3, vcc, 1.0, v0, 1.0
	v_mul_f32_e32 v4, v3, v2
	v_fma_f32 v5, -v1, v4, v3
	v_fmac_f32_e32 v4, v5, v2
	v_fma_f32 v1, -v1, v4, v3
	v_div_fmas_f32 v1, v1, v2, v4
	v_div_fixup_f32 v150, v1, v0, 1.0
	v_mul_f32_e32 v0, v6, v18
	v_mul_f32_e32 v0, 0xbfb8aa3b, v0
	v_exp_f32_e32 v0, v0
	s_nop 0
	v_add_f32_e32 v0, 1.0, v0
	v_div_scale_f32 v1, s[2:3], v0, v0, 1.0
	v_rcp_f32_e32 v2, v1
	s_nop 0
	v_fma_f32 v3, -v1, v2, 1.0
	v_fmac_f32_e32 v2, v3, v2
	v_div_scale_f32 v3, vcc, 1.0, v0, 1.0
	v_mul_f32_e32 v4, v3, v2
	v_fma_f32 v5, -v1, v4, v3
	v_fmac_f32_e32 v4, v5, v2
	v_fma_f32 v1, -v1, v4, v3
	v_div_fmas_f32 v1, v1, v2, v4
	v_div_fixup_f32 v152, v1, v0, 1.0
	v_mul_f32_e32 v0, v7, v19
	v_mul_f32_e32 v0, 0xbfb8aa3b, v0
	v_exp_f32_e32 v0, v0
	s_nop 0
	v_add_f32_e32 v0, 1.0, v0
	v_div_scale_f32 v1, s[2:3], v0, v0, 1.0
	v_rcp_f32_e32 v2, v1
	s_nop 0
	v_fma_f32 v3, -v1, v2, 1.0
	v_fmac_f32_e32 v2, v3, v2
	v_div_scale_f32 v3, vcc, 1.0, v0, 1.0
	v_mul_f32_e32 v4, v3, v2
; DI float sigmoidf_(float v) { return 1.f / (1.f + __expf(-v)); }
; #define ZERO_ACC(a) ZERO_ACCM(a, 2)
; #define EPI_BEGIN(accv) EPI_BEGINM(accv, 2)
; template <bool NORM, bool DEEP, int MTW, int KSEG, class HOOK>
; DI void gemm_core_h(const bfu* __restrict__ A, int lda, const bfu* __restrict__ Bt, int ldb, int K, int m0, int n0,
;                     f32x16 (&acc)[MTW][2], char* smem, HOOK hook) {
;     ...
; #pragma unroll
;   for (int j = 0; j < NA; ++j) ra0[j] = *(const u32x4*)AP_(j, 0);
; #pragma unroll
;   for (int j = 0; j < 4; ++j) rb0[j] = *(const u32x4*)BP_(j, 0);
;   if (DEEP) {
; #pragma unroll
;     for (int j = 0; j < NA; ++j) ra1[j] = *(const u32x4*)AP_(j, 64);
; #pragma unroll
;     for (int j = 0; j < 4; ++j) rb1[j] = *(const u32x4*)BP_(j, 64);
;   }
; DI void phase_ple(const Params& p, int L, char* smem) {
;     ...
;     EPI_BEGIN(gt) gt[mt][nt][i] = sigmoidf_(v * rstd_s[rl]); EPI_END
;     f32x16 acc[2][2]; ZERO_ACC(acc)
;     gemm_core<false, false>(p.pb, 256, p.wt_pp, 256, 256, m0, n0, acc, smem);
	v_fma_f32 v5, -v1, v4, v3
	v_fmac_f32_e32 v4, v5, v2
	v_fma_f32 v1, -v1, v4, v3
	v_div_fmas_f32 v1, v1, v2, v4
	v_div_fixup_f32 v127, v1, v0, 1.0
	v_mul_f32_e32 v0, v8, v20
	v_mul_f32_e32 v0, 0xbfb8aa3b, v0
	v_exp_f32_e32 v0, v0
	s_nop 0
	v_add_f32_e32 v0, 1.0, v0
	v_div_scale_f32 v1, s[2:3], v0, v0, 1.0
	v_rcp_f32_e32 v2, v1
	s_nop 0
	v_fma_f32 v3, -v1, v2, 1.0
	v_fmac_f32_e32 v2, v3, v2
	v_div_scale_f32 v3, vcc, 1.0, v0, 1.0
	v_mul_f32_e32 v4, v3, v2
	v_fma_f32 v5, -v1, v4, v3
	v_fmac_f32_e32 v4, v5, v2
	v_fma_f32 v1, -v1, v4, v3
	v_div_fmas_f32 v1, v1, v2, v4
	v_div_fixup_f32 v129, v1, v0, 1.0
	v_mul_f32_e32 v0, v9, v21
	v_mul_f32_e32 v0, 0xbfb8aa3b, v0
	v_exp_f32_e32 v0, v0
	v_mov_b32_e32 v9, v189
	v_mov_b32_e32 v21, v189
	v_add_f32_e32 v0, 1.0, v0
	v_div_scale_f32 v1, s[2:3], v0, v0, 1.0
	v_rcp_f32_e32 v2, v1
	s_nop 0
	v_fma_f32 v3, -v1, v2, 1.0
	v_fmac_f32_e32 v2, v3, v2
	v_div_scale_f32 v3, vcc, 1.0, v0, 1.0
	v_mul_f32_e32 v4, v3, v2
	v_fma_f32 v5, -v1, v4, v3
	v_fmac_f32_e32 v4, v5, v2
	v_fma_f32 v1, -v1, v4, v3
	v_div_fmas_f32 v1, v1, v2, v4
	v_div_fixup_f32 v130, v1, v0, 1.0
	v_mul_f32_e32 v0, v10, v22
	v_mul_f32_e32 v0, 0xbfb8aa3b, v0
	v_exp_f32_e32 v0, v0
	s_nop 0
	v_add_f32_e32 v0, 1.0, v0
	v_div_scale_f32 v1, s[2:3], v0, v0, 1.0
	v_rcp_f32_e32 v2, v1
	s_nop 0
	v_fma_f32 v3, -v1, v2, 1.0
	v_fmac_f32_e32 v2, v3, v2
	v_div_scale_f32 v3, vcc, 1.0, v0, 1.0
	v_mul_f32_e32 v4, v3, v2
	v_fma_f32 v5, -v1, v4, v3
	v_fmac_f32_e32 v4, v5, v2
	v_fma_f32 v1, -v1, v4, v3
	v_div_fmas_f32 v1, v1, v2, v4
	v_div_fixup_f32 v131, v1, v0, 1.0
	v_mul_f32_e32 v0, v11, v23
	v_mul_f32_e32 v0, 0xbfb8aa3b, v0
	v_exp_f32_e32 v0, v0
	s_nop 0
	v_add_f32_e32 v0, 1.0, v0
	v_div_scale_f32 v1, s[2:3], v0, v0, 1.0
	v_rcp_f32_e32 v2, v1
	s_nop 0
	v_fma_f32 v3, -v1, v2, 1.0
	v_fmac_f32_e32 v2, v3, v2
	v_div_scale_f32 v3, vcc, 1.0, v0, 1.0
	v_mul_f32_e32 v4, v3, v2
	v_fma_f32 v5, -v1, v4, v3
	v_fmac_f32_e32 v4, v5, v2
	v_fma_f32 v1, -v1, v4, v3
	v_div_fmas_f32 v1, v1, v2, v4
	v_div_fixup_f32 v120, v1, v0, 1.0
	v_mul_f32_e32 v0, v12, v24
	v_mul_f32_e32 v0, 0xbfb8aa3b, v0
	v_exp_f32_e32 v0, v0
	s_nop 0
	v_add_f32_e32 v0, 1.0, v0
	v_div_scale_f32 v1, s[2:3], v0, v0, 1.0
	v_rcp_f32_e32 v2, v1
	s_nop 0
	v_fma_f32 v3, -v1, v2, 1.0
	v_fmac_f32_e32 v2, v3, v2
	v_div_scale_f32 v3, vcc, 1.0, v0, 1.0
	v_mul_f32_e32 v4, v3, v2
	v_fma_f32 v5, -v1, v4, v3
	v_fmac_f32_e32 v4, v5, v2
	v_fma_f32 v1, -v1, v4, v3
	v_div_fmas_f32 v1, v1, v2, v4
	v_div_fixup_f32 v121, v1, v0, 1.0
	v_mul_f32_e32 v0, v13, v25
	v_mul_f32_e32 v0, 0xbfb8aa3b, v0
	v_exp_f32_e32 v0, v0
	v_mov_b32_e32 v13, v189
	v_mov_b32_e32 v25, v189
	v_add_f32_e32 v0, 1.0, v0
	v_div_scale_f32 v1, s[2:3], v0, v0, 1.0
	v_rcp_f32_e32 v2, v1
	s_nop 0
	v_fma_f32 v3, -v1, v2, 1.0
	v_fmac_f32_e32 v2, v3, v2
	v_div_scale_f32 v3, vcc, 1.0, v0, 1.0
	v_mul_f32_e32 v4, v3, v2
	v_fma_f32 v5, -v1, v4, v3
	v_fmac_f32_e32 v4, v5, v2
	v_fma_f32 v1, -v1, v4, v3
	v_div_fmas_f32 v1, v1, v2, v4
	v_div_fixup_f32 v122, v1, v0, 1.0
	v_mul_f32_e32 v0, v14, v26
	v_mul_f32_e32 v0, 0xbfb8aa3b, v0
	v_exp_f32_e32 v0, v0
	s_nop 0
	v_add_f32_e32 v0, 1.0, v0
	v_div_scale_f32 v1, s[2:3], v0, v0, 1.0
	v_rcp_f32_e32 v2, v1
	s_nop 0
	v_fma_f32 v3, -v1, v2, 1.0
	v_fmac_f32_e32 v2, v3, v2
	v_div_scale_f32 v3, vcc, 1.0, v0, 1.0
	v_mul_f32_e32 v4, v3, v2
	v_fma_f32 v5, -v1, v4, v3
	v_fmac_f32_e32 v4, v5, v2
	v_fma_f32 v1, -v1, v4, v3
	v_div_fmas_f32 v1, v1, v2, v4
	v_div_fixup_f32 v124, v1, v0, 1.0
	v_mul_f32_e32 v0, v15, v27
	v_mul_f32_e32 v0, 0xbfb8aa3b, v0
	v_exp_f32_e32 v0, v0
	s_nop 0
	v_add_f32_e32 v0, 1.0, v0
	v_div_scale_f32 v1, s[2:3], v0, v0, 1.0
	v_rcp_f32_e32 v2, v1
	s_nop 0
	v_fma_f32 v3, -v1, v2, 1.0
	v_fmac_f32_e32 v2, v3, v2
	v_div_scale_f32 v3, vcc, 1.0, v0, 1.0
	v_mul_f32_e32 v4, v3, v2
	v_fma_f32 v5, -v1, v4, v3
	v_fmac_f32_e32 v4, v5, v2
	v_fma_f32 v1, -v1, v4, v3
	v_div_fmas_f32 v1, v1, v2, v4
	v_div_fixup_f32 v116, v1, v0, 1.0
	v_lshlrev_b32_e32 v1, 3, v32
	v_add_u32_e32 v0, s9, v33
	v_and_b32_e32 v34, 56, v1
	v_lshl_or_b32 v188, v0, 8, v34
	v_lshl_add_u64 v[102:103], v[188:189], 1, s[42:43]
	v_add_u32_e32 v4, 0x2000, v188
	v_mov_b32_e32 v5, v189
	global_load_dwordx4 v[0:3], v[102:103], off
	v_lshl_add_u64 v[4:5], v[4:5], 1, s[42:43]
	v_add_u32_e32 v8, 0x4000, v188
	global_load_dwordx4 v[4:7], v[4:5], off
	v_lshl_add_u64 v[8:9], v[8:9], 1, s[42:43]
	v_add_u32_e32 v12, 0x6000, v188
	global_load_dwordx4 v[8:11], v[8:9], off
	v_lshl_add_u64 v[12:13], v[12:13], 1, s[42:43]
	v_lshl_or_b32 v104, v16, 8, v34
	global_load_dwordx4 v[12:15], v[12:13], off
	v_lshl_add_u64 v[106:107], v[104:105], 1, s[30:31]
	v_add_u32_e32 v20, 0x2000, v104
	global_load_dwordx4 v[16:19], v[106:107], off
	v_lshl_add_u64 v[20:21], v[20:21], 1, s[30:31]
	v_add_u32_e32 v24, 0x4000, v104
	global_load_dwordx4 v[20:23], v[20:21], off
	v_lshl_add_u64 v[24:25], v[24:25], 1, s[30:31]
	v_add_u32_e32 v28, 0x6000, v104
	global_load_dwordx4 v[24:27], v[24:25], off
	v_lshl_add_u64 v[28:29], v[28:29], 1, s[30:31]
	global_load_dwordx4 v[28:31], v[28:29], off
	v_and_b32_e32 v32, 16, v37
	v_mad_u32_u24 v105, v36, s6, v32
	v_mad_u64_u32 v[100:101], s[2:3], v35, s6, v[32:33]
	v_mul_lo_u32 v32, v33, s6
	v_lshl_add_u32 v101, v34, 1, v32
	s_waitcnt lgkmcnt(0)
	s_barrier
	s_waitcnt vmcnt(7)
	ds_write_b128 v101, v[0:3]
	s_waitcnt vmcnt(6)
	ds_write_b128 v101, v[4:7] offset:4608
	s_waitcnt vmcnt(5)
	ds_write_b128 v101, v[8:11] offset:9216
	s_waitcnt vmcnt(4)
	ds_write_b128 v101, v[12:15] offset:13824
	s_waitcnt vmcnt(3)
	ds_write_b128 v101, v[16:19] offset:18432
	s_waitcnt vmcnt(2)
	ds_write_b128 v101, v[20:23] offset:23040
	s_waitcnt vmcnt(1)
	ds_write_b128 v101, v[24:27] offset:27648
	s_waitcnt vmcnt(0)
	ds_write_b128 v101, v[28:31] offset:32256
	v_add_u32_e32 v0, 0x2040, v188
	v_mov_b32_e32 v1, v189
	s_waitcnt lgkmcnt(0)
	s_barrier
	v_lshl_add_u64 v[0:1], v[0:1], 1, s[42:43]
	global_load_dwordx4 v[64:67], v[102:103], off offset:128
	global_load_dwordx4 v[68:71], v[0:1], off
	v_add_u32_e32 v0, 0x4040, v188
	v_mov_b32_e32 v1, v189
	v_lshl_add_u64 v[0:1], v[0:1], 1, s[42:43]
	global_load_dwordx4 v[72:75], v[0:1], off
	v_add_u32_e32 v0, 0x6040, v188
	v_mov_b32_e32 v1, v189
	v_lshl_add_u64 v[0:1], v[0:1], 1, s[42:43]
	global_load_dwordx4 v[76:79], v[0:1], off
	global_load_dwordx4 v[80:83], v[106:107], off offset:128
	v_add_u32_e32 v0, 0x2040, v104
	v_mov_b32_e32 v1, v189
	v_lshl_add_u64 v[0:1], v[0:1], 1, s[30:31]
	global_load_dwordx4 v[84:87], v[0:1], off
	v_add_u32_e32 v0, 0x4040, v104
	v_mov_b32_e32 v1, v189
	v_lshl_add_u64 v[0:1], v[0:1], 1, s[30:31]
	global_load_dwordx4 v[88:91], v[0:1], off
	v_add_u32_e32 v0, 0x6040, v104
	v_mov_b32_e32 v1, v189
	v_lshl_add_u64 v[0:1], v[0:1], 1, s[30:31]
	global_load_dwordx4 v[92:95], v[0:1], off
	ds_read_b128 v[0:3], v105 offset:23040
	ds_read_b128 v[4:7], v105 offset:18432
	ds_read_b128 v[96:99], v105 offset:18464
	ds_read_b128 v[8:11], v100
	ds_read_b128 v[182:185], v100 offset:32
	s_waitcnt lgkmcnt(1)
	v_mfma_f32_32x32x16_bf16 v[48:63], v[8:11], v[4:7], 0
	ds_read_b128 v[190:193], v105 offset:23072
	v_readlane_b32 s2, v254, 38
	v_readlane_b32 s3, v254, 39
	v_mfma_f32_32x32x16_bf16 v[32:47], v[8:11], v[0:3], 0
	ds_read_b128 v[8:11], v100 offset:4608
	s_waitcnt lgkmcnt(2)
	v_mfma_f32_32x32x16_bf16 v[48:63], v[182:185], v[96:99], v[48:63]
	s_waitcnt lgkmcnt(1)
	v_mfma_f32_32x32x16_bf16 v[32:47], v[182:185], v[190:193], v[32:47]
	ds_read_b128 v[182:185], v100 offset:4640
	s_waitcnt lgkmcnt(1)
	v_mfma_f32_32x32x16_bf16 v[16:31], v[8:11], v[4:7], 0
	v_mfma_f32_32x32x16_bf16 v[0:15], v[8:11], v[0:3], 0
	s_waitcnt lgkmcnt(0)
	v_mfma_f32_32x32x16_bf16 v[16:31], v[182:185], v[96:99], v[16:31]
	v_mfma_f32_32x32x16_bf16 v[0:15], v[182:185], v[190:193], v[0:15]
	ds_read_b128 v[96:99], v105 offset:18496
	ds_read_b128 v[182:185], v105 offset:23104
	ds_read_b128 v[190:193], v100 offset:64
	s_waitcnt lgkmcnt(0)
	v_mfma_f32_32x32x16_bf16 v[48:63], v[190:193], v[96:99], v[48:63]
	v_mfma_f32_32x32x16_bf16 v[32:47], v[190:193], v[182:185], v[32:47]
	ds_read_b128 v[190:193], v100 offset:4672
	s_waitcnt lgkmcnt(0)
	v_mfma_f32_32x32x16_bf16 v[16:31], v[190:193], v[96:99], v[16:31]
	v_mfma_f32_32x32x16_bf16 v[0:15], v[190:193], v[182:185], v[0:15]
	ds_read_b128 v[96:99], v105 offset:18528
	ds_read_b128 v[182:185], v105 offset:23136
	ds_read_b128 v[190:193], v100 offset:96
	s_waitcnt lgkmcnt(0)
	v_mfma_f32_32x32x16_bf16 v[48:63], v[190:193], v[96:99], v[48:63]
	v_mfma_f32_32x32x16_bf16 v[32:47], v[190:193], v[182:185], v[32:47]
	ds_read_b128 v[190:193], v100 offset:4704
	s_waitcnt lgkmcnt(0)
	s_barrier
	s_waitcnt vmcnt(7)
	ds_write_b128 v101, v[64:67]
	s_waitcnt vmcnt(6)
	ds_write_b128 v101, v[68:71] offset:4608
	s_waitcnt vmcnt(5)
	ds_write_b128 v101, v[72:75] offset:9216
	s_waitcnt vmcnt(4)
	ds_write_b128 v101, v[76:79] offset:13824
	s_waitcnt vmcnt(3)
	ds_write_b128 v101, v[80:83] offset:18432
	s_waitcnt vmcnt(2)
	ds_write_b128 v101, v[84:87] offset:23040
	s_waitcnt vmcnt(1)
	ds_write_b128 v101, v[88:91] offset:27648
	s_waitcnt vmcnt(0)
	ds_write_b128 v101, v[92:95] offset:32256
	v_add_u32_e32 v68, 0x2080, v188
	v_mov_b32_e32 v69, v189
	v_add_u32_e32 v72, 0x4080, v188
	v_mov_b32_e32 v73, v189
	v_add_u32_e32 v76, 0x6080, v188
	v_mov_b32_e32 v77, v189
	s_waitcnt lgkmcnt(0)
	s_barrier
	v_lshl_add_u64 v[68:69], v[68:69], 1, s[42:43]
	v_lshl_add_u64 v[72:73], v[72:73], 1, s[42:43]
	v_lshl_add_u64 v[76:77], v[76:77], 1, s[42:43]
	global_load_dwordx4 v[64:67], v[102:103], off offset:256
	v_add_u32_e32 v84, 0x2080, v104
	global_load_dwordx4 v[68:71], v[68:69], off
	v_mov_b32_e32 v85, v189
	global_load_dwordx4 v[72:75], v[72:73], off
	s_nop 0
	global_load_dwordx4 v[76:79], v[76:77], off
	s_nop 0
	global_load_dwordx4 v[80:83], v[106:107], off offset:256
	v_lshl_add_u64 v[84:85], v[84:85], 1, s[30:31]
	v_add_u32_e32 v88, 0x4080, v104
	v_mov_b32_e32 v89, v189
	global_load_dwordx4 v[84:87], v[84:85], off
	v_lshl_add_u64 v[88:89], v[88:89], 1, s[30:31]
	v_add_u32_e32 v92, 0x6080, v104
	v_mov_b32_e32 v93, v189
	global_load_dwordx4 v[88:91], v[88:89], off
	v_lshl_add_u64 v[92:93], v[92:93], 1, s[30:31]
	global_load_dwordx4 v[92:95], v[92:93], off
	s_waitcnt lgkmcnt(8)
	v_mfma_f32_32x32x16_bf16 v[16:31], v[190:193], v[96:99], v[16:31]
	v_mfma_f32_32x32x16_bf16 v[0:15], v[190:193], v[182:185], v[0:15]
	ds_read_b128 v[182:185], v105 offset:23040
	ds_read_b128 v[190:193], v105 offset:18432
	ds_read_b128 v[96:99], v105 offset:18464
	ds_read_b128 v[194:197], v100
	ds_read_b128 v[198:201], v100 offset:32
	s_waitcnt lgkmcnt(1)
	v_mfma_f32_32x32x16_bf16 v[48:63], v[194:197], v[190:193], v[48:63]
	v_mfma_f32_32x32x16_bf16 v[32:47], v[194:197], v[182:185], v[32:47]
	ds_read_b128 v[194:197], v100 offset:4608
	s_waitcnt lgkmcnt(0)
	v_mfma_f32_32x32x16_bf16 v[16:31], v[194:197], v[190:193], v[16:31]
	ds_read_b128 v[190:193], v100 offset:4640
	v_mfma_f32_32x32x16_bf16 v[0:15], v[194:197], v[182:185], v[0:15]
	ds_read_b128 v[182:185], v105 offset:23072
	v_mfma_f32_32x32x16_bf16 v[48:63], v[198:201], v[96:99], v[48:63]
	s_waitcnt lgkmcnt(0)
	v_mfma_f32_32x32x16_bf16 v[32:47], v[198:201], v[182:185], v[32:47]
	v_mfma_f32_32x32x16_bf16 v[16:31], v[190:193], v[96:99], v[16:31]
	v_mfma_f32_32x32x16_bf16 v[0:15], v[190:193], v[182:185], v[0:15]
	ds_read_b128 v[96:99], v105 offset:18496
	ds_read_b128 v[182:185], v105 offset:23104
	ds_read_b128 v[190:193], v100 offset:64
	s_waitcnt lgkmcnt(0)
	v_mfma_f32_32x32x16_bf16 v[48:63], v[190:193], v[96:99], v[48:63]
	v_mfma_f32_32x32x16_bf16 v[32:47], v[190:193], v[182:185], v[32:47]
	ds_read_b128 v[190:193], v100 offset:4672
	s_waitcnt lgkmcnt(0)
	v_mfma_f32_32x32x16_bf16 v[16:31], v[190:193], v[96:99], v[16:31]
	v_mfma_f32_32x32x16_bf16 v[0:15], v[190:193], v[182:185], v[0:15]
	ds_read_b128 v[96:99], v105 offset:18528
	ds_read_b128 v[182:185], v105 offset:23136
	ds_read_b128 v[190:193], v100 offset:96
	s_waitcnt lgkmcnt(0)
	v_mfma_f32_32x32x16_bf16 v[48:63], v[190:193], v[96:99], v[48:63]
	v_mfma_f32_32x32x16_bf16 v[32:47], v[190:193], v[182:185], v[32:47]
	ds_read_b128 v[190:193], v100 offset:4704
	s_waitcnt lgkmcnt(0)
	s_barrier
	s_waitcnt vmcnt(7)
	ds_write_b128 v101, v[64:67]
	s_waitcnt vmcnt(6)
	ds_write_b128 v101, v[68:71] offset:4608
	s_waitcnt vmcnt(5)
	ds_write_b128 v101, v[72:75] offset:9216
	s_waitcnt vmcnt(4)
	ds_write_b128 v101, v[76:79] offset:13824
	s_waitcnt vmcnt(3)
	ds_write_b128 v101, v[80:83] offset:18432
	s_waitcnt vmcnt(2)
	ds_write_b128 v101, v[84:87] offset:23040
	s_waitcnt vmcnt(1)
	ds_write_b128 v101, v[88:91] offset:27648
	s_waitcnt vmcnt(0)
	ds_write_b128 v101, v[92:95] offset:32256
	v_add_u32_e32 v68, 0x20c0, v188
	v_mov_b32_e32 v69, v189
	v_add_u32_e32 v72, 0x40c0, v188
	v_mov_b32_e32 v73, v189
	v_add_u32_e32 v188, 0x60c0, v188
	s_waitcnt lgkmcnt(0)
	s_barrier
	v_lshl_add_u64 v[68:69], v[68:69], 1, s[42:43]
	v_lshl_add_u64 v[72:73], v[72:73], 1, s[42:43]
	v_lshl_add_u64 v[76:77], v[188:189], 1, s[42:43]
	global_load_dwordx4 v[64:67], v[102:103], off offset:384
	v_add_u32_e32 v188, 0x20c0, v104
	global_load_dwordx4 v[68:71], v[68:69], off
	v_lshl_add_u64 v[84:85], v[188:189], 1, s[30:31]
	global_load_dwordx4 v[72:75], v[72:73], off
	s_nop 0
	global_load_dwordx4 v[76:79], v[76:77], off
	s_nop 0
	global_load_dwordx4 v[80:83], v[106:107], off offset:384
	v_add_u32_e32 v188, 0x40c0, v104
	global_load_dwordx4 v[84:87], v[84:85], off
	v_lshl_add_u64 v[88:89], v[188:189], 1, s[30:31]
	v_add_u32_e32 v188, 0x60c0, v104
	global_load_dwordx4 v[88:91], v[88:89], off
	v_lshl_add_u64 v[92:93], v[188:189], 1, s[30:31]
	global_load_dwordx4 v[92:95], v[92:93], off
	s_waitcnt lgkmcnt(8)
	v_mfma_f32_32x32x16_bf16 v[16:31], v[190:193], v[96:99], v[16:31]
	v_mfma_f32_32x32x16_bf16 v[0:15], v[190:193], v[182:185], v[0:15]
	ds_read_b128 v[106:109], v105 offset:23040
	ds_read_b128 v[182:185], v105 offset:18432
	ds_read_b128 v[96:99], v105 offset:18464
	ds_read_b128 v[190:193], v100
	ds_read_b128 v[194:197], v100 offset:32
	s_waitcnt lgkmcnt(1)
	v_mfma_f32_32x32x16_bf16 v[48:63], v[190:193], v[182:185], v[48:63]
	v_mfma_f32_32x32x16_bf16 v[32:47], v[190:193], v[106:109], v[32:47]
	ds_read_b128 v[190:193], v100 offset:4608
	s_waitcnt lgkmcnt(0)
	v_mfma_f32_32x32x16_bf16 v[16:31], v[190:193], v[182:185], v[16:31]
	ds_read_b128 v[182:185], v100 offset:4640
	v_mfma_f32_32x32x16_bf16 v[0:15], v[190:193], v[106:109], v[0:15]
	ds_read_b128 v[106:109], v105 offset:23072
	v_mfma_f32_32x32x16_bf16 v[48:63], v[194:197], v[96:99], v[48:63]
	s_waitcnt lgkmcnt(0)
	v_mfma_f32_32x32x16_bf16 v[32:47], v[194:197], v[106:109], v[32:47]
	v_mfma_f32_32x32x16_bf16 v[16:31], v[182:185], v[96:99], v[16:31]
	v_mfma_f32_32x32x16_bf16 v[0:15], v[182:185], v[106:109], v[0:15]
	ds_read_b128 v[96:99], v105 offset:18496
	ds_read_b128 v[106:109], v105 offset:23104
	ds_read_b128 v[182:185], v100 offset:64
	s_waitcnt lgkmcnt(0)
	v_mfma_f32_32x32x16_bf16 v[48:63], v[182:185], v[96:99], v[48:63]
	v_mfma_f32_32x32x16_bf16 v[32:47], v[182:185], v[106:109], v[32:47]
	ds_read_b128 v[182:185], v100 offset:4672
	s_waitcnt lgkmcnt(0)
	v_mfma_f32_32x32x16_bf16 v[16:31], v[182:185], v[96:99], v[16:31]
	v_mfma_f32_32x32x16_bf16 v[0:15], v[182:185], v[106:109], v[0:15]
	ds_read_b128 v[96:99], v105 offset:18528
	ds_read_b128 v[106:109], v105 offset:23136
	ds_read_b128 v[182:185], v100 offset:96
	s_waitcnt lgkmcnt(0)
	v_mfma_f32_32x32x16_bf16 v[48:63], v[182:185], v[96:99], v[48:63]
	v_mfma_f32_32x32x16_bf16 v[32:47], v[182:185], v[106:109], v[32:47]
	ds_read_b128 v[182:185], v100 offset:4704
	s_waitcnt lgkmcnt(0)
	s_barrier
	s_waitcnt vmcnt(7)
	ds_write_b128 v101, v[64:67]
	s_waitcnt vmcnt(6)
	ds_write_b128 v101, v[68:71] offset:4608
	s_waitcnt vmcnt(5)
	ds_write_b128 v101, v[72:75] offset:9216
	s_waitcnt vmcnt(4)
	ds_write_b128 v101, v[76:79] offset:13824
	s_waitcnt vmcnt(3)
	ds_write_b128 v101, v[80:83] offset:18432
	s_waitcnt vmcnt(2)
	ds_write_b128 v101, v[84:87] offset:23040
	s_waitcnt vmcnt(1)
	ds_write_b128 v101, v[88:91] offset:27648
	s_waitcnt vmcnt(0)
	ds_write_b128 v101, v[92:95] offset:32256
	s_waitcnt lgkmcnt(0)
	s_barrier
	ds_read_b128 v[64:67], v105 offset:23040
	ds_read_b128 v[68:71], v105 offset:18432
	ds_read_b128 v[72:75], v105 offset:18464
	ds_read_b128 v[76:79], v100
	ds_read_b128 v[80:83], v100 offset:32
	s_waitcnt lgkmcnt(1)
	v_mfma_f32_32x32x16_bf16 v[48:63], v[76:79], v[68:71], v[48:63]
	v_mfma_f32_32x32x16_bf16 v[32:47], v[76:79], v[64:67], v[32:47]
	ds_read_b128 v[76:79], v100 offset:4608
	v_mfma_f32_32x32x16_bf16 v[16:31], v[182:185], v[96:99], v[16:31]
	v_mfma_f32_32x32x16_bf16 v[0:15], v[182:185], v[106:109], v[0:15]
	s_waitcnt lgkmcnt(0)
	v_mfma_f32_32x32x16_bf16 v[16:31], v[76:79], v[68:71], v[16:31]
	ds_read_b128 v[68:71], v100 offset:4640
	v_mfma_f32_32x32x16_bf16 v[0:15], v[76:79], v[64:67], v[0:15]
	ds_read_b128 v[64:67], v105 offset:23072
	v_mfma_f32_32x32x16_bf16 v[48:63], v[80:83], v[72:75], v[48:63]
	s_waitcnt lgkmcnt(0)
	v_mfma_f32_32x32x16_bf16 v[32:47], v[80:83], v[64:67], v[32:47]
	v_mfma_f32_32x32x16_bf16 v[16:31], v[68:71], v[72:75], v[16:31]
	v_mfma_f32_32x32x16_bf16 v[0:15], v[68:71], v[64:67], v[0:15]
	ds_read_b128 v[64:67], v105 offset:18496
	ds_read_b128 v[68:71], v105 offset:23104
	ds_read_b128 v[72:75], v100 offset:64
	s_waitcnt lgkmcnt(0)
	v_mfma_f32_32x32x16_bf16 v[48:63], v[72:75], v[64:67], v[48:63]
	v_mfma_f32_32x32x16_bf16 v[32:47], v[72:75], v[68:71], v[32:47]
	ds_read_b128 v[72:75], v100 offset:4672
	s_waitcnt lgkmcnt(0)
	v_mfma_f32_32x32x16_bf16 v[16:31], v[72:75], v[64:67], v[16:31]
	v_mfma_f32_32x32x16_bf16 v[0:15], v[72:75], v[68:71], v[0:15]
	ds_read_b128 v[64:67], v105 offset:18528
	ds_read_b128 v[68:71], v105 offset:23136
	ds_read_b128 v[72:75], v100 offset:96
	s_waitcnt lgkmcnt(0)
	v_mfma_f32_32x32x16_bf16 v[48:63], v[72:75], v[64:67], v[48:63]
	v_mfma_f32_32x32x16_bf16 v[32:47], v[72:75], v[68:71], v[32:47]
	ds_read_b128 v[72:75], v100 offset:4704
	s_waitcnt lgkmcnt(0)
	s_barrier
; #define EPI_BEGIN(accv) EPI_BEGINM(accv, 2)
; DI void phase_ple(const Params& p, int L, char* smem) {
;     ...
;     EPI_BEGIN(acc)
;       float* xp = p.out + (size_t)row * 1024 + col;
;       float nv = *xp + gt[mt][nt][i] * v; *xp = nv; p.xb2[(size_t)row * 1024 + col] = f2bf(nv);
;     EPI_END
	v_mfma_f32_32x32x16_bf16 v[16:31], v[72:75], v[64:67], v[16:31]
	v_mfma_f32_32x32x16_bf16 v[0:15], v[72:75], v[68:71], v[0:15]
	v_add_u32_e32 v186, s9, v156
	v_or_b32_e32 v187, s10, v157
	v_lshlrev_b32_e32 v186, 12, v186
	v_lshl_add_u32 v186, v187, 2, v186
	v_lshrrev_b32_e32 v187, 1, v186
	global_load_dword v76, v186, s[64:65]
	global_load_dword v77, v186, s[64:65] offset:128
	v_add_u32_e32 v220, 0x1000, v186
	global_load_dword v78, v220, s[64:65]
	global_load_dword v79, v220, s[64:65] offset:128
	v_add_u32_e32 v220, 0x2000, v186
	global_load_dword v80, v220, s[64:65]
	global_load_dword v81, v220, s[64:65] offset:128
	v_add_u32_e32 v220, 0x3000, v186
	global_load_dword v82, v220, s[64:65]
	global_load_dword v83, v220, s[64:65] offset:128
	v_add_u32_e32 v220, 0x8000, v186
	global_load_dword v84, v220, s[64:65]
	global_load_dword v85, v220, s[64:65] offset:128
	v_add_u32_e32 v220, 0x9000, v186
	global_load_dword v86, v220, s[64:65]
	global_load_dword v87, v220, s[64:65] offset:128
	v_add_u32_e32 v220, 0xa000, v186
	global_load_dword v88, v220, s[64:65]
	global_load_dword v89, v220, s[64:65] offset:128
	v_add_u32_e32 v220, 0xb000, v186
	global_load_dword v90, v220, s[64:65]
	global_load_dword v91, v220, s[64:65] offset:128
	v_add_u32_e32 v220, 0x10000, v186
	global_load_dword v92, v220, s[64:65]
	global_load_dword v93, v220, s[64:65] offset:128
	v_add_u32_e32 v220, 0x11000, v186
	global_load_dword v94, v220, s[64:65]
	global_load_dword v95, v220, s[64:65] offset:128
	v_add_u32_e32 v220, 0x12000, v186
	global_load_dword v96, v220, s[64:65]
	global_load_dword v97, v220, s[64:65] offset:128
	v_add_u32_e32 v220, 0x13000, v186
	global_load_dword v98, v220, s[64:65]
	global_load_dword v99, v220, s[64:65] offset:128
	v_add_u32_e32 v220, 0x18000, v186
	global_load_dword v100, v220, s[64:65]
	global_load_dword v101, v220, s[64:65] offset:128
	v_add_u32_e32 v220, 0x19000, v186
	global_load_dword v102, v220, s[64:65]
	global_load_dword v103, v220, s[64:65] offset:128
	v_add_u32_e32 v220, 0x1a000, v186
	global_load_dword v104, v220, s[64:65]
	global_load_dword v105, v220, s[64:65] offset:128
	v_add_u32_e32 v220, 0x1b000, v186
	global_load_dword v106, v220, s[64:65]
	global_load_dword v107, v220, s[64:65] offset:128
	v_add_u32_e32 v220, 0x20000, v186
	global_load_dword v108, v220, s[64:65]
	global_load_dword v109, v220, s[64:65] offset:128
	v_add_u32_e32 v220, 0x21000, v186
	global_load_dword v202, v220, s[64:65]
	global_load_dword v203, v220, s[64:65] offset:128
	v_add_u32_e32 v220, 0x22000, v186
	global_load_dword v204, v220, s[64:65]
	global_load_dword v205, v220, s[64:65] offset:128
	v_add_u32_e32 v220, 0x23000, v186
	global_load_dword v206, v220, s[64:65]
	global_load_dword v207, v220, s[64:65] offset:128
	v_add_u32_e32 v220, 0x28000, v186
	global_load_dword v208, v220, s[64:65]
	global_load_dword v209, v220, s[64:65] offset:128
	v_add_u32_e32 v220, 0x29000, v186
	global_load_dword v210, v220, s[64:65]
	global_load_dword v211, v220, s[64:65] offset:128
	v_add_u32_e32 v220, 0x2a000, v186
	global_load_dword v212, v220, s[64:65]
	global_load_dword v213, v220, s[64:65] offset:128
	v_add_u32_e32 v220, 0x2b000, v186
	global_load_dword v214, v220, s[64:65]
	global_load_dword v215, v220, s[64:65] offset:128
	v_add_u32_e32 v220, 0x30000, v186
	global_load_dword v216, v220, s[64:65]
	global_load_dword v217, v220, s[64:65] offset:128
	v_add_u32_e32 v220, 0x31000, v186
	global_load_dword v218, v220, s[64:65]
	global_load_dword v219, v220, s[64:65] offset:128
	v_add_u32_e32 v220, 0x32000, v186
	global_load_dword v64, v220, s[64:65]
	global_load_dword v65, v220, s[64:65] offset:128
	v_add_u32_e32 v220, 0x33000, v186
	global_load_dword v66, v220, s[64:65]
	global_load_dword v67, v220, s[64:65] offset:128
	v_add_u32_e32 v220, 0x38000, v186
	global_load_dword v68, v220, s[64:65]
	global_load_dword v69, v220, s[64:65] offset:128
	v_add_u32_e32 v220, 0x39000, v186
	global_load_dword v70, v220, s[64:65]
	global_load_dword v71, v220, s[64:65] offset:128
	v_add_u32_e32 v220, 0x3a000, v186
	global_load_dword v72, v220, s[64:65]
	global_load_dword v73, v220, s[64:65] offset:128
	v_add_u32_e32 v220, 0x3b000, v186
	global_load_dword v74, v220, s[64:65]
	global_load_dword v75, v220, s[64:65] offset:128
	s_waitcnt vmcnt(32)
; #define EPI_BEGIN(accv) EPI_BEGINM(accv, 2)
; DI void phase_ple(const Params& p, int L, char* smem) {
;     ...
;     EPI_BEGIN(acc)
;       float* xp = p.out + (size_t)row * 1024 + col;
;       float nv = *xp + gt[mt][nt][i] * v; *xp = nv; p.xb2[(size_t)row * 1024 + col] = f2bf(nv);
;     EPI_END
	v_fmac_f32_e32 v76, v110, v48
	global_store_dword v186, v76, s[64:65]
	v_cvt_pk_bf16_f32 v48, v76, v76
	global_store_short v187, v48, s[38:39]
	v_fmac_f32_e32 v77, v171, v32
	global_store_dword v186, v77, s[64:65] offset:128
	v_cvt_pk_bf16_f32 v32, v77, v77
	global_store_short v187, v32, s[38:39] offset:64
	v_add_u32_e32 v220, 0x1000, v186
	v_add_u32_e32 v221, 0x800, v187
	v_fmac_f32_e32 v78, v114, v49
	global_store_dword v220, v78, s[64:65]
	v_cvt_pk_bf16_f32 v49, v78, v78
	global_store_short v221, v49, s[38:39]
	v_fmac_f32_e32 v79, v172, v33
	global_store_dword v220, v79, s[64:65] offset:128
	v_cvt_pk_bf16_f32 v33, v79, v79
	global_store_short v221, v33, s[38:39] offset:64
	v_add_u32_e32 v220, 0x2000, v186
	v_add_u32_e32 v221, 0x1000, v187
	v_fmac_f32_e32 v80, v118, v50
	global_store_dword v220, v80, s[64:65]
	v_cvt_pk_bf16_f32 v50, v80, v80
	global_store_short v221, v50, s[38:39]
	v_fmac_f32_e32 v81, v173, v34
	global_store_dword v220, v81, s[64:65] offset:128
	v_cvt_pk_bf16_f32 v34, v81, v81
	global_store_short v221, v34, s[38:39] offset:64
	v_add_u32_e32 v220, 0x3000, v186
	v_add_u32_e32 v221, 0x1800, v187
	v_fmac_f32_e32 v82, v117, v51
	global_store_dword v220, v82, s[64:65]
	v_cvt_pk_bf16_f32 v51, v82, v82
	global_store_short v221, v51, s[38:39]
	v_fmac_f32_e32 v83, v142, v35
	global_store_dword v220, v83, s[64:65] offset:128
	v_cvt_pk_bf16_f32 v35, v83, v83
	global_store_short v221, v35, s[38:39] offset:64
	v_add_u32_e32 v220, 0x8000, v186
	v_add_u32_e32 v221, 0x4000, v187
	v_fmac_f32_e32 v84, v119, v52
	global_store_dword v220, v84, s[64:65]
	v_cvt_pk_bf16_f32 v52, v84, v84
	global_store_short v221, v52, s[38:39]
	v_fmac_f32_e32 v85, v148, v36
	global_store_dword v220, v85, s[64:65] offset:128
	v_cvt_pk_bf16_f32 v36, v85, v85
	global_store_short v221, v36, s[38:39] offset:64
	v_add_u32_e32 v220, 0x9000, v186
	v_add_u32_e32 v221, 0x4800, v187
	v_fmac_f32_e32 v86, v123, v53
	global_store_dword v220, v86, s[64:65]
	v_cvt_pk_bf16_f32 v53, v86, v86
	global_store_short v221, v53, s[38:39]
	v_fmac_f32_e32 v87, v153, v37
	global_store_dword v220, v87, s[64:65] offset:128
	v_cvt_pk_bf16_f32 v37, v87, v87
	global_store_short v221, v37, s[38:39] offset:64
	v_add_u32_e32 v220, 0xa000, v186
	v_add_u32_e32 v221, 0x5000, v187
	v_fmac_f32_e32 v88, v125, v54
	global_store_dword v220, v88, s[64:65]
	v_cvt_pk_bf16_f32 v54, v88, v88
	global_store_short v221, v54, s[38:39]
	v_fmac_f32_e32 v89, v155, v38
	global_store_dword v220, v89, s[64:65] offset:128
	v_cvt_pk_bf16_f32 v38, v89, v89
	global_store_short v221, v38, s[38:39] offset:64
	v_add_u32_e32 v220, 0xb000, v186
	v_add_u32_e32 v221, 0x5800, v187
	v_fmac_f32_e32 v90, v128, v55
	global_store_dword v220, v90, s[64:65]
	v_cvt_pk_bf16_f32 v55, v90, v90
	global_store_short v221, v55, s[38:39]
	v_fmac_f32_e32 v91, v138, v39
	global_store_dword v220, v91, s[64:65] offset:128
	v_cvt_pk_bf16_f32 v39, v91, v91
	global_store_short v221, v39, s[38:39] offset:64
	v_add_u32_e32 v220, 0x10000, v186
	v_add_u32_e32 v221, 0x8000, v187
	v_fmac_f32_e32 v92, v132, v56
	global_store_dword v220, v92, s[64:65]
	v_cvt_pk_bf16_f32 v56, v92, v92
	global_store_short v221, v56, s[38:39]
	v_fmac_f32_e32 v93, v139, v40
	global_store_dword v220, v93, s[64:65] offset:128
	v_cvt_pk_bf16_f32 v40, v93, v93
	global_store_short v221, v40, s[38:39] offset:64
	v_add_u32_e32 v220, 0x11000, v186
	v_add_u32_e32 v221, 0x8800, v187
	v_fmac_f32_e32 v94, v133, v57
	global_store_dword v220, v94, s[64:65]
	v_cvt_pk_bf16_f32 v57, v94, v94
	global_store_short v221, v57, s[38:39]
	v_fmac_f32_e32 v95, v143, v41
	global_store_dword v220, v95, s[64:65] offset:128
	v_cvt_pk_bf16_f32 v41, v95, v95
	global_store_short v221, v41, s[38:39] offset:64
	v_add_u32_e32 v220, 0x12000, v186
	v_add_u32_e32 v221, 0x9000, v187
	v_fmac_f32_e32 v96, v134, v58
	global_store_dword v220, v96, s[64:65]
	v_cvt_pk_bf16_f32 v58, v96, v96
	global_store_short v221, v58, s[38:39]
	v_fmac_f32_e32 v97, v149, v42
	global_store_dword v220, v97, s[64:65] offset:128
	v_cvt_pk_bf16_f32 v42, v97, v97
	global_store_short v221, v42, s[38:39] offset:64
	v_add_u32_e32 v220, 0x13000, v186
	v_add_u32_e32 v221, 0x9800, v187
	v_fmac_f32_e32 v98, v135, v59
	global_store_dword v220, v98, s[64:65]
	v_cvt_pk_bf16_f32 v59, v98, v98
	global_store_short v221, v59, s[38:39]
	v_fmac_f32_e32 v99, v140, v43
	global_store_dword v220, v99, s[64:65] offset:128
	v_cvt_pk_bf16_f32 v43, v99, v99
	global_store_short v221, v43, s[38:39] offset:64
	v_add_u32_e32 v220, 0x18000, v186
	v_add_u32_e32 v221, 0xc000, v187
	v_fmac_f32_e32 v100, v161, v60
	global_store_dword v220, v100, s[64:65]
	v_cvt_pk_bf16_f32 v60, v100, v100
	global_store_short v221, v60, s[38:39]
	v_fmac_f32_e32 v101, v144, v44
	global_store_dword v220, v101, s[64:65] offset:128
	v_cvt_pk_bf16_f32 v44, v101, v101
	global_store_short v221, v44, s[38:39] offset:64
	v_add_u32_e32 v220, 0x19000, v186
	v_add_u32_e32 v221, 0xc800, v187
	v_fmac_f32_e32 v102, v163, v61
	global_store_dword v220, v102, s[64:65]
	v_cvt_pk_bf16_f32 v61, v102, v102
	global_store_short v221, v61, s[38:39]
	v_fmac_f32_e32 v103, v151, v45
	global_store_dword v220, v103, s[64:65] offset:128
	v_cvt_pk_bf16_f32 v45, v103, v103
	global_store_short v221, v45, s[38:39] offset:64
	v_add_u32_e32 v220, 0x1a000, v186
	v_add_u32_e32 v221, 0xd000, v187
	v_fmac_f32_e32 v104, v165, v62
	global_store_dword v220, v104, s[64:65]
	v_cvt_pk_bf16_f32 v62, v104, v104
	global_store_short v221, v62, s[38:39]
	v_fmac_f32_e32 v105, v154, v46
	global_store_dword v220, v105, s[64:65] offset:128
	v_cvt_pk_bf16_f32 v46, v105, v105
	global_store_short v221, v46, s[38:39] offset:64
	v_add_u32_e32 v220, 0x1b000, v186
	v_add_u32_e32 v221, 0xd800, v187
	v_fmac_f32_e32 v106, v170, v63
	global_store_dword v220, v106, s[64:65]
	v_cvt_pk_bf16_f32 v63, v106, v106
	global_store_short v221, v63, s[38:39]
	v_fmac_f32_e32 v107, v145, v47
	global_store_dword v220, v107, s[64:65] offset:128
	v_cvt_pk_bf16_f32 v47, v107, v107
	global_store_short v221, v47, s[38:39] offset:64
	s_waitcnt vmcnt(63)
; #define EPI_BEGIN(accv) EPI_BEGINM(accv, 2)
; DI void phase_ple(const Params& p, int L, char* smem) {
;     ...
;   for (int id = blockIdx.x; id < 128 * 8; id += gridDim.x) {
;     ...
;     EPI_BEGIN(acc)
;       float* xp = p.out + (size_t)row * 1024 + col;
;       float nv = *xp + gt[mt][nt][i] * v; *xp = nv; p.xb2[(size_t)row * 1024 + col] = f2bf(nv);
;     EPI_END
	v_add_u32_e32 v220, 0x20000, v186
	v_add_u32_e32 v221, 0x10000, v187
	v_fmac_f32_e32 v108, v141, v16
	global_store_dword v220, v108, s[64:65]
	v_cvt_pk_bf16_f32 v16, v108, v108
	global_store_short v221, v16, s[38:39]
	v_fmac_f32_e32 v109, v178, v0
	global_store_dword v220, v109, s[64:65] offset:128
	v_cvt_pk_bf16_f32 v0, v109, v109
	global_store_short v221, v0, s[38:39] offset:64
	v_add_u32_e32 v220, 0x21000, v186
	v_add_u32_e32 v221, 0x10800, v187
	v_fmac_f32_e32 v202, v137, v17
	global_store_dword v220, v202, s[64:65]
	v_cvt_pk_bf16_f32 v17, v202, v202
	global_store_short v221, v17, s[38:39]
	v_fmac_f32_e32 v203, v179, v1
	global_store_dword v220, v203, s[64:65] offset:128
	v_cvt_pk_bf16_f32 v1, v203, v203
	global_store_short v221, v1, s[38:39] offset:64
	v_add_u32_e32 v220, 0x22000, v186
	v_add_u32_e32 v221, 0x11000, v187
	v_fmac_f32_e32 v204, v136, v18
	global_store_dword v220, v204, s[64:65]
	v_cvt_pk_bf16_f32 v18, v204, v204
	global_store_short v221, v18, s[38:39]
	v_fmac_f32_e32 v205, v180, v2
	global_store_dword v220, v205, s[64:65] offset:128
	v_cvt_pk_bf16_f32 v2, v205, v205
	global_store_short v221, v2, s[38:39] offset:64
	v_add_u32_e32 v220, 0x23000, v186
	v_add_u32_e32 v221, 0x11800, v187
	v_fmac_f32_e32 v206, v126, v19
	global_store_dword v220, v206, s[64:65]
	v_cvt_pk_bf16_f32 v19, v206, v206
	global_store_short v221, v19, s[38:39]
	v_fmac_f32_e32 v207, v146, v3
	global_store_dword v220, v207, s[64:65] offset:128
	v_cvt_pk_bf16_f32 v3, v207, v207
	global_store_short v221, v3, s[38:39] offset:64
	v_add_u32_e32 v220, 0x28000, v186
	v_add_u32_e32 v221, 0x14000, v187
	v_fmac_f32_e32 v208, v159, v20
	global_store_dword v220, v208, s[64:65]
	v_cvt_pk_bf16_f32 v20, v208, v208
	global_store_short v221, v20, s[38:39]
	v_fmac_f32_e32 v209, v147, v4
	global_store_dword v220, v209, s[64:65] offset:128
	v_cvt_pk_bf16_f32 v4, v209, v209
	global_store_short v221, v4, s[38:39] offset:64
	v_add_u32_e32 v220, 0x29000, v186
	v_add_u32_e32 v221, 0x14800, v187
	v_fmac_f32_e32 v210, v160, v21
	global_store_dword v220, v210, s[64:65]
	v_cvt_pk_bf16_f32 v21, v210, v210
	global_store_short v221, v21, s[38:39]
	v_fmac_f32_e32 v211, v150, v5
	global_store_dword v220, v211, s[64:65] offset:128
	v_cvt_pk_bf16_f32 v5, v211, v211
	global_store_short v221, v5, s[38:39] offset:64
	v_add_u32_e32 v220, 0x2a000, v186
	v_add_u32_e32 v221, 0x15000, v187
	v_fmac_f32_e32 v212, v162, v22
	global_store_dword v220, v212, s[64:65]
	v_cvt_pk_bf16_f32 v22, v212, v212
	global_store_short v221, v22, s[38:39]
	v_fmac_f32_e32 v213, v152, v6
	global_store_dword v220, v213, s[64:65] offset:128
	v_cvt_pk_bf16_f32 v6, v213, v213
	global_store_short v221, v6, s[38:39] offset:64
	v_add_u32_e32 v220, 0x2b000, v186
	v_add_u32_e32 v221, 0x15800, v187
	v_fmac_f32_e32 v214, v164, v23
	global_store_dword v220, v214, s[64:65]
	v_cvt_pk_bf16_f32 v23, v214, v214
	global_store_short v221, v23, s[38:39]
	v_fmac_f32_e32 v215, v127, v7
	global_store_dword v220, v215, s[64:65] offset:128
	v_cvt_pk_bf16_f32 v7, v215, v215
	global_store_short v221, v7, s[38:39] offset:64
	v_add_u32_e32 v220, 0x30000, v186
	v_add_u32_e32 v221, 0x18000, v187
	v_fmac_f32_e32 v216, v166, v24
	global_store_dword v220, v216, s[64:65]
	v_cvt_pk_bf16_f32 v24, v216, v216
	global_store_short v221, v24, s[38:39]
	v_fmac_f32_e32 v217, v129, v8
	global_store_dword v220, v217, s[64:65] offset:128
	v_cvt_pk_bf16_f32 v8, v217, v217
	global_store_short v221, v8, s[38:39] offset:64
	v_add_u32_e32 v220, 0x31000, v186
	v_add_u32_e32 v221, 0x18800, v187
	v_fmac_f32_e32 v218, v167, v25
	global_store_dword v220, v218, s[64:65]
	v_cvt_pk_bf16_f32 v25, v218, v218
	global_store_short v221, v25, s[38:39]
	v_fmac_f32_e32 v219, v130, v9
	global_store_dword v220, v219, s[64:65] offset:128
	v_cvt_pk_bf16_f32 v9, v219, v219
	global_store_short v221, v9, s[38:39] offset:64
	v_add_u32_e32 v220, 0x32000, v186
	v_add_u32_e32 v221, 0x19000, v187
	v_fmac_f32_e32 v64, v168, v26
	global_store_dword v220, v64, s[64:65]
	v_cvt_pk_bf16_f32 v26, v64, v64
	global_store_short v221, v26, s[38:39]
	v_fmac_f32_e32 v65, v131, v10
	global_store_dword v220, v65, s[64:65] offset:128
	v_cvt_pk_bf16_f32 v10, v65, v65
	global_store_short v221, v10, s[38:39] offset:64
	v_add_u32_e32 v220, 0x33000, v186
	v_add_u32_e32 v221, 0x19800, v187
	v_fmac_f32_e32 v66, v169, v27
	global_store_dword v220, v66, s[64:65]
	v_cvt_pk_bf16_f32 v27, v66, v66
	global_store_short v221, v27, s[38:39]
	v_fmac_f32_e32 v67, v120, v11
	global_store_dword v220, v67, s[64:65] offset:128
	v_cvt_pk_bf16_f32 v11, v67, v67
	global_store_short v221, v11, s[38:39] offset:64
	v_add_u32_e32 v220, 0x38000, v186
	v_add_u32_e32 v221, 0x1c000, v187
	v_fmac_f32_e32 v68, v174, v28
	global_store_dword v220, v68, s[64:65]
	v_cvt_pk_bf16_f32 v28, v68, v68
	global_store_short v221, v28, s[38:39]
	v_fmac_f32_e32 v69, v121, v12
	global_store_dword v220, v69, s[64:65] offset:128
	v_cvt_pk_bf16_f32 v12, v69, v69
	global_store_short v221, v12, s[38:39] offset:64
	v_add_u32_e32 v220, 0x39000, v186
	v_add_u32_e32 v221, 0x1c800, v187
	v_fmac_f32_e32 v70, v175, v29
	global_store_dword v220, v70, s[64:65]
	v_cvt_pk_bf16_f32 v29, v70, v70
	global_store_short v221, v29, s[38:39]
	v_fmac_f32_e32 v71, v122, v13
	global_store_dword v220, v71, s[64:65] offset:128
	v_cvt_pk_bf16_f32 v13, v71, v71
	global_store_short v221, v13, s[38:39] offset:64
	v_add_u32_e32 v220, 0x3a000, v186
	v_add_u32_e32 v221, 0x1d000, v187
	v_fmac_f32_e32 v72, v176, v30
	global_store_dword v220, v72, s[64:65]
	v_cvt_pk_bf16_f32 v30, v72, v72
	global_store_short v221, v30, s[38:39]
	v_fmac_f32_e32 v73, v124, v14
	global_store_dword v220, v73, s[64:65] offset:128
	v_cvt_pk_bf16_f32 v14, v73, v73
	global_store_short v221, v14, s[38:39] offset:64
	v_add_u32_e32 v220, 0x3b000, v186
	v_add_u32_e32 v221, 0x1d800, v187
	v_fmac_f32_e32 v74, v177, v31
	global_store_dword v220, v74, s[64:65]
	v_cvt_pk_bf16_f32 v31, v74, v74
	global_store_short v221, v31, s[38:39]
	v_fmac_f32_e32 v75, v116, v15
	global_store_dword v220, v75, s[64:65] offset:128
	v_cvt_pk_bf16_f32 v15, v75, v75
	global_store_short v221, v15, s[38:39] offset:64
	s_load_dword s2, s[2:3], 0x0
	s_waitcnt lgkmcnt(0)
	s_add_i32 s8, s2, s8
	s_cmpk_gt_i32 s8, 0x3ff
	s_cbranch_scc1 .LBB0_22

; #define ZERO_ACCM(a, MT) _Pragma("unroll") for (int _m = 0; _m < MT; ++_m) _Pragma("unroll") for (int _n = 0; _n < 2; ++_n) _Pragma("unroll") for (int _i = 0; _i < 16; ++_i) a[_m][_n][_i] = 0.f;
; template <bool NORM, bool DEEP, int MTW, int KSEG, class HOOK>
; DI void gemm_core_h(const bfu* __restrict__ A, int lda, const bfu* __restrict__ Bt, int ldb, int K, int m0, int n0,
;                     f32x16 (&acc)[MTW][2], char* smem, HOOK hook) {
;     ...
; #pragma unroll
;   for (int j = 0; j < NA; ++j) ra0[j] = *(const u32x4*)AP_(j, 0);
; #pragma unroll
;   for (int j = 0; j < 4; ++j) rb0[j] = *(const u32x4*)BP_(j, 0);
; DI void phase_up(const Params& p, char* smem) {
;     ...
;   for (int id = blockIdx.x; id < 64 * 32; id += gridDim.x) {
;     int tm, tn; map_tile(id, 32, tm, tn);
;     const int m0 = tm * 256, n0 = tn * 128;
;     f32x16 acc[4][2]; ZERO_ACCM(acc, 4)
;     gemm_core<true, false, 4>(p.xb, D, p.wt_up, D, D, m0, n0, acc, smem);
.LBB0_103:
	s_ashr_i32 s3, s6, 31
	s_ashr_i32 s2, s6, 3
	s_lshr_b32 s3, s3, 24
	s_add_i32 s3, s2, s3
	s_and_b32 s4, s3, 0xffffff00
	s_lshr_b32 s3, s3, 2
	s_lshl_b32 s5, s6, 3
	s_sub_i32 s2, s2, s4
	s_and_b32 s3, s3, 0x3fffffc0
	s_and_b32 s5, s5, 56
	s_and_b32 s4, s2, 7
	s_or_b32 s3, s3, s5
	s_or_b32 s3, s3, s4
	v_mov_b32_e32 v4, v224
	s_lshl_b32 s7, s3, 8
	v_mov_b32_e32 v199, v189
	v_ashrrev_i32_e32 v240, 3, v4
	v_and_b32_e32 v241, 7, v4
	v_add_u32_e32 v0, s7, v240
	v_lshlrev_b32_e32 v5, 3, v241
	v_lshl_or_b32 v198, v0, 10, v5
	v_add_u32_e32 v188, 0x8000, v198
	v_lshl_add_u64 v[0:1], v[198:199], 1, s[36:37]
	v_lshl_add_u64 v[2:3], v[188:189], 1, s[36:37]
	v_add_u32_e32 v188, 0x10000, v198
	global_load_dwordx4 v[156:159], v[0:1], off
	global_load_dwordx4 v[152:155], v[2:3], off
	v_lshl_add_u64 v[0:1], v[188:189], 1, s[36:37]
	v_add_u32_e32 v188, 0x18000, v198
	s_lshl_b32 s2, s2, 4
	v_lshl_add_u64 v[2:3], v[188:189], 1, s[36:37]
	v_add_u32_e32 v188, 0x20000, v198
	s_and_b32 s10, s2, 0xffffff80
	global_load_dwordx4 v[148:151], v[0:1], off
	global_load_dwordx4 v[144:147], v[2:3], off
	v_lshl_add_u64 v[0:1], v[188:189], 1, s[36:37]
	v_add_u32_e32 v188, 0x28000, v198
	v_add_u32_e32 v6, s10, v240
	v_lshl_add_u64 v[2:3], v[188:189], 1, s[36:37]
	v_add_u32_e32 v188, 0x30000, v198
	global_load_dwordx4 v[140:143], v[0:1], off
	global_load_dwordx4 v[136:139], v[2:3], off
	v_lshl_add_u64 v[0:1], v[188:189], 1, s[36:37]
	v_add_u32_e32 v188, 0x38000, v198
	v_lshl_or_b32 v200, v6, 10, v5
	v_readlane_b32 s16, v253, 48
	v_lshl_add_u64 v[2:3], v[188:189], 1, s[36:37]
	v_mov_b32_e32 v201, v189
	v_readlane_b32 s24, v253, 56
	v_readlane_b32 s25, v253, 57
	v_add_u32_e32 v188, 0x8000, v200
	global_load_dwordx4 v[132:135], v[0:1], off
	global_load_dwordx4 v[128:131], v[2:3], off
	v_lshl_add_u64 v[0:1], v[200:201], 1, s[24:25]
	v_lshl_add_u64 v[2:3], v[188:189], 1, s[24:25]
	v_add_u32_e32 v188, 0x10000, v200
	global_load_dwordx4 v[160:163], v[0:1], off
	global_load_dwordx4 v[164:167], v[2:3], off
	v_lshl_add_u64 v[0:1], v[188:189], 1, s[24:25]
	v_add_u32_e32 v188, 0x18000, v200
	v_lshl_add_u64 v[2:3], v[188:189], 1, s[24:25]
	global_load_dwordx4 v[168:171], v[0:1], off
	global_load_dwordx4 v[172:175], v[2:3], off
	v_lshrrev_b32_e32 v2, 1, v4
	v_and_b32_e32 v0, 0x5f, v4
	v_and_b32_e32 v2, 16, v2
	s_movk_i32 s2, 0x90
	v_mad_u32_u24 v242, v0, s2, v2
	v_and_b32_e32 v0, 0xfffff9f, v4
	v_mul_lo_u32 v3, v0, s2
	v_or_b32_e32 v0, 0x60, v4
	v_lshlrev_b32_e32 v1, 4, v241
	v_mul_lo_u32 v5, v240, s2
	v_mul_lo_u32 v4, v0, s2
	v_mov_b32_e32 v0, 0
	s_mov_b32 s2, 0
	v_add_u32_e32 v243, v1, v5
	v_add_u32_e32 v201, v2, v3
	v_add_u32_e32 v199, v2, v4
	v_mov_b32_e32 v1, v0
	v_mov_b32_e32 v2, v0
	v_mov_b32_e32 v3, v0
	v_mov_b32_e32 v4, v0
	v_mov_b32_e32 v5, v0
	v_mov_b32_e32 v6, v0
	v_mov_b32_e32 v7, v0
	v_mov_b32_e32 v8, v0
	v_mov_b32_e32 v9, v0
	v_mov_b32_e32 v10, v0
	v_mov_b32_e32 v11, v0
	v_mov_b32_e32 v12, v0
	v_mov_b32_e32 v13, v0
	v_mov_b32_e32 v14, v0
	v_mov_b32_e32 v15, v0
	v_mov_b32_e32 v16, v0
	v_mov_b32_e32 v17, v0
	v_mov_b32_e32 v18, v0
	v_mov_b32_e32 v19, v0
	v_mov_b32_e32 v20, v0
	v_mov_b32_e32 v21, v0
	v_mov_b32_e32 v22, v0
	v_mov_b32_e32 v23, v0
	v_mov_b32_e32 v24, v0
	v_mov_b32_e32 v25, v0
	v_mov_b32_e32 v26, v0
	v_mov_b32_e32 v27, v0
	v_mov_b32_e32 v28, v0
	v_mov_b32_e32 v29, v0
	v_mov_b32_e32 v30, v0
	v_mov_b32_e32 v31, v0
	v_mov_b32_e32 v32, v0
	v_mov_b32_e32 v33, v0
	v_mov_b32_e32 v34, v0
	v_mov_b32_e32 v35, v0
	v_mov_b32_e32 v36, v0
	v_mov_b32_e32 v37, v0
	v_mov_b32_e32 v38, v0
	v_mov_b32_e32 v39, v0
	v_mov_b32_e32 v40, v0
	v_mov_b32_e32 v41, v0
	v_mov_b32_e32 v42, v0
	v_mov_b32_e32 v43, v0
	v_mov_b32_e32 v44, v0
	v_mov_b32_e32 v45, v0
	v_mov_b32_e32 v46, v0
	v_mov_b32_e32 v47, v0
	v_mov_b32_e32 v48, v0
	v_mov_b32_e32 v49, v0
	v_mov_b32_e32 v50, v0
	v_mov_b32_e32 v51, v0
	v_mov_b32_e32 v52, v0
	v_mov_b32_e32 v53, v0
	v_mov_b32_e32 v54, v0
	v_mov_b32_e32 v55, v0
	v_mov_b32_e32 v56, v0
	v_mov_b32_e32 v57, v0
	v_mov_b32_e32 v58, v0
	v_mov_b32_e32 v59, v0
	v_mov_b32_e32 v60, v0
	v_mov_b32_e32 v61, v0
	v_mov_b32_e32 v62, v0
	v_mov_b32_e32 v63, v0
	s_waitcnt vmcnt(27)
	v_mov_b32_e32 v64, v0
	v_mov_b32_e32 v65, v0
	v_mov_b32_e32 v66, v0
	v_mov_b32_e32 v67, v0
	s_waitcnt vmcnt(26)
	v_mov_b32_e32 v68, v0
	v_mov_b32_e32 v69, v0
	v_mov_b32_e32 v70, v0
	v_mov_b32_e32 v71, v0
	s_waitcnt vmcnt(17)
	v_mov_b32_e32 v72, v0
	v_mov_b32_e32 v73, v0
	v_mov_b32_e32 v74, v0
	v_mov_b32_e32 v75, v0
	s_waitcnt vmcnt(16)
	v_mov_b32_e32 v76, v0
	v_mov_b32_e32 v77, v0
	v_mov_b32_e32 v78, v0
	v_mov_b32_e32 v79, v0
	s_waitcnt vmcnt(14)
	v_mov_b32_e32 v80, v0
	v_mov_b32_e32 v81, v0
	v_mov_b32_e32 v82, v0
	v_mov_b32_e32 v83, v0
	v_mov_b32_e32 v84, v0
	v_mov_b32_e32 v85, v0
	v_mov_b32_e32 v86, v0
	v_mov_b32_e32 v87, v0
	s_waitcnt vmcnt(13)
	v_mov_b32_e32 v88, v0
	v_mov_b32_e32 v89, v0
	v_mov_b32_e32 v90, v0
	v_mov_b32_e32 v91, v0
	s_waitcnt vmcnt(12)
	v_mov_b32_e32 v92, v0
	v_mov_b32_e32 v93, v0
	v_mov_b32_e32 v94, v0
	v_mov_b32_e32 v95, v0
	v_mov_b32_e32 v96, v0
	v_mov_b32_e32 v97, v0
	v_mov_b32_e32 v98, v0
	v_mov_b32_e32 v99, v0
	v_mov_b32_e32 v100, v0
	v_mov_b32_e32 v101, v0
	v_mov_b32_e32 v102, v0
	v_mov_b32_e32 v103, v0
	v_mov_b32_e32 v104, v0
	v_mov_b32_e32 v105, v0
	v_mov_b32_e32 v106, v0
	v_mov_b32_e32 v107, v0
	v_mov_b32_e32 v108, v0
	v_mov_b32_e32 v109, v0
	v_mov_b32_e32 v110, v0
	v_mov_b32_e32 v111, v0
	v_mov_b32_e32 v112, v0
	v_mov_b32_e32 v113, v0
	v_mov_b32_e32 v114, v0
	v_mov_b32_e32 v115, v0
	v_mov_b32_e32 v116, v0
	v_mov_b32_e32 v117, v0
	v_mov_b32_e32 v118, v0
	v_mov_b32_e32 v119, v0
	v_mov_b32_e32 v120, v0
	v_mov_b32_e32 v121, v0
	v_mov_b32_e32 v122, v0
	v_mov_b32_e32 v123, v0
	v_mov_b32_e32 v124, v0
	v_mov_b32_e32 v125, v0
	v_mov_b32_e32 v126, v0
	v_mov_b32_e32 v127, v0
	v_mov_b32_e32 v190, v0
	v_mov_b32_e32 v191, v0
	v_mov_b32_e32 v192, v0
	v_mov_b32_e32 v193, v0
	v_mov_b32_e32 v194, v0
	v_mov_b32_e32 v195, v0
	v_mov_b32_e32 v196, v0
	v_mov_b32_e32 v197, v0
	v_readlane_b32 s17, v253, 49
	v_readlane_b32 s18, v253, 50
	v_readlane_b32 s19, v253, 51
	v_readlane_b32 s20, v253, 52
	v_readlane_b32 s21, v253, 53
	v_readlane_b32 s22, v253, 54
	v_readlane_b32 s23, v253, 55
	v_readlane_b32 s26, v253, 58
	v_readlane_b32 s27, v253, 59
	v_readlane_b32 s28, v253, 60
	v_readlane_b32 s29, v253, 61
	v_readlane_b32 s30, v253, 62
	v_readlane_b32 s31, v253, 63
	s_waitcnt vmcnt(0)
.LBB0_104:
	s_waitcnt lgkmcnt(0)
	s_barrier
	s_waitcnt vmcnt(11)
	ds_write_b128 v243, v[160:163] offset:36864
	s_waitcnt vmcnt(10)
	ds_write_b128 v243, v[164:167] offset:41472
	s_waitcnt vmcnt(9)
	ds_write_b128 v243, v[168:171] offset:46080
	s_waitcnt vmcnt(8)
	ds_write_b128 v243, v[172:175] offset:50688
	s_waitcnt vmcnt(7)
	ds_write_b128 v243, v[156:159]
	s_waitcnt vmcnt(6)
	ds_write_b128 v243, v[152:155] offset:4608
	s_waitcnt vmcnt(5)
	ds_write_b128 v243, v[148:151] offset:9216
	s_waitcnt vmcnt(4)
	ds_write_b128 v243, v[144:147] offset:13824
	s_waitcnt vmcnt(3)
	ds_write_b128 v243, v[140:143] offset:18432
	s_waitcnt vmcnt(2)
	ds_write_b128 v243, v[136:139] offset:23040
	s_waitcnt vmcnt(1)
	ds_write_b128 v243, v[132:135] offset:27648
	s_waitcnt vmcnt(0)
	ds_write_b128 v243, v[128:131] offset:32256
	v_add_u32_e32 v252, s2, v200
	v_add_u32_e32 v188, 0x40, v252
	v_lshl_add_u64 v[160:161], v[188:189], 1, s[24:25]
	global_load_dwordx4 v[160:163], v[160:161], off
	v_add_u32_e32 v188, 0x8040, v252
	v_lshl_add_u64 v[164:165], v[188:189], 1, s[24:25]
	global_load_dwordx4 v[164:167], v[164:165], off
	v_add_u32_e32 v188, 0x10040, v252
	v_lshl_add_u64 v[168:169], v[188:189], 1, s[24:25]
	global_load_dwordx4 v[168:171], v[168:169], off
	v_add_u32_e32 v188, 0x18040, v252
	v_lshl_add_u64 v[172:173], v[188:189], 1, s[24:25]
	global_load_dwordx4 v[172:175], v[172:173], off
	s_waitcnt lgkmcnt(0)
	s_barrier
	ds_read_b128 v[184:187], v242 offset:41472
	ds_read_b128 v[244:247], v242 offset:36864
	ds_read_b128 v[176:179], v242 offset:36896
	ds_read_b128 v[180:183], v201
	ds_read_b128 v[248:251], v201 offset:32
	v_and_b32_e32 v252, 0xffff0000, v156
	v_fmac_f32_e32 v197, v252, v252
	v_and_b32_e32 v188, 0xffff0000, v152
	v_fmac_f32_e32 v196, v188, v188
	v_lshlrev_b32_e32 v252, 16, v156
	v_fmac_f32_e32 v197, v252, v252
	v_lshlrev_b32_e32 v188, 16, v152
	v_fmac_f32_e32 v196, v188, v188
	v_and_b32_e32 v252, 0xffff0000, v157
	v_fmac_f32_e32 v197, v252, v252
	v_and_b32_e32 v188, 0xffff0000, v153
	v_fmac_f32_e32 v196, v188, v188
	v_lshlrev_b32_e32 v252, 16, v157
	v_fmac_f32_e32 v197, v252, v252
	v_lshlrev_b32_e32 v188, 16, v153
	v_fmac_f32_e32 v196, v188, v188
	v_and_b32_e32 v252, 0xffff0000, v158
	v_fmac_f32_e32 v197, v252, v252
	v_and_b32_e32 v188, 0xffff0000, v154
	v_fmac_f32_e32 v196, v188, v188
	s_waitcnt lgkmcnt(1)
	v_mfma_f32_32x32x16_bf16 v[112:127], v[180:183], v[244:247], v[112:127]
	v_mfma_f32_32x32x16_bf16 v[96:111], v[180:183], v[184:187], v[96:111]
	ds_read_b128 v[180:183], v201 offset:4608
	v_lshlrev_b32_e32 v252, 16, v158
	v_fmac_f32_e32 v197, v252, v252
	v_lshlrev_b32_e32 v188, 16, v154
	v_fmac_f32_e32 v196, v188, v188
	v_and_b32_e32 v252, 0xffff0000, v159
	v_fmac_f32_e32 v197, v252, v252
	v_and_b32_e32 v188, 0xffff0000, v155
	v_fmac_f32_e32 v196, v188, v188
	v_lshlrev_b32_e32 v252, 16, v159
	v_fmac_f32_e32 v197, v252, v252
	v_lshlrev_b32_e32 v188, 16, v155
	v_fmac_f32_e32 v196, v188, v188
	v_add_u32_e32 v188, s2, v198
	v_add_u32_e32 v188, 0x40, v188
	v_lshl_add_u64 v[156:157], v[188:189], 1, s[36:37]
	global_load_dwordx4 v[156:159], v[156:157], off
	v_add_u32_e32 v188, s2, v198
	v_add_u32_e32 v188, 0x8040, v188
	v_lshl_add_u64 v[152:153], v[188:189], 1, s[36:37]
	global_load_dwordx4 v[152:155], v[152:153], off
	s_waitcnt lgkmcnt(0)
	v_mfma_f32_32x32x16_bf16 v[80:95], v[180:183], v[244:247], v[80:95]
	v_mfma_f32_32x32x16_bf16 v[64:79], v[180:183], v[184:187], v[64:79]
	ds_read_b128 v[180:183], v201 offset:9216
	v_and_b32_e32 v252, 0xffff0000, v148
	v_fmac_f32_e32 v195, v252, v252
	v_and_b32_e32 v188, 0xffff0000, v144
	v_fmac_f32_e32 v194, v188, v188
	v_lshlrev_b32_e32 v252, 16, v148
	v_fmac_f32_e32 v195, v252, v252
	v_lshlrev_b32_e32 v188, 16, v144
	v_fmac_f32_e32 v194, v188, v188
	v_and_b32_e32 v252, 0xffff0000, v149
	v_fmac_f32_e32 v195, v252, v252
	v_and_b32_e32 v188, 0xffff0000, v145
	v_fmac_f32_e32 v194, v188, v188
	v_lshlrev_b32_e32 v252, 16, v149
	v_fmac_f32_e32 v195, v252, v252
	v_lshlrev_b32_e32 v188, 16, v145
	v_fmac_f32_e32 v194, v188, v188
	v_and_b32_e32 v252, 0xffff0000, v150
	v_fmac_f32_e32 v195, v252, v252
	v_and_b32_e32 v188, 0xffff0000, v146
	v_fmac_f32_e32 v194, v188, v188
	s_waitcnt lgkmcnt(0)
	v_mfma_f32_32x32x16_bf16 v[48:63], v[180:183], v[244:247], v[48:63]
	v_mfma_f32_32x32x16_bf16 v[32:47], v[180:183], v[184:187], v[32:47]
	ds_read_b128 v[232:235], v199
	ds_read_b128 v[180:183], v199 offset:32
	v_lshlrev_b32_e32 v252, 16, v150
	v_fmac_f32_e32 v195, v252, v252
	v_lshlrev_b32_e32 v188, 16, v146
	v_fmac_f32_e32 v194, v188, v188
	v_and_b32_e32 v252, 0xffff0000, v151
	v_fmac_f32_e32 v195, v252, v252
	v_and_b32_e32 v188, 0xffff0000, v147
	v_fmac_f32_e32 v194, v188, v188
	v_lshlrev_b32_e32 v252, 16, v151
	v_fmac_f32_e32 v195, v252, v252
	v_lshlrev_b32_e32 v188, 16, v147
	v_fmac_f32_e32 v194, v188, v188
	v_add_u32_e32 v188, s2, v198
	v_add_u32_e32 v188, 0x10040, v188
	v_lshl_add_u64 v[148:149], v[188:189], 1, s[36:37]
	global_load_dwordx4 v[148:151], v[148:149], off
	v_add_u32_e32 v188, s2, v198
	v_add_u32_e32 v188, 0x18040, v188
	v_lshl_add_u64 v[144:145], v[188:189], 1, s[36:37]
	global_load_dwordx4 v[144:147], v[144:145], off
	s_waitcnt lgkmcnt(1)
	v_mfma_f32_32x32x16_bf16 v[16:31], v[232:235], v[244:247], v[16:31]
	v_mfma_f32_32x32x16_bf16 v[0:15], v[232:235], v[184:187], v[0:15]
	ds_read_b128 v[184:187], v242 offset:41504
	ds_read_b128 v[232:235], v201 offset:4640
	v_and_b32_e32 v252, 0xffff0000, v140
	v_fmac_f32_e32 v193, v252, v252
	v_and_b32_e32 v188, 0xffff0000, v136
	v_fmac_f32_e32 v192, v188, v188
	v_lshlrev_b32_e32 v252, 16, v140
	v_fmac_f32_e32 v193, v252, v252
	v_lshlrev_b32_e32 v188, 16, v136
	v_fmac_f32_e32 v192, v188, v188
	v_and_b32_e32 v252, 0xffff0000, v141
	v_fmac_f32_e32 v193, v252, v252
	v_and_b32_e32 v188, 0xffff0000, v137
	v_fmac_f32_e32 v192, v188, v188
	v_lshlrev_b32_e32 v252, 16, v141
	v_fmac_f32_e32 v193, v252, v252
	v_lshlrev_b32_e32 v188, 16, v137
	v_fmac_f32_e32 v192, v188, v188
	v_and_b32_e32 v252, 0xffff0000, v142
	v_fmac_f32_e32 v193, v252, v252
	v_and_b32_e32 v188, 0xffff0000, v138
	v_fmac_f32_e32 v192, v188, v188
	s_waitcnt lgkmcnt(0)
	v_mfma_f32_32x32x16_bf16 v[80:95], v[232:235], v[176:179], v[80:95]
	v_mfma_f32_32x32x16_bf16 v[64:79], v[232:235], v[184:187], v[64:79]
	ds_read_b128 v[232:235], v201 offset:9248
	v_mfma_f32_32x32x16_bf16 v[112:127], v[248:251], v[176:179], v[112:127]
	v_mfma_f32_32x32x16_bf16 v[96:111], v[248:251], v[184:187], v[96:111]
	v_lshlrev_b32_e32 v252, 16, v142
	v_fmac_f32_e32 v193, v252, v252
	v_lshlrev_b32_e32 v188, 16, v138
	v_fmac_f32_e32 v192, v188, v188
	v_and_b32_e32 v252, 0xffff0000, v143
	v_fmac_f32_e32 v193, v252, v252
	v_and_b32_e32 v188, 0xffff0000, v139
	v_fmac_f32_e32 v192, v188, v188
	v_lshlrev_b32_e32 v252, 16, v143
	v_fmac_f32_e32 v193, v252, v252
	v_lshlrev_b32_e32 v188, 16, v139
	v_fmac_f32_e32 v192, v188, v188
	v_add_u32_e32 v188, s2, v198
	v_add_u32_e32 v188, 0x20040, v188
	v_lshl_add_u64 v[140:141], v[188:189], 1, s[36:37]
	global_load_dwordx4 v[140:143], v[140:141], off
	v_add_u32_e32 v188, s2, v198
	v_add_u32_e32 v188, 0x28040, v188
	v_lshl_add_u64 v[136:137], v[188:189], 1, s[36:37]
	global_load_dwordx4 v[136:139], v[136:137], off
	s_waitcnt lgkmcnt(0)
	v_mfma_f32_32x32x16_bf16 v[48:63], v[232:235], v[176:179], v[48:63]
	v_mfma_f32_32x32x16_bf16 v[32:47], v[232:235], v[184:187], v[32:47]
	v_mfma_f32_32x32x16_bf16 v[16:31], v[180:183], v[176:179], v[16:31]
	v_mfma_f32_32x32x16_bf16 v[0:15], v[180:183], v[184:187], v[0:15]
	ds_read_b128 v[176:179], v242 offset:36928
	ds_read_b128 v[180:183], v242 offset:41536
	ds_read_b128 v[184:187], v201 offset:64
	v_and_b32_e32 v252, 0xffff0000, v132
	v_fmac_f32_e32 v191, v252, v252
	v_and_b32_e32 v188, 0xffff0000, v128
	v_fmac_f32_e32 v190, v188, v188
	v_lshlrev_b32_e32 v252, 16, v132
	v_fmac_f32_e32 v191, v252, v252
	v_lshlrev_b32_e32 v188, 16, v128
	v_fmac_f32_e32 v190, v188, v188
	v_and_b32_e32 v252, 0xffff0000, v133
	v_fmac_f32_e32 v191, v252, v252
	v_and_b32_e32 v188, 0xffff0000, v129
	v_fmac_f32_e32 v190, v188, v188
	v_lshlrev_b32_e32 v252, 16, v133
	v_fmac_f32_e32 v191, v252, v252
	v_lshlrev_b32_e32 v188, 16, v129
	v_fmac_f32_e32 v190, v188, v188
	v_and_b32_e32 v252, 0xffff0000, v134
	v_fmac_f32_e32 v191, v252, v252
	v_and_b32_e32 v188, 0xffff0000, v130
	v_fmac_f32_e32 v190, v188, v188
	s_waitcnt lgkmcnt(0)
	v_mfma_f32_32x32x16_bf16 v[112:127], v[184:187], v[176:179], v[112:127]
	v_mfma_f32_32x32x16_bf16 v[96:111], v[184:187], v[180:183], v[96:111]
	ds_read_b128 v[184:187], v201 offset:4672
	v_lshlrev_b32_e32 v252, 16, v134
	v_fmac_f32_e32 v191, v252, v252
	v_lshlrev_b32_e32 v188, 16, v130
	v_fmac_f32_e32 v190, v188, v188
	v_and_b32_e32 v252, 0xffff0000, v135
	v_fmac_f32_e32 v191, v252, v252
	v_and_b32_e32 v188, 0xffff0000, v131
	v_fmac_f32_e32 v190, v188, v188
	v_lshlrev_b32_e32 v252, 16, v135
	v_fmac_f32_e32 v191, v252, v252
	v_lshlrev_b32_e32 v188, 16, v131
	v_fmac_f32_e32 v190, v188, v188
	v_add_u32_e32 v188, s2, v198
	v_add_u32_e32 v188, 0x30040, v188
	v_lshl_add_u64 v[132:133], v[188:189], 1, s[36:37]
	global_load_dwordx4 v[132:135], v[132:133], off
	v_add_u32_e32 v188, s2, v198
	v_add_u32_e32 v188, 0x38040, v188
	v_lshl_add_u64 v[128:129], v[188:189], 1, s[36:37]
	global_load_dwordx4 v[128:131], v[128:129], off
	s_waitcnt lgkmcnt(0)
	v_mfma_f32_32x32x16_bf16 v[80:95], v[184:187], v[176:179], v[80:95]
	v_mfma_f32_32x32x16_bf16 v[64:79], v[184:187], v[180:183], v[64:79]
	ds_read_b128 v[184:187], v201 offset:9280
	s_waitcnt lgkmcnt(0)
	v_mfma_f32_32x32x16_bf16 v[48:63], v[184:187], v[176:179], v[48:63]
	v_mfma_f32_32x32x16_bf16 v[32:47], v[184:187], v[180:183], v[32:47]
	ds_read_b128 v[184:187], v199 offset:64
	s_waitcnt lgkmcnt(0)
	v_mfma_f32_32x32x16_bf16 v[16:31], v[184:187], v[176:179], v[16:31]
	v_mfma_f32_32x32x16_bf16 v[0:15], v[184:187], v[180:183], v[0:15]
	ds_read_b128 v[176:179], v242 offset:36960
	ds_read_b128 v[180:183], v242 offset:41568
	ds_read_b128 v[184:187], v201 offset:96
	s_waitcnt lgkmcnt(0)
	v_mfma_f32_32x32x16_bf16 v[112:127], v[184:187], v[176:179], v[112:127]
	v_mfma_f32_32x32x16_bf16 v[96:111], v[184:187], v[180:183], v[96:111]
	ds_read_b128 v[184:187], v201 offset:4704
	s_waitcnt lgkmcnt(0)
	v_mfma_f32_32x32x16_bf16 v[80:95], v[184:187], v[176:179], v[80:95]
	v_mfma_f32_32x32x16_bf16 v[64:79], v[184:187], v[180:183], v[64:79]
	ds_read_b128 v[184:187], v201 offset:9312
	s_waitcnt lgkmcnt(0)
	v_mfma_f32_32x32x16_bf16 v[48:63], v[184:187], v[176:179], v[48:63]
	v_mfma_f32_32x32x16_bf16 v[32:47], v[184:187], v[180:183], v[32:47]
	ds_read_b128 v[184:187], v199 offset:96
	s_waitcnt lgkmcnt(0)
	v_mfma_f32_32x32x16_bf16 v[16:31], v[184:187], v[176:179], v[16:31]
	v_mfma_f32_32x32x16_bf16 v[0:15], v[184:187], v[180:183], v[0:15]
	s_add_i32 s2, s2, 64
	s_cmpk_eq_i32 s2, 0x3c0
	s_cbranch_scc0 .LBB0_104
	s_waitcnt vmcnt(0)
	s_waitcnt lgkmcnt(0)
	s_barrier
	s_waitcnt vmcnt(11)
	ds_write_b128 v243, v[156:159]
	s_waitcnt vmcnt(10)
	ds_write_b128 v243, v[152:155] offset:4608
	s_waitcnt vmcnt(9)
	ds_write_b128 v243, v[148:151] offset:9216
	s_waitcnt vmcnt(8)
	ds_write_b128 v243, v[144:147] offset:13824
	s_waitcnt vmcnt(7)
	ds_write_b128 v243, v[140:143] offset:18432
	s_waitcnt vmcnt(6)
	ds_write_b128 v243, v[136:139] offset:23040
	s_waitcnt vmcnt(5)
	ds_write_b128 v243, v[132:135] offset:27648
	s_waitcnt vmcnt(4)
	ds_write_b128 v243, v[128:131] offset:32256
	s_waitcnt vmcnt(3)
	ds_write_b128 v243, v[160:163] offset:36864
	s_waitcnt vmcnt(2)
	ds_write_b128 v243, v[164:167] offset:41472
	s_waitcnt vmcnt(1)
	ds_write_b128 v243, v[168:171] offset:46080
	s_waitcnt vmcnt(0)
	ds_write_b128 v243, v[172:175] offset:50688
	s_waitcnt lgkmcnt(0)
	s_barrier
; template <bool NORM, bool DEEP, int MTW, int KSEG, class HOOK>
; DI void gemm_core_h(const bfu* __restrict__ A, int lda, const bfu* __restrict__ Bt, int ldb, int K, int m0, int n0,
;                     f32x16 (&acc)[MTW][2], char* smem, HOOK hook) {
;     ...
;   if (DEEP) {
;     for (int kt = 0; kt < nk; kt += 2) {
;       GEMM_STEP(ra0, rb0, kt, 2)
;       GEMM_STEP(ra1, rb1, kt + 1, 2)
;     }
;   } else {
;     for (int kt = 0; kt < nk; ++kt) {
;       GEMM_STEP(ra0, rb0, kt, 1)
;       if (KSEG > 0) { if (((kt + 1) % (KSEG > 0 ? KSEG : 1)) == 0) hook((kt + 1) / (KSEG > 0 ? KSEG : 1) - 1); }
;     }
;   }
;     ...
;   if (NORM) {
; #pragma unroll
;     for (int j = 0; j < NA; ++j) {
;       float v = ssq[j];
;       v += __shfl_xor(v, 1); v += __shfl_xor(v, 2); v += __shfl_xor(v, 4);
;       if (lkc == 0) rstd_s[lrow + 32 * j] = rsqrtf(v / (float)K + EPS);
	ds_read_b128 v[160:163], v201
	ds_read_b128 v[164:167], v242 offset:36864
	ds_read_b128 v[168:171], v242 offset:41472
	s_waitcnt lgkmcnt(1)
	v_mfma_f32_32x32x16_bf16 v[112:127], v[160:163], v[164:167], v[112:127]
	v_lshlrev_b32_e32 v176, 16, v156
	v_and_b32_e32 v156, 0xffff0000, v156
	v_mul_f32_e32 v156, v156, v156
	v_fmac_f32_e32 v156, v176, v176
	v_add_f32_e32 v156, v197, v156
	s_waitcnt lgkmcnt(0)
	v_mfma_f32_32x32x16_bf16 v[96:111], v[160:163], v[168:171], v[96:111]
	ds_read_b128 v[160:163], v201 offset:4608
	s_waitcnt lgkmcnt(0)
	v_mfma_f32_32x32x16_bf16 v[80:95], v[160:163], v[164:167], v[80:95]
	v_mfma_f32_32x32x16_bf16 v[64:79], v[160:163], v[168:171], v[64:79]
	ds_read_b128 v[160:163], v201 offset:9216
	s_waitcnt lgkmcnt(0)
	v_mfma_f32_32x32x16_bf16 v[48:63], v[160:163], v[164:167], v[48:63]
	v_mfma_f32_32x32x16_bf16 v[32:47], v[160:163], v[168:171], v[32:47]
	ds_read_b128 v[160:163], v199
	s_waitcnt lgkmcnt(0)
	v_mfma_f32_32x32x16_bf16 v[16:31], v[160:163], v[164:167], v[16:31]
	v_mfma_f32_32x32x16_bf16 v[0:15], v[160:163], v[168:171], v[0:15]
	ds_read_b128 v[160:163], v201 offset:32
	ds_read_b128 v[164:167], v242 offset:36896
	ds_read_b128 v[168:171], v242 offset:41504
	s_waitcnt lgkmcnt(1)
	v_mfma_f32_32x32x16_bf16 v[112:127], v[160:163], v[164:167], v[112:127]
	s_waitcnt lgkmcnt(0)
	v_mfma_f32_32x32x16_bf16 v[96:111], v[160:163], v[168:171], v[96:111]
	ds_read_b128 v[160:163], v201 offset:4640
	s_waitcnt lgkmcnt(0)
	v_mfma_f32_32x32x16_bf16 v[80:95], v[160:163], v[164:167], v[80:95]
	v_mfma_f32_32x32x16_bf16 v[64:79], v[160:163], v[168:171], v[64:79]
	ds_read_b128 v[160:163], v201 offset:9248
	s_waitcnt lgkmcnt(0)
	v_mfma_f32_32x32x16_bf16 v[48:63], v[160:163], v[164:167], v[48:63]
	v_mfma_f32_32x32x16_bf16 v[32:47], v[160:163], v[168:171], v[32:47]
	ds_read_b128 v[160:163], v199 offset:32
	s_waitcnt lgkmcnt(0)
	v_mfma_f32_32x32x16_bf16 v[16:31], v[160:163], v[164:167], v[16:31]
	v_mfma_f32_32x32x16_bf16 v[0:15], v[160:163], v[168:171], v[0:15]
	ds_read_b128 v[160:163], v201 offset:64
	ds_read_b128 v[164:167], v242 offset:36928
	ds_read_b128 v[168:171], v242 offset:41536
	s_waitcnt lgkmcnt(1)
	v_mfma_f32_32x32x16_bf16 v[112:127], v[160:163], v[164:167], v[112:127]
	s_waitcnt lgkmcnt(0)
	v_mfma_f32_32x32x16_bf16 v[96:111], v[160:163], v[168:171], v[96:111]
	ds_read_b128 v[160:163], v201 offset:4672
	s_waitcnt lgkmcnt(0)
	v_mfma_f32_32x32x16_bf16 v[80:95], v[160:163], v[164:167], v[80:95]
	v_mfma_f32_32x32x16_bf16 v[64:79], v[160:163], v[168:171], v[64:79]
	ds_read_b128 v[160:163], v201 offset:9280
	s_waitcnt lgkmcnt(0)
	v_mfma_f32_32x32x16_bf16 v[48:63], v[160:163], v[164:167], v[48:63]
	v_mfma_f32_32x32x16_bf16 v[32:47], v[160:163], v[168:171], v[32:47]
	ds_read_b128 v[160:163], v199 offset:64
	s_waitcnt lgkmcnt(0)
	v_mfma_f32_32x32x16_bf16 v[16:31], v[160:163], v[164:167], v[16:31]
	v_mfma_f32_32x32x16_bf16 v[0:15], v[160:163], v[168:171], v[0:15]
	ds_read_b128 v[164:167], v201 offset:96
	ds_read_b128 v[168:171], v242 offset:36960
	ds_read_b128 v[160:163], v242 offset:41568
	ds_read_b128 v[172:175], v201 offset:4704
	s_waitcnt lgkmcnt(2)
	v_mfma_f32_32x32x16_bf16 v[112:127], v[164:167], v[168:171], v[112:127]
	s_waitcnt lgkmcnt(1)
	v_mfma_f32_32x32x16_bf16 v[96:111], v[164:167], v[160:163], v[96:111]
	v_lshlrev_b32_e32 v164, 16, v157
	v_and_b32_e32 v157, 0xffff0000, v157
	v_mul_f32_e32 v157, v157, v157
	v_fmac_f32_e32 v157, v164, v164
	v_add_f32_e32 v156, v157, v156
	v_lshlrev_b32_e32 v157, 16, v158
	v_and_b32_e32 v158, 0xffff0000, v158
	v_mul_f32_e32 v158, v158, v158
	ds_read_b128 v[164:167], v201 offset:9312
	v_fmac_f32_e32 v158, v157, v157
	v_add_f32_e32 v156, v158, v156
	v_and_b32_e32 v158, 0xffff0000, v159
	v_lshlrev_b32_e32 v157, 16, v159
	v_mul_f32_e32 v158, v158, v158
	v_mbcnt_hi_u32_b32 v159, -1, v226
	v_fmac_f32_e32 v158, v157, v157
	v_and_b32_e32 v157, 64, v159
	v_add_f32_e32 v158, v158, v156
	v_xor_b32_e32 v156, 1, v159
	v_add_u32_e32 v176, 64, v157
	v_cmp_lt_i32_e64 s[2:3], v156, v176
	s_waitcnt lgkmcnt(1)
	v_mfma_f32_32x32x16_bf16 v[80:95], v[172:175], v[168:171], v[80:95]
	v_xor_b32_e32 v157, 2, v159
	v_cndmask_b32_e64 v156, v159, v156, s[2:3]
	v_lshlrev_b32_e32 v156, 2, v156
	v_cmp_lt_i32_e64 s[2:3], v157, v176
	s_nop 1
	v_cndmask_b32_e64 v157, v159, v157, s[2:3]
	v_mfma_f32_32x32x16_bf16 v[64:79], v[172:175], v[160:163], v[64:79]
	ds_read_b128 v[172:175], v199 offset:96
	v_lshlrev_b32_e32 v157, 2, v157
	s_waitcnt lgkmcnt(1)
	v_mfma_f32_32x32x16_bf16 v[48:63], v[164:167], v[168:171], v[48:63]
	v_mfma_f32_32x32x16_bf16 v[32:47], v[164:167], v[160:163], v[32:47]
	ds_bpermute_b32 v164, v156, v158
	v_xor_b32_e32 v165, 4, v159
	v_cmp_lt_i32_e64 s[2:3], v165, v176
	s_waitcnt lgkmcnt(0)
	v_add_f32_e32 v164, v158, v164
	ds_bpermute_b32 v166, v157, v164
	v_mfma_f32_32x32x16_bf16 v[16:31], v[172:175], v[168:171], v[16:31]
	v_cndmask_b32_e64 v158, v159, v165, s[2:3]
	v_lshlrev_b32_e32 v159, 2, v158
	v_cmp_eq_u32_e64 s[2:3], 0, v241
	s_waitcnt lgkmcnt(0)
	v_add_f32_e32 v164, v164, v166
	ds_bpermute_b32 v165, v159, v164
	v_lshlrev_b32_e32 v158, 2, v240
	v_mfma_f32_32x32x16_bf16 v[0:15], v[172:175], v[160:163], v[0:15]
	s_and_saveexec_b64 s[8:9], s[2:3]
	s_cbranch_execz .LBB0_107
	s_waitcnt lgkmcnt(0)
	v_add_f32_e32 v160, v164, v165
	v_fmamk_f32 v160, v160, 0x3a800000, v225
	s_mov_b32 s4, 0x800000
	v_mul_f32_e32 v161, 0x4b800000, v160
	v_cmp_gt_f32_e64 s[4:5], s4, v160
	s_nop 1
	v_cndmask_b32_e64 v160, v160, v161, s[4:5]
	v_rsq_f32_e32 v160, v160
	s_nop 0
	v_mul_f32_e32 v161, 0x45800000, v160
	v_cndmask_b32_e64 v160, v160, v161, s[4:5]
	ds_write_b32 v158, v160 offset:55296

; DI float bf2f(bfu b) { return __uint_as_float(((unsigned)b) << 16); }
; #define EPI_BEGIN(accv) EPI_BEGINM(accv, 2)
; template <bool NORM, bool DEEP, int MTW, int KSEG, class HOOK>
; DI void gemm_core_h(const bfu* __restrict__ A, int lda, const bfu* __restrict__ Bt, int ldb, int K, int m0, int n0,
;                     f32x16 (&acc)[MTW][2], char* smem, HOOK hook) {
;     ...
;   if (DEEP) {
;     for (int kt = 0; kt < nk; kt += 2) {
;       GEMM_STEP(ra0, rb0, kt, 2)
;       GEMM_STEP(ra1, rb1, kt + 1, 2)
;     }
;   } else {
;     for (int kt = 0; kt < nk; ++kt) {
;       GEMM_STEP(ra0, rb0, kt, 1)
;       if (KSEG > 0) { if (((kt + 1) % (KSEG > 0 ? KSEG : 1)) == 0) hook((kt + 1) / (KSEG > 0 ? KSEG : 1) - 1); }
; DI void phase_widen(const Params& p, char* smem) {
;     ...
;     auto flush = [&](int n) {
;       EPI_BEGIN(acc) tot[mt][nt][i] += v * bf2f(p.gates[(size_t)row * 4096 + n * 1024 + col]); acc[mt][nt][i] = 0.f; EPI_END
;     };
.LBB0_137:
	s_waitcnt lgkmcnt(0)
	s_barrier
	s_waitcnt vmcnt(7)
	ds_write_b128 v133, v[68:71]
	s_waitcnt vmcnt(6)
	ds_write_b128 v133, v[64:67] offset:4608
	s_waitcnt vmcnt(5)
	ds_write_b128 v133, v[72:75] offset:9216
	s_waitcnt vmcnt(4)
	ds_write_b128 v133, v[76:79] offset:13824
	s_waitcnt vmcnt(3)
	ds_write_b128 v133, v[84:87] offset:18432
	s_waitcnt vmcnt(2)
	ds_write_b128 v133, v[80:83] offset:23040
	s_waitcnt vmcnt(1)
	ds_write_b128 v133, v[88:91] offset:27648
	s_waitcnt vmcnt(0)
	ds_write_b128 v133, v[92:95] offset:32256
	s_waitcnt lgkmcnt(0)
	s_barrier
	ds_read_b128 v[64:67], v213
	ds_read_b128 v[68:71], v129 offset:18432
	ds_read_b128 v[72:75], v129 offset:18464
	ds_read_b128 v[76:79], v213 offset:32
	ds_read_b128 v[80:83], v129 offset:23040
	ds_read_b128 v[84:87], v129 offset:23072
	s_waitcnt lgkmcnt(4)
	v_mfma_f32_32x32x16_bf16 v[48:63], v[64:67], v[68:71], v[48:63]
	s_cmpk_lg_i32 s2, 0x1e00
	s_cselect_b32 s7, s6, 0x3c0
	v_add_u32_e32 v188, s7, v128
	v_readlane_b32 s16, v253, 48
	v_readlane_b32 s20, v253, 52
	v_readlane_b32 s21, v253, 53
	v_readlane_b32 s17, v253, 49
	s_waitcnt lgkmcnt(1)
	v_mfma_f32_32x32x16_bf16 v[32:47], v[64:67], v[80:83], v[32:47]
	ds_read_b128 v[64:67], v213 offset:4608
	ds_read_b128 v[88:91], v213 offset:4640
	v_readlane_b32 s18, v253, 50
	v_readlane_b32 s19, v253, 51
	v_readlane_b32 s22, v253, 54
	v_readlane_b32 s23, v253, 55
	v_readlane_b32 s24, v253, 56
	v_readlane_b32 s25, v253, 57
	s_waitcnt lgkmcnt(1)
	v_mfma_f32_32x32x16_bf16 v[16:31], v[64:67], v[68:71], v[16:31]
	v_readlane_b32 s26, v253, 58
	v_readlane_b32 s27, v253, 59
	v_readlane_b32 s28, v253, 60
	v_readlane_b32 s29, v253, 61
	v_readlane_b32 s30, v253, 62
	v_readlane_b32 s31, v253, 63
	v_mfma_f32_32x32x16_bf16 v[0:15], v[64:67], v[80:83], v[0:15]
	v_mfma_f32_32x32x16_bf16 v[48:63], v[76:79], v[72:75], v[48:63]
	v_mfma_f32_32x32x16_bf16 v[32:47], v[76:79], v[84:87], v[32:47]
	s_waitcnt lgkmcnt(0)
	v_mfma_f32_32x32x16_bf16 v[16:31], v[88:91], v[72:75], v[16:31]
	v_mfma_f32_32x32x16_bf16 v[0:15], v[88:91], v[84:87], v[0:15]
	ds_read_b128 v[64:67], v213 offset:64
	ds_read_b128 v[68:71], v129 offset:18496
	ds_read_b128 v[88:91], v129 offset:18528
	ds_read_b128 v[80:83], v213 offset:96
	ds_read_b128 v[72:75], v129 offset:23104
	ds_read_b128 v[184:187], v129 offset:23136
	v_mov_b32_e32 v87, v189
	s_waitcnt lgkmcnt(4)
	v_mfma_f32_32x32x16_bf16 v[48:63], v[64:67], v[68:71], v[48:63]
	s_waitcnt lgkmcnt(1)
	v_mfma_f32_32x32x16_bf16 v[32:47], v[64:67], v[72:75], v[32:47]
	ds_read_b128 v[64:67], v213 offset:4672
	ds_read_b128 v[190:193], v213 offset:4704
	s_waitcnt lgkmcnt(1)
	v_mfma_f32_32x32x16_bf16 v[16:31], v[64:67], v[68:71], v[16:31]
	v_add_u32_e32 v70, 0x8000, v188
	v_mov_b32_e32 v71, v189
	v_lshl_add_u64 v[68:69], v[188:189], 1, s[74:75]
	v_lshl_add_u64 v[76:77], v[70:71], 1, s[74:75]
	v_mfma_f32_32x32x16_bf16 v[0:15], v[64:67], v[72:75], v[0:15]
	v_add_u32_e32 v72, 0x10000, v188
	v_add_u32_e32 v188, 0x18000, v188
	global_load_dwordx4 v[68:71], v[68:69], off
	s_nop 0
	global_load_dwordx4 v[64:67], v[76:77], off
	v_lshl_add_u64 v[76:77], v[188:189], 1, s[74:75]
	v_add_u32_e32 v188, s7, v132
	v_mov_b32_e32 v73, v189
	v_add_u32_e32 v86, 0x8000, v188
	v_lshl_add_u64 v[72:73], v[72:73], 1, s[74:75]
	v_lshl_add_u64 v[84:85], v[188:189], 1, s[20:21]
	v_lshl_add_u64 v[92:93], v[86:87], 1, s[20:21]
	v_mfma_f32_32x32x16_bf16 v[48:63], v[80:83], v[88:91], v[48:63]
	global_load_dwordx4 v[72:75], v[72:73], off
	s_nop 0
	global_load_dwordx4 v[76:79], v[76:77], off
	s_and_b32 s7, s5, 3
	s_cmp_lg_u32 s7, 0
	v_mfma_f32_32x32x16_bf16 v[32:47], v[80:83], v[184:187], v[32:47]
	global_load_dwordx4 v[84:87], v[84:85], off
	s_nop 0
	global_load_dwordx4 v[80:83], v[92:93], off
	v_add_u32_e32 v92, 0x10000, v188
	v_mov_b32_e32 v93, v189
	v_add_u32_e32 v188, 0x18000, v188
	v_lshl_add_u64 v[92:93], v[92:93], 1, s[20:21]
	v_lshl_add_u64 v[94:95], v[188:189], 1, s[20:21]
	s_waitcnt lgkmcnt(0)
	v_mfma_f32_32x32x16_bf16 v[16:31], v[190:193], v[88:91], v[16:31]
	global_load_dwordx4 v[88:91], v[92:93], off
	s_nop 0
	global_load_dwordx4 v[92:95], v[94:95], off
	v_mfma_f32_32x32x16_bf16 v[0:15], v[190:193], v[184:187], v[0:15]
	s_cbranch_scc1 .LBB0_136
	v_lshlrev_b32_e32 v200, 13, v96
	v_lshl_add_u32 v200, v150, 1, v200
	s_add_u32 s8, s2, 0xfffffa00
	s_add_u32 s8, s70, s8
	s_addc_u32 s9, s71, 0
	global_load_ushort v216, v200, s[8:9]
	global_load_ushort v217, v200, s[8:9] offset:64
	v_add_u32_e32 v199, 0x2000, v200
	global_load_ushort v218, v199, s[8:9]
	global_load_ushort v219, v199, s[8:9] offset:64
	v_add_u32_e32 v199, 0x4000, v200
	global_load_ushort v220, v199, s[8:9]
	global_load_ushort v221, v199, s[8:9] offset:64
	v_add_u32_e32 v199, 0x6000, v200
	global_load_ushort v223, v199, s[8:9]
	global_load_ushort v232, v199, s[8:9] offset:64
	v_add_u32_e32 v199, 0x10000, v200
	global_load_ushort v233, v199, s[8:9]
	global_load_ushort v234, v199, s[8:9] offset:64
	v_add_u32_e32 v199, 0x12000, v200
	global_load_ushort v235, v199, s[8:9]
	global_load_ushort v237, v199, s[8:9] offset:64
	v_add_u32_e32 v199, 0x14000, v200
	global_load_ushort v238, v199, s[8:9]
	global_load_ushort v239, v199, s[8:9] offset:64
	v_add_u32_e32 v199, 0x16000, v200
	global_load_ushort v240, v199, s[8:9]
	global_load_ushort v241, v199, s[8:9] offset:64
	v_add_u32_e32 v199, 0x20000, v200
	global_load_ushort v242, v199, s[8:9]
	global_load_ushort v243, v199, s[8:9] offset:64
	v_add_u32_e32 v199, 0x22000, v200
	global_load_ushort v244, v199, s[8:9]
	global_load_ushort v245, v199, s[8:9] offset:64
	v_add_u32_e32 v199, 0x24000, v200
	global_load_ushort v246, v199, s[8:9]
	global_load_ushort v247, v199, s[8:9] offset:64
; DI float bf2f(bfu b) { return __uint_as_float(((unsigned)b) << 16); }
; #define EPI_BEGIN(accv) EPI_BEGINM(accv, 2)
; DI void phase_widen(const Params& p, char* smem) {
;     ...
;     auto flush = [&](int n) {
;       EPI_BEGIN(acc) tot[mt][nt][i] += v * bf2f(p.gates[(size_t)row * 4096 + n * 1024 + col]); acc[mt][nt][i] = 0.f; EPI_END
;     };
	v_add_u32_e32 v199, 0x26000, v200
	global_load_ushort v248, v199, s[8:9]
	global_load_ushort v249, v199, s[8:9] offset:64
	v_add_u32_e32 v199, 0x30000, v200
	global_load_ushort v250, v199, s[8:9]
	global_load_ushort v251, v199, s[8:9] offset:64
	v_add_u32_e32 v199, 0x32000, v200
	global_load_ushort v252, v199, s[8:9]
	global_load_ushort v194, v199, s[8:9] offset:64
	v_add_u32_e32 v199, 0x34000, v200
	global_load_ushort v195, v199, s[8:9]
	global_load_ushort v196, v199, s[8:9] offset:64
	v_add_u32_e32 v199, 0x36000, v200
	global_load_ushort v197, v199, s[8:9]
	global_load_ushort v198, v199, s[8:9] offset:64
	v_add_u32_e32 v199, 0x40000, v200
	global_load_ushort v201, v199, s[8:9]
	global_load_ushort v202, v199, s[8:9] offset:64
	v_add_u32_e32 v199, 0x42000, v200
	global_load_ushort v203, v199, s[8:9]
	global_load_ushort v214, v199, s[8:9] offset:64
	v_add_u32_e32 v199, 0x44000, v200
	global_load_ushort v215, v199, s[8:9]
	global_load_ushort v184, v199, s[8:9] offset:64
	v_add_u32_e32 v199, 0x46000, v200
	global_load_ushort v185, v199, s[8:9]
	global_load_ushort v186, v199, s[8:9] offset:64
	v_add_u32_e32 v199, 0x50000, v200
	global_load_ushort v187, v199, s[8:9]
	global_load_ushort v190, v199, s[8:9] offset:64
	v_add_u32_e32 v199, 0x52000, v200
	global_load_ushort v191, v199, s[8:9]
	global_load_ushort v192, v199, s[8:9] offset:64
	v_add_u32_e32 v199, 0x54000, v200
	global_load_ushort v193, v199, s[8:9]
	s_waitcnt vmcnt(13)
	v_lshlrev_b32_e32 v216, 16, v216
	v_fmac_f32_e32 v182, v48, v216
	v_lshlrev_b32_e32 v217, 16, v217
	v_fmac_f32_e32 v148, v32, v217
	v_lshlrev_b32_e32 v218, 16, v218
	v_fmac_f32_e32 v183, v49, v218
	v_lshlrev_b32_e32 v219, 16, v219
	v_fmac_f32_e32 v149, v33, v219
	v_lshlrev_b32_e32 v220, 16, v220
	v_fmac_f32_e32 v180, v50, v220
	v_lshlrev_b32_e32 v221, 16, v221
	v_fmac_f32_e32 v146, v34, v221
	v_lshlrev_b32_e32 v223, 16, v223
	v_fmac_f32_e32 v181, v51, v223
	v_lshlrev_b32_e32 v232, 16, v232
	v_fmac_f32_e32 v147, v35, v232
	v_lshlrev_b32_e32 v233, 16, v233
	v_fmac_f32_e32 v178, v52, v233
	v_lshlrev_b32_e32 v234, 16, v234
	v_fmac_f32_e32 v144, v36, v234
	v_lshlrev_b32_e32 v235, 16, v235
	v_fmac_f32_e32 v179, v53, v235
	v_lshlrev_b32_e32 v237, 16, v237
	v_fmac_f32_e32 v145, v37, v237
	v_lshlrev_b32_e32 v238, 16, v238
	v_fmac_f32_e32 v176, v54, v238
	v_lshlrev_b32_e32 v239, 16, v239
	v_fmac_f32_e32 v142, v38, v239
	v_lshlrev_b32_e32 v240, 16, v240
	v_fmac_f32_e32 v177, v55, v240
	v_lshlrev_b32_e32 v241, 16, v241
	v_fmac_f32_e32 v143, v39, v241
	v_lshlrev_b32_e32 v242, 16, v242
	v_fmac_f32_e32 v170, v56, v242
	v_lshlrev_b32_e32 v243, 16, v243
	v_fmac_f32_e32 v140, v40, v243
	v_lshlrev_b32_e32 v244, 16, v244
	v_fmac_f32_e32 v171, v57, v244
	v_lshlrev_b32_e32 v245, 16, v245
	v_fmac_f32_e32 v141, v41, v245
	v_lshlrev_b32_e32 v246, 16, v246
	v_fmac_f32_e32 v164, v58, v246
	v_lshlrev_b32_e32 v247, 16, v247
	v_fmac_f32_e32 v138, v42, v247
	v_lshlrev_b32_e32 v248, 16, v248
	v_fmac_f32_e32 v165, v59, v248
	v_lshlrev_b32_e32 v249, 16, v249
	v_fmac_f32_e32 v139, v43, v249
	v_lshlrev_b32_e32 v250, 16, v250
	v_fmac_f32_e32 v158, v60, v250
	v_lshlrev_b32_e32 v251, 16, v251
	v_fmac_f32_e32 v136, v44, v251
	v_lshlrev_b32_e32 v252, 16, v252
	v_fmac_f32_e32 v159, v61, v252
	v_lshlrev_b32_e32 v194, 16, v194
	v_fmac_f32_e32 v137, v45, v194
	v_lshlrev_b32_e32 v195, 16, v195
	v_fmac_f32_e32 v152, v62, v195
	v_lshlrev_b32_e32 v196, 16, v196
	v_fmac_f32_e32 v134, v46, v196
	v_lshlrev_b32_e32 v197, 16, v197
	v_fmac_f32_e32 v153, v63, v197
	v_lshlrev_b32_e32 v198, 16, v198
	v_fmac_f32_e32 v135, v47, v198
	v_add_u32_e32 v199, 0x54000, v200
	global_load_ushort v216, v199, s[8:9] offset:64
	v_add_u32_e32 v199, 0x56000, v200
	global_load_ushort v217, v199, s[8:9]
	global_load_ushort v218, v199, s[8:9] offset:64
	v_add_u32_e32 v199, 0x60000, v200
	global_load_ushort v219, v199, s[8:9]
	global_load_ushort v220, v199, s[8:9] offset:64
	v_add_u32_e32 v199, 0x62000, v200
	global_load_ushort v221, v199, s[8:9]
	global_load_ushort v223, v199, s[8:9] offset:64
	v_add_u32_e32 v199, 0x64000, v200
	global_load_ushort v232, v199, s[8:9]
	global_load_ushort v233, v199, s[8:9] offset:64
	v_add_u32_e32 v199, 0x66000, v200
	global_load_ushort v234, v199, s[8:9]
	global_load_ushort v235, v199, s[8:9] offset:64
	v_add_u32_e32 v199, 0x70000, v200
	global_load_ushort v237, v199, s[8:9]
	global_load_ushort v238, v199, s[8:9] offset:64
	v_add_u32_e32 v199, 0x72000, v200
	global_load_ushort v239, v199, s[8:9]
	global_load_ushort v240, v199, s[8:9] offset:64
	v_add_u32_e32 v199, 0x74000, v200
	global_load_ushort v241, v199, s[8:9]
	global_load_ushort v242, v199, s[8:9] offset:64
	v_add_u32_e32 v199, 0x76000, v200
	global_load_ushort v243, v199, s[8:9]
	global_load_ushort v244, v199, s[8:9] offset:64
	s_waitcnt vmcnt(19)
; DI float bf2f(bfu b) { return __uint_as_float(((unsigned)b) << 16); }
; #define EPI_BEGIN(accv) EPI_BEGINM(accv, 2)
; DI void phase_widen(const Params& p, char* smem) {
;     ...
;     auto flush = [&](int n) {
;       EPI_BEGIN(acc) tot[mt][nt][i] += v * bf2f(p.gates[(size_t)row * 4096 + n * 1024 + col]); acc[mt][nt][i] = 0.f; EPI_END
;     };
	v_lshlrev_b32_e32 v201, 16, v201
	v_fmac_f32_e32 v130, v16, v201
	v_lshlrev_b32_e32 v202, 16, v202
	v_fmac_f32_e32 v104, v0, v202
	v_lshlrev_b32_e32 v203, 16, v203
	v_fmac_f32_e32 v131, v17, v203
	v_lshlrev_b32_e32 v214, 16, v214
	v_fmac_f32_e32 v105, v1, v214
	v_lshlrev_b32_e32 v215, 16, v215
	v_fmac_f32_e32 v126, v18, v215
	v_lshlrev_b32_e32 v184, 16, v184
	v_fmac_f32_e32 v112, v2, v184
	v_lshlrev_b32_e32 v185, 16, v185
	v_fmac_f32_e32 v127, v19, v185
	v_lshlrev_b32_e32 v186, 16, v186
	v_fmac_f32_e32 v113, v3, v186
	v_lshlrev_b32_e32 v187, 16, v187
	v_fmac_f32_e32 v124, v20, v187
	v_lshlrev_b32_e32 v190, 16, v190
	v_fmac_f32_e32 v110, v4, v190
	v_lshlrev_b32_e32 v191, 16, v191
	v_fmac_f32_e32 v125, v21, v191
	v_lshlrev_b32_e32 v192, 16, v192
	v_fmac_f32_e32 v111, v5, v192
	v_lshlrev_b32_e32 v193, 16, v193
	v_fmac_f32_e32 v122, v22, v193
	s_waitcnt vmcnt(0)
	v_lshlrev_b32_e32 v216, 16, v216
	v_fmac_f32_e32 v108, v6, v216
	v_lshlrev_b32_e32 v217, 16, v217
	v_fmac_f32_e32 v123, v23, v217
	v_lshlrev_b32_e32 v218, 16, v218
	v_fmac_f32_e32 v109, v7, v218
	v_lshlrev_b32_e32 v219, 16, v219
	v_fmac_f32_e32 v120, v24, v219
	v_lshlrev_b32_e32 v220, 16, v220
	v_fmac_f32_e32 v106, v8, v220
	v_lshlrev_b32_e32 v221, 16, v221
	v_fmac_f32_e32 v121, v25, v221
	v_lshlrev_b32_e32 v223, 16, v223
	v_fmac_f32_e32 v107, v9, v223
	v_lshlrev_b32_e32 v232, 16, v232
	v_fmac_f32_e32 v118, v26, v232
	v_lshlrev_b32_e32 v233, 16, v233
	v_fmac_f32_e32 v102, v10, v233
	v_lshlrev_b32_e32 v234, 16, v234
	v_fmac_f32_e32 v119, v27, v234
	v_lshlrev_b32_e32 v235, 16, v235
	v_fmac_f32_e32 v103, v11, v235
	v_lshlrev_b32_e32 v237, 16, v237
	v_fmac_f32_e32 v116, v28, v237
	v_lshlrev_b32_e32 v238, 16, v238
	v_fmac_f32_e32 v100, v12, v238
	v_lshlrev_b32_e32 v239, 16, v239
	v_fmac_f32_e32 v117, v29, v239
	v_lshlrev_b32_e32 v240, 16, v240
	v_fmac_f32_e32 v101, v13, v240
	v_lshlrev_b32_e32 v241, 16, v241
	v_fmac_f32_e32 v114, v30, v241
	v_lshlrev_b32_e32 v242, 16, v242
	v_fmac_f32_e32 v98, v14, v242
	v_lshlrev_b32_e32 v243, 16, v243
	v_fmac_f32_e32 v115, v31, v243
	v_lshlrev_b32_e32 v244, 16, v244
	v_fmac_f32_e32 v99, v15, v244
	v_mov_b32_e32 v0, 0
	v_mov_b32_e32 v1, v0
	v_mov_b32_e32 v2, v0
	v_mov_b32_e32 v3, v0
	v_mov_b32_e32 v4, v0
	v_mov_b32_e32 v5, v0
	v_mov_b32_e32 v6, v0
	v_mov_b32_e32 v7, v0
	v_mov_b32_e32 v8, v0
	v_mov_b32_e32 v9, v0
	v_mov_b32_e32 v10, v0
	v_mov_b32_e32 v11, v0
	v_mov_b32_e32 v12, v0
	v_mov_b32_e32 v13, v0
	v_mov_b32_e32 v14, v0
	v_mov_b32_e32 v15, v0
	v_mov_b32_e32 v16, v0
	v_mov_b32_e32 v17, v0
	v_mov_b32_e32 v18, v0
	v_mov_b32_e32 v19, v0
	v_mov_b32_e32 v20, v0
	v_mov_b32_e32 v21, v0
	v_mov_b32_e32 v22, v0
	v_mov_b32_e32 v23, v0
	v_mov_b32_e32 v24, v0
	v_mov_b32_e32 v25, v0
	v_mov_b32_e32 v26, v0
	v_mov_b32_e32 v27, v0
	v_mov_b32_e32 v28, v0
	v_mov_b32_e32 v29, v0
	v_mov_b32_e32 v30, v0
	v_mov_b32_e32 v31, v0
	v_mov_b32_e32 v32, v0
	v_mov_b32_e32 v33, v0
	v_mov_b32_e32 v34, v0
	v_mov_b32_e32 v35, v0
	v_mov_b32_e32 v36, v0
	v_mov_b32_e32 v37, v0
	v_mov_b32_e32 v38, v0
	v_mov_b32_e32 v39, v0
	v_mov_b32_e32 v40, v0
	v_mov_b32_e32 v41, v0
	v_mov_b32_e32 v42, v0
	v_mov_b32_e32 v43, v0
	v_mov_b32_e32 v44, v0
	v_mov_b32_e32 v45, v0
	v_mov_b32_e32 v46, v0
	v_mov_b32_e32 v47, v0
	v_mov_b32_e32 v48, v0
	v_mov_b32_e32 v49, v0
	v_mov_b32_e32 v50, v0
	v_mov_b32_e32 v51, v0
	v_mov_b32_e32 v52, v0
	v_mov_b32_e32 v53, v0
	v_mov_b32_e32 v54, v0
	v_mov_b32_e32 v55, v0
	v_mov_b32_e32 v56, v0
	v_mov_b32_e32 v57, v0
	v_mov_b32_e32 v58, v0
	v_mov_b32_e32 v59, v0
	v_mov_b32_e32 v60, v0
	v_mov_b32_e32 v61, v0
	v_mov_b32_e32 v62, v0
	v_mov_b32_e32 v63, v0
	s_branch .LBB0_136

; #define ZERO_ACCM(a, MT) _Pragma("unroll") for (int _m = 0; _m < MT; ++_m) _Pragma("unroll") for (int _n = 0; _n < 2; ++_n) _Pragma("unroll") for (int _i = 0; _i < 16; ++_i) a[_m][_n][_i] = 0.f;
; template <bool NORM, bool DEEP, int MTW, int KSEG, class HOOK>
; DI void gemm_core_h(const bfu* __restrict__ A, int lda, const bfu* __restrict__ Bt, int ldb, int K, int m0, int n0,
;                     f32x16 (&acc)[MTW][2], char* smem, HOOK hook) {
;     ...
; #pragma unroll
;   for (int j = 0; j < NA; ++j) ra0[j] = *(const u32x4*)AP_(j, 0);
; #pragma unroll
;   for (int j = 0; j < 4; ++j) rb0[j] = *(const u32x4*)BP_(j, 0);
; DI void phase_in(const Params& p, int L, char* smem) {
;     ...
;   for (int id = blockIdx.x; id < 64 * NT; id += gridDim.x) {
;     int tm, tn; map_tile(id, NT, tm, tn);
;     const int m0 = tm * 256, n0 = tn * 128;
;     f32x16 acc[4][2]; ZERO_ACCM(acc, 4)
;     gemm_core<true, false, 4>(p.xb2, D, p.wt_in, D, D, m0, n0, acc, smem);
.LBB0_781:
	s_ashr_i32 s2, s12, 3
	s_mul_hi_i32 s3, s2, 0x4bda12f7
	s_lshr_b32 s4, s3, 31
	s_ashr_i32 s3, s3, 7
	s_add_i32 s3, s3, s4
	s_mul_i32 s4, s3, 0x1b0
	s_lshl_b32 s5, s12, 3
	s_sub_i32 s2, s2, s4
	s_lshl_b32 s3, s3, 6
	s_and_b32 s5, s5, 56
	s_and_b32 s4, s2, 7
	s_or_b32 s23, s3, s5
	s_or_b32 s3, s23, s4
	v_mov_b32_e32 v4, v224
	s_lshl_b32 s34, s3, 8
	v_mov_b32_e32 v203, v189
	v_ashrrev_i32_e32 v193, 3, v4
	v_and_b32_e32 v210, 7, v4
	v_add_u32_e32 v0, s34, v193
	v_lshlrev_b32_e32 v5, 3, v210
	v_lshl_or_b32 v202, v0, 10, v5
	v_add_u32_e32 v188, 0x8000, v202
	v_lshl_add_u64 v[0:1], v[202:203], 1, s[38:39]
	v_lshl_add_u64 v[2:3], v[188:189], 1, s[38:39]
	v_add_u32_e32 v188, 0x10000, v202
	global_load_dwordx4 v[156:159], v[0:1], off
	global_load_dwordx4 v[152:155], v[2:3], off
	v_lshl_add_u64 v[0:1], v[188:189], 1, s[38:39]
	v_add_u32_e32 v188, 0x18000, v202
	s_ashr_i32 s6, s2, 3
	v_lshl_add_u64 v[2:3], v[188:189], 1, s[38:39]
	v_add_u32_e32 v188, 0x20000, v202
	s_lshl_b32 s33, s6, 7
	global_load_dwordx4 v[148:151], v[0:1], off
	global_load_dwordx4 v[144:147], v[2:3], off
	v_lshl_add_u64 v[0:1], v[188:189], 1, s[38:39]
	v_add_u32_e32 v188, 0x28000, v202
	v_add_u32_e32 v6, s33, v193
	v_lshl_add_u64 v[2:3], v[188:189], 1, s[38:39]
	v_add_u32_e32 v188, 0x30000, v202
	global_load_dwordx4 v[140:143], v[0:1], off
	global_load_dwordx4 v[136:139], v[2:3], off
	v_lshl_add_u64 v[0:1], v[188:189], 1, s[38:39]
	v_add_u32_e32 v188, 0x38000, v202
	v_lshl_or_b32 v204, v6, 10, v5
	v_readlane_b32 s52, v253, 32
	v_lshl_add_u64 v[2:3], v[188:189], 1, s[38:39]
	v_mov_b32_e32 v205, v189
	v_readlane_b32 s66, v253, 46
	v_readlane_b32 s67, v253, 47
	v_add_u32_e32 v188, 0x8000, v204
	global_load_dwordx4 v[132:135], v[0:1], off
	global_load_dwordx4 v[128:131], v[2:3], off
	v_lshl_add_u64 v[0:1], v[204:205], 1, s[66:67]
	v_lshl_add_u64 v[2:3], v[188:189], 1, s[66:67]
	v_add_u32_e32 v188, 0x10000, v204
	global_load_dwordx4 v[160:163], v[0:1], off
	global_load_dwordx4 v[164:167], v[2:3], off
	v_lshl_add_u64 v[0:1], v[188:189], 1, s[66:67]
	v_add_u32_e32 v188, 0x18000, v204
	v_lshl_add_u64 v[2:3], v[188:189], 1, s[66:67]
	global_load_dwordx4 v[168:171], v[0:1], off
	global_load_dwordx4 v[172:175], v[2:3], off
	v_lshrrev_b32_e32 v2, 1, v4
	v_and_b32_e32 v0, 0x5f, v4
	v_and_b32_e32 v2, 16, v2
	s_movk_i32 s2, 0x90
	v_mad_u32_u24 v211, v0, s2, v2
	v_and_b32_e32 v0, 0xfffff9f, v4
	v_mul_lo_u32 v3, v0, s2
	v_or_b32_e32 v0, 0x60, v4
	v_lshlrev_b32_e32 v1, 4, v210
	v_mul_lo_u32 v5, v193, s2
	v_mul_lo_u32 v4, v0, s2
	v_mov_b32_e32 v0, 0
	s_mov_b32 s2, 0
	v_add_u32_e32 v212, v1, v5
	v_add_u32_e32 v205, v2, v3
	v_add_u32_e32 v203, v2, v4
	v_mov_b32_e32 v1, v0
	v_mov_b32_e32 v2, v0
	v_mov_b32_e32 v3, v0
	v_mov_b32_e32 v4, v0
	v_mov_b32_e32 v5, v0
	v_mov_b32_e32 v6, v0
	v_mov_b32_e32 v7, v0
	v_mov_b32_e32 v8, v0
	v_mov_b32_e32 v9, v0
	v_mov_b32_e32 v10, v0
	v_mov_b32_e32 v11, v0
	v_mov_b32_e32 v12, v0
	v_mov_b32_e32 v13, v0
	v_mov_b32_e32 v14, v0
	v_mov_b32_e32 v15, v0
	v_mov_b32_e32 v16, v0
	v_mov_b32_e32 v17, v0
	v_mov_b32_e32 v18, v0
	v_mov_b32_e32 v19, v0
	v_mov_b32_e32 v20, v0
	v_mov_b32_e32 v21, v0
	v_mov_b32_e32 v22, v0
	v_mov_b32_e32 v23, v0
	v_mov_b32_e32 v24, v0
	v_mov_b32_e32 v25, v0
	v_mov_b32_e32 v26, v0
	v_mov_b32_e32 v27, v0
	v_mov_b32_e32 v28, v0
	v_mov_b32_e32 v29, v0
	v_mov_b32_e32 v30, v0
	v_mov_b32_e32 v31, v0
	v_mov_b32_e32 v32, v0
	v_mov_b32_e32 v33, v0
	v_mov_b32_e32 v34, v0
	v_mov_b32_e32 v35, v0
	v_mov_b32_e32 v36, v0
	v_mov_b32_e32 v37, v0
	v_mov_b32_e32 v38, v0
	v_mov_b32_e32 v39, v0
	v_mov_b32_e32 v40, v0
	v_mov_b32_e32 v41, v0
	v_mov_b32_e32 v42, v0
	v_mov_b32_e32 v43, v0
	v_mov_b32_e32 v44, v0
	v_mov_b32_e32 v45, v0
	v_mov_b32_e32 v46, v0
	v_mov_b32_e32 v47, v0
	v_mov_b32_e32 v48, v0
	v_mov_b32_e32 v49, v0
	v_mov_b32_e32 v50, v0
	v_mov_b32_e32 v51, v0
	v_mov_b32_e32 v52, v0
	v_mov_b32_e32 v53, v0
	v_mov_b32_e32 v54, v0
	v_mov_b32_e32 v55, v0
	v_mov_b32_e32 v56, v0
	v_mov_b32_e32 v57, v0
	v_mov_b32_e32 v58, v0
	v_mov_b32_e32 v59, v0
	v_mov_b32_e32 v60, v0
	v_mov_b32_e32 v61, v0
	v_mov_b32_e32 v62, v0
	v_mov_b32_e32 v63, v0
	s_waitcnt vmcnt(27)
	v_mov_b32_e32 v64, v0
	v_mov_b32_e32 v65, v0
	v_mov_b32_e32 v66, v0
	v_mov_b32_e32 v67, v0
	s_waitcnt vmcnt(26)
	v_mov_b32_e32 v68, v0
	v_mov_b32_e32 v69, v0
	v_mov_b32_e32 v70, v0
	v_mov_b32_e32 v71, v0
	s_waitcnt vmcnt(17)
	v_mov_b32_e32 v72, v0
	v_mov_b32_e32 v73, v0
	v_mov_b32_e32 v74, v0
	v_mov_b32_e32 v75, v0
	s_waitcnt vmcnt(16)
	v_mov_b32_e32 v76, v0
	v_mov_b32_e32 v77, v0
	v_mov_b32_e32 v78, v0
	v_mov_b32_e32 v79, v0
	s_waitcnt vmcnt(14)
	v_mov_b32_e32 v80, v0
	v_mov_b32_e32 v81, v0
	v_mov_b32_e32 v82, v0
	v_mov_b32_e32 v83, v0
	v_mov_b32_e32 v84, v0
	v_mov_b32_e32 v85, v0
	v_mov_b32_e32 v86, v0
	v_mov_b32_e32 v87, v0
	s_waitcnt vmcnt(13)
	v_mov_b32_e32 v88, v0
	v_mov_b32_e32 v89, v0
	v_mov_b32_e32 v90, v0
	v_mov_b32_e32 v91, v0
	s_waitcnt vmcnt(12)
	v_mov_b32_e32 v92, v0
	v_mov_b32_e32 v93, v0
	v_mov_b32_e32 v94, v0
	v_mov_b32_e32 v95, v0
	v_mov_b32_e32 v96, v0
	v_mov_b32_e32 v97, v0
	v_mov_b32_e32 v98, v0
	v_mov_b32_e32 v99, v0
	v_mov_b32_e32 v100, v0
	v_mov_b32_e32 v101, v0
	v_mov_b32_e32 v102, v0
	v_mov_b32_e32 v103, v0
	v_mov_b32_e32 v104, v0
	v_mov_b32_e32 v105, v0
	v_mov_b32_e32 v106, v0
	v_mov_b32_e32 v107, v0
	v_mov_b32_e32 v108, v0
	v_mov_b32_e32 v109, v0
	v_mov_b32_e32 v110, v0
	v_mov_b32_e32 v111, v0
	v_mov_b32_e32 v112, v0
	v_mov_b32_e32 v113, v0
	v_mov_b32_e32 v114, v0
	v_mov_b32_e32 v115, v0
	v_mov_b32_e32 v116, v0
	v_mov_b32_e32 v117, v0
	v_mov_b32_e32 v118, v0
	v_mov_b32_e32 v119, v0
	v_mov_b32_e32 v120, v0
	v_mov_b32_e32 v121, v0
	v_mov_b32_e32 v122, v0
	v_mov_b32_e32 v123, v0
	v_mov_b32_e32 v124, v0
	v_mov_b32_e32 v125, v0
	v_mov_b32_e32 v126, v0
	v_mov_b32_e32 v127, v0
	v_mov_b32_e32 v194, v0
	v_mov_b32_e32 v195, v0
	v_mov_b32_e32 v196, v0
	v_mov_b32_e32 v197, v0
	v_mov_b32_e32 v198, v0
	v_mov_b32_e32 v199, v0
	v_mov_b32_e32 v200, v0
	v_mov_b32_e32 v201, v0
	v_readlane_b32 s53, v253, 33
	v_readlane_b32 s54, v253, 34
	v_readlane_b32 s55, v253, 35
	v_readlane_b32 s56, v253, 36
	v_readlane_b32 s57, v253, 37
	v_readlane_b32 s58, v253, 38
	v_readlane_b32 s59, v253, 39
	v_readlane_b32 s60, v253, 40
	v_readlane_b32 s61, v253, 41
	v_readlane_b32 s62, v253, 42
	v_readlane_b32 s63, v253, 43
	v_readlane_b32 s64, v253, 44
	v_readlane_b32 s65, v253, 45
	s_waitcnt vmcnt(0)
.LBB0_782:
	s_waitcnt lgkmcnt(0)
	s_barrier
	v_readlane_b32 s52, v253, 32
	v_readlane_b32 s66, v253, 46
	v_readlane_b32 s67, v253, 47
	v_readlane_b32 s53, v253, 33
	v_readlane_b32 s54, v253, 34
	v_readlane_b32 s55, v253, 35
	v_readlane_b32 s56, v253, 36
	v_readlane_b32 s57, v253, 37
	v_readlane_b32 s58, v253, 38
	v_readlane_b32 s59, v253, 39
	v_readlane_b32 s60, v253, 40
	v_readlane_b32 s61, v253, 41
	v_readlane_b32 s62, v253, 42
	v_readlane_b32 s63, v253, 43
	v_readlane_b32 s64, v253, 44
	v_readlane_b32 s65, v253, 45
	s_waitcnt vmcnt(11)
	ds_write_b128 v212, v[160:163] offset:36864
	s_waitcnt vmcnt(10)
	ds_write_b128 v212, v[164:167] offset:41472
	s_waitcnt vmcnt(9)
	ds_write_b128 v212, v[168:171] offset:46080
	s_waitcnt vmcnt(8)
	ds_write_b128 v212, v[172:175] offset:50688
	s_waitcnt vmcnt(7)
	ds_write_b128 v212, v[156:159]
	s_waitcnt vmcnt(6)
	ds_write_b128 v212, v[152:155] offset:4608
	s_waitcnt vmcnt(5)
	ds_write_b128 v212, v[148:151] offset:9216
	s_waitcnt vmcnt(4)
	ds_write_b128 v212, v[144:147] offset:13824
	s_waitcnt vmcnt(3)
	ds_write_b128 v212, v[140:143] offset:18432
	s_waitcnt vmcnt(2)
	ds_write_b128 v212, v[136:139] offset:23040
	s_waitcnt vmcnt(1)
	ds_write_b128 v212, v[132:135] offset:27648
	s_waitcnt vmcnt(0)
	ds_write_b128 v212, v[128:131] offset:32256
	v_add_u32_e32 v252, s2, v204
	v_add_u32_e32 v188, 0x40, v252
	v_lshl_add_u64 v[160:161], v[188:189], 1, s[66:67]
	global_load_dwordx4 v[160:163], v[160:161], off
	v_add_u32_e32 v188, 0x8040, v252
	v_lshl_add_u64 v[164:165], v[188:189], 1, s[66:67]
	global_load_dwordx4 v[164:167], v[164:165], off
	v_add_u32_e32 v188, 0x10040, v252
	v_lshl_add_u64 v[168:169], v[188:189], 1, s[66:67]
	global_load_dwordx4 v[168:171], v[168:169], off
	v_add_u32_e32 v188, 0x18040, v252
	v_lshl_add_u64 v[172:173], v[188:189], 1, s[66:67]
	global_load_dwordx4 v[172:175], v[172:173], off
	s_waitcnt lgkmcnt(0)
	s_barrier
	ds_read_b128 v[184:187], v211 offset:41472
	ds_read_b128 v[214:217], v211 offset:36864
	ds_read_b128 v[176:179], v211 offset:36896
	ds_read_b128 v[180:183], v205
	ds_read_b128 v[218:221], v205 offset:32
	v_and_b32_e32 v252, 0xffff0000, v156
	v_fmac_f32_e32 v201, v252, v252
	v_and_b32_e32 v188, 0xffff0000, v152
	v_fmac_f32_e32 v200, v188, v188
	v_lshlrev_b32_e32 v252, 16, v156
	v_fmac_f32_e32 v201, v252, v252
	v_lshlrev_b32_e32 v188, 16, v152
	v_fmac_f32_e32 v200, v188, v188
	v_and_b32_e32 v252, 0xffff0000, v157
	v_fmac_f32_e32 v201, v252, v252
	v_and_b32_e32 v188, 0xffff0000, v153
	v_fmac_f32_e32 v200, v188, v188
	v_lshlrev_b32_e32 v252, 16, v157
	v_fmac_f32_e32 v201, v252, v252
	v_lshlrev_b32_e32 v188, 16, v153
	v_fmac_f32_e32 v200, v188, v188
	v_and_b32_e32 v252, 0xffff0000, v158
	v_fmac_f32_e32 v201, v252, v252
	v_and_b32_e32 v188, 0xffff0000, v154
	v_fmac_f32_e32 v200, v188, v188
	s_waitcnt lgkmcnt(1)
	v_mfma_f32_32x32x16_bf16 v[112:127], v[180:183], v[214:217], v[112:127]
	v_mfma_f32_32x32x16_bf16 v[96:111], v[180:183], v[184:187], v[96:111]
	ds_read_b128 v[180:183], v205 offset:4608
	v_lshlrev_b32_e32 v252, 16, v158
	v_fmac_f32_e32 v201, v252, v252
	v_lshlrev_b32_e32 v188, 16, v154
	v_fmac_f32_e32 v200, v188, v188
	v_and_b32_e32 v252, 0xffff0000, v159
	v_fmac_f32_e32 v201, v252, v252
	v_and_b32_e32 v188, 0xffff0000, v155
	v_fmac_f32_e32 v200, v188, v188
	v_lshlrev_b32_e32 v252, 16, v159
	v_fmac_f32_e32 v201, v252, v252
	v_lshlrev_b32_e32 v188, 16, v155
	v_fmac_f32_e32 v200, v188, v188
	v_add_u32_e32 v188, s2, v202
	v_add_u32_e32 v188, 0x40, v188
	v_lshl_add_u64 v[156:157], v[188:189], 1, s[38:39]
	global_load_dwordx4 v[156:159], v[156:157], off
	v_add_u32_e32 v188, s2, v202
	v_add_u32_e32 v188, 0x8040, v188
	v_lshl_add_u64 v[152:153], v[188:189], 1, s[38:39]
	global_load_dwordx4 v[152:155], v[152:153], off
	s_waitcnt lgkmcnt(0)
	v_mfma_f32_32x32x16_bf16 v[80:95], v[180:183], v[214:217], v[80:95]
	v_mfma_f32_32x32x16_bf16 v[64:79], v[180:183], v[184:187], v[64:79]
	ds_read_b128 v[180:183], v205 offset:9216
	v_and_b32_e32 v252, 0xffff0000, v148
	v_fmac_f32_e32 v199, v252, v252
	v_and_b32_e32 v188, 0xffff0000, v144
	v_fmac_f32_e32 v198, v188, v188
	v_lshlrev_b32_e32 v252, 16, v148
	v_fmac_f32_e32 v199, v252, v252
	v_lshlrev_b32_e32 v188, 16, v144
	v_fmac_f32_e32 v198, v188, v188
	v_and_b32_e32 v252, 0xffff0000, v149
	v_fmac_f32_e32 v199, v252, v252
	v_and_b32_e32 v188, 0xffff0000, v145
	v_fmac_f32_e32 v198, v188, v188
	v_lshlrev_b32_e32 v252, 16, v149
	v_fmac_f32_e32 v199, v252, v252
	v_lshlrev_b32_e32 v188, 16, v145
	v_fmac_f32_e32 v198, v188, v188
	v_and_b32_e32 v252, 0xffff0000, v150
	v_fmac_f32_e32 v199, v252, v252
	v_and_b32_e32 v188, 0xffff0000, v146
	v_fmac_f32_e32 v198, v188, v188
	s_waitcnt lgkmcnt(0)
	v_mfma_f32_32x32x16_bf16 v[48:63], v[180:183], v[214:217], v[48:63]
	v_mfma_f32_32x32x16_bf16 v[32:47], v[180:183], v[184:187], v[32:47]
	ds_read_b128 v[238:241], v203
	ds_read_b128 v[180:183], v203 offset:32
	v_lshlrev_b32_e32 v252, 16, v150
	v_fmac_f32_e32 v199, v252, v252
	v_lshlrev_b32_e32 v188, 16, v146
	v_fmac_f32_e32 v198, v188, v188
	v_and_b32_e32 v252, 0xffff0000, v151
	v_fmac_f32_e32 v199, v252, v252
	v_and_b32_e32 v188, 0xffff0000, v147
	v_fmac_f32_e32 v198, v188, v188
	v_lshlrev_b32_e32 v252, 16, v151
	v_fmac_f32_e32 v199, v252, v252
	v_lshlrev_b32_e32 v188, 16, v147
	v_fmac_f32_e32 v198, v188, v188
	v_add_u32_e32 v188, s2, v202
	v_add_u32_e32 v188, 0x10040, v188
	v_lshl_add_u64 v[148:149], v[188:189], 1, s[38:39]
	global_load_dwordx4 v[148:151], v[148:149], off
	v_add_u32_e32 v188, s2, v202
	v_add_u32_e32 v188, 0x18040, v188
	v_lshl_add_u64 v[144:145], v[188:189], 1, s[38:39]
	global_load_dwordx4 v[144:147], v[144:145], off
	s_waitcnt lgkmcnt(1)
	v_mfma_f32_32x32x16_bf16 v[16:31], v[238:241], v[214:217], v[16:31]
	ds_read_b128 v[214:217], v205 offset:4640
	v_mfma_f32_32x32x16_bf16 v[0:15], v[238:241], v[184:187], v[0:15]
	ds_read_b128 v[184:187], v211 offset:41504
	v_and_b32_e32 v252, 0xffff0000, v140
	v_fmac_f32_e32 v197, v252, v252
	v_and_b32_e32 v188, 0xffff0000, v136
	v_fmac_f32_e32 v196, v188, v188
	v_lshlrev_b32_e32 v252, 16, v140
	v_fmac_f32_e32 v197, v252, v252
	v_lshlrev_b32_e32 v188, 16, v136
	v_fmac_f32_e32 v196, v188, v188
	v_and_b32_e32 v252, 0xffff0000, v141
	v_fmac_f32_e32 v197, v252, v252
	v_and_b32_e32 v188, 0xffff0000, v137
	v_fmac_f32_e32 v196, v188, v188
	v_lshlrev_b32_e32 v252, 16, v141
	v_fmac_f32_e32 v197, v252, v252
	v_lshlrev_b32_e32 v188, 16, v137
	v_fmac_f32_e32 v196, v188, v188
	v_and_b32_e32 v252, 0xffff0000, v142
	v_fmac_f32_e32 v197, v252, v252
	v_and_b32_e32 v188, 0xffff0000, v138
	v_fmac_f32_e32 v196, v188, v188
	s_waitcnt lgkmcnt(1)
	v_mfma_f32_32x32x16_bf16 v[80:95], v[214:217], v[176:179], v[80:95]
	v_lshlrev_b32_e32 v252, 16, v142
	v_fmac_f32_e32 v197, v252, v252
	v_lshlrev_b32_e32 v188, 16, v138
	v_fmac_f32_e32 v196, v188, v188
	v_and_b32_e32 v252, 0xffff0000, v143
	v_fmac_f32_e32 v197, v252, v252
	v_and_b32_e32 v188, 0xffff0000, v139
	v_fmac_f32_e32 v196, v188, v188
	v_lshlrev_b32_e32 v252, 16, v143
	v_fmac_f32_e32 v197, v252, v252
	v_lshlrev_b32_e32 v188, 16, v139
	v_fmac_f32_e32 v196, v188, v188
	v_add_u32_e32 v188, s2, v202
	v_add_u32_e32 v188, 0x20040, v188
	v_lshl_add_u64 v[140:141], v[188:189], 1, s[38:39]
	global_load_dwordx4 v[140:143], v[140:141], off
	v_add_u32_e32 v188, s2, v202
	v_add_u32_e32 v188, 0x28040, v188
	v_lshl_add_u64 v[136:137], v[188:189], 1, s[38:39]
	global_load_dwordx4 v[136:139], v[136:137], off
	s_waitcnt lgkmcnt(0)
	v_mfma_f32_32x32x16_bf16 v[64:79], v[214:217], v[184:187], v[64:79]
	ds_read_b128 v[214:217], v205 offset:9248
	v_mfma_f32_32x32x16_bf16 v[112:127], v[218:221], v[176:179], v[112:127]
	v_mfma_f32_32x32x16_bf16 v[96:111], v[218:221], v[184:187], v[96:111]
	v_and_b32_e32 v252, 0xffff0000, v132
	v_fmac_f32_e32 v195, v252, v252
	v_and_b32_e32 v188, 0xffff0000, v128
	v_fmac_f32_e32 v194, v188, v188
	v_lshlrev_b32_e32 v252, 16, v132
	v_fmac_f32_e32 v195, v252, v252
	v_lshlrev_b32_e32 v188, 16, v128
	v_fmac_f32_e32 v194, v188, v188
	v_and_b32_e32 v252, 0xffff0000, v133
	v_fmac_f32_e32 v195, v252, v252
	v_and_b32_e32 v188, 0xffff0000, v129
	v_fmac_f32_e32 v194, v188, v188
	v_lshlrev_b32_e32 v252, 16, v133
	v_fmac_f32_e32 v195, v252, v252
	v_lshlrev_b32_e32 v188, 16, v129
	v_fmac_f32_e32 v194, v188, v188
	v_and_b32_e32 v252, 0xffff0000, v134
	v_fmac_f32_e32 v195, v252, v252
	v_and_b32_e32 v188, 0xffff0000, v130
	v_fmac_f32_e32 v194, v188, v188
	s_waitcnt lgkmcnt(0)
	v_mfma_f32_32x32x16_bf16 v[48:63], v[214:217], v[176:179], v[48:63]
	v_mfma_f32_32x32x16_bf16 v[32:47], v[214:217], v[184:187], v[32:47]
	v_mfma_f32_32x32x16_bf16 v[16:31], v[180:183], v[176:179], v[16:31]
	v_mfma_f32_32x32x16_bf16 v[0:15], v[180:183], v[184:187], v[0:15]
	ds_read_b128 v[176:179], v211 offset:36928
	ds_read_b128 v[180:183], v211 offset:41536
	ds_read_b128 v[184:187], v205 offset:64
	v_lshlrev_b32_e32 v252, 16, v134
	v_fmac_f32_e32 v195, v252, v252
	v_lshlrev_b32_e32 v188, 16, v130
	v_fmac_f32_e32 v194, v188, v188
	v_and_b32_e32 v252, 0xffff0000, v135
	v_fmac_f32_e32 v195, v252, v252
	v_and_b32_e32 v188, 0xffff0000, v131
	v_fmac_f32_e32 v194, v188, v188
	v_lshlrev_b32_e32 v252, 16, v135
	v_fmac_f32_e32 v195, v252, v252
	v_lshlrev_b32_e32 v188, 16, v131
	v_fmac_f32_e32 v194, v188, v188
	v_add_u32_e32 v188, s2, v202
	v_add_u32_e32 v188, 0x30040, v188
	v_lshl_add_u64 v[132:133], v[188:189], 1, s[38:39]
	global_load_dwordx4 v[132:135], v[132:133], off
	v_add_u32_e32 v188, s2, v202
	v_add_u32_e32 v188, 0x38040, v188
	v_lshl_add_u64 v[128:129], v[188:189], 1, s[38:39]
	global_load_dwordx4 v[128:131], v[128:129], off
	s_waitcnt lgkmcnt(0)
	v_mfma_f32_32x32x16_bf16 v[112:127], v[184:187], v[176:179], v[112:127]
	v_mfma_f32_32x32x16_bf16 v[96:111], v[184:187], v[180:183], v[96:111]
	ds_read_b128 v[184:187], v205 offset:4672
	s_waitcnt lgkmcnt(0)
	v_mfma_f32_32x32x16_bf16 v[80:95], v[184:187], v[176:179], v[80:95]
	v_mfma_f32_32x32x16_bf16 v[64:79], v[184:187], v[180:183], v[64:79]
	ds_read_b128 v[184:187], v205 offset:9280
	s_waitcnt lgkmcnt(0)
	v_mfma_f32_32x32x16_bf16 v[48:63], v[184:187], v[176:179], v[48:63]
	v_mfma_f32_32x32x16_bf16 v[32:47], v[184:187], v[180:183], v[32:47]
	ds_read_b128 v[184:187], v203 offset:64
	s_waitcnt lgkmcnt(0)
	v_mfma_f32_32x32x16_bf16 v[16:31], v[184:187], v[176:179], v[16:31]
	v_mfma_f32_32x32x16_bf16 v[0:15], v[184:187], v[180:183], v[0:15]
	ds_read_b128 v[176:179], v211 offset:36960
	ds_read_b128 v[180:183], v211 offset:41568
	ds_read_b128 v[184:187], v205 offset:96
	s_waitcnt lgkmcnt(0)
	v_mfma_f32_32x32x16_bf16 v[112:127], v[184:187], v[176:179], v[112:127]
	v_mfma_f32_32x32x16_bf16 v[96:111], v[184:187], v[180:183], v[96:111]
	ds_read_b128 v[184:187], v205 offset:4704
	s_waitcnt lgkmcnt(0)
	v_mfma_f32_32x32x16_bf16 v[80:95], v[184:187], v[176:179], v[80:95]
	v_mfma_f32_32x32x16_bf16 v[64:79], v[184:187], v[180:183], v[64:79]
	ds_read_b128 v[184:187], v205 offset:9312
	s_waitcnt lgkmcnt(0)
	v_mfma_f32_32x32x16_bf16 v[48:63], v[184:187], v[176:179], v[48:63]
	v_mfma_f32_32x32x16_bf16 v[32:47], v[184:187], v[180:183], v[32:47]
	ds_read_b128 v[184:187], v203 offset:96
	s_waitcnt lgkmcnt(0)
	v_mfma_f32_32x32x16_bf16 v[16:31], v[184:187], v[176:179], v[16:31]
	v_mfma_f32_32x32x16_bf16 v[0:15], v[184:187], v[180:183], v[0:15]
	s_add_i32 s2, s2, 64
	s_cmpk_eq_i32 s2, 0x3c0
	s_cbranch_scc0 .LBB0_782
; template <bool NORM, bool DEEP, int MTW, int KSEG, class HOOK>
; DI void gemm_core_h(const bfu* __restrict__ A, int lda, const bfu* __restrict__ Bt, int ldb, int K, int m0, int n0,
;                     f32x16 (&acc)[MTW][2], char* smem, HOOK hook) {
;     ...
;   if (DEEP) {
;     for (int kt = 0; kt < nk; kt += 2) {
;       GEMM_STEP(ra0, rb0, kt, 2)
;       GEMM_STEP(ra1, rb1, kt + 1, 2)
;     }
;   } else {
;     for (int kt = 0; kt < nk; ++kt) {
;       GEMM_STEP(ra0, rb0, kt, 1)
;       if (KSEG > 0) { if (((kt + 1) % (KSEG > 0 ? KSEG : 1)) == 0) hook((kt + 1) / (KSEG > 0 ? KSEG : 1) - 1); }
;     }
;   }
;     ...
;   if (NORM) {
; #pragma unroll
;     for (int j = 0; j < NA; ++j) {
;       float v = ssq[j];
;       v += __shfl_xor(v, 1); v += __shfl_xor(v, 2); v += __shfl_xor(v, 4);
;       if (lkc == 0) rstd_s[lrow + 32 * j] = rsqrtf(v / (float)K + EPS);
	s_waitcnt vmcnt(0)
	s_waitcnt lgkmcnt(0)
	s_barrier
	s_waitcnt vmcnt(11)
	ds_write_b128 v212, v[156:159]
	s_waitcnt vmcnt(10)
	ds_write_b128 v212, v[152:155] offset:4608
	s_waitcnt vmcnt(9)
	ds_write_b128 v212, v[148:151] offset:9216
	s_waitcnt vmcnt(8)
	ds_write_b128 v212, v[144:147] offset:13824
	s_waitcnt vmcnt(7)
	ds_write_b128 v212, v[140:143] offset:18432
	s_waitcnt vmcnt(6)
	ds_write_b128 v212, v[136:139] offset:23040
	s_waitcnt vmcnt(5)
	ds_write_b128 v212, v[132:135] offset:27648
	s_waitcnt vmcnt(4)
	ds_write_b128 v212, v[128:131] offset:32256
	s_waitcnt vmcnt(3)
	ds_write_b128 v212, v[160:163] offset:36864
	s_waitcnt vmcnt(2)
	ds_write_b128 v212, v[164:167] offset:41472
	s_waitcnt vmcnt(1)
	ds_write_b128 v212, v[168:171] offset:46080
	s_waitcnt vmcnt(0)
	ds_write_b128 v212, v[172:175] offset:50688
	s_waitcnt lgkmcnt(0)
	s_barrier
	ds_read_b128 v[160:163], v205
	ds_read_b128 v[164:167], v211 offset:36864
	ds_read_b128 v[168:171], v211 offset:41472
	s_waitcnt lgkmcnt(1)
	v_mfma_f32_32x32x16_bf16 v[112:127], v[160:163], v[164:167], v[112:127]
	s_waitcnt lgkmcnt(0)
	v_mfma_f32_32x32x16_bf16 v[96:111], v[160:163], v[168:171], v[96:111]
	ds_read_b128 v[160:163], v205 offset:4608
	s_waitcnt lgkmcnt(0)
	v_mfma_f32_32x32x16_bf16 v[80:95], v[160:163], v[164:167], v[80:95]
	v_mfma_f32_32x32x16_bf16 v[64:79], v[160:163], v[168:171], v[64:79]
	ds_read_b128 v[160:163], v205 offset:9216
	s_waitcnt lgkmcnt(0)
	v_mfma_f32_32x32x16_bf16 v[48:63], v[160:163], v[164:167], v[48:63]
	v_mfma_f32_32x32x16_bf16 v[32:47], v[160:163], v[168:171], v[32:47]
	ds_read_b128 v[160:163], v203
	s_waitcnt lgkmcnt(0)
	v_mfma_f32_32x32x16_bf16 v[16:31], v[160:163], v[164:167], v[16:31]
	v_mfma_f32_32x32x16_bf16 v[0:15], v[160:163], v[168:171], v[0:15]
	ds_read_b128 v[160:163], v205 offset:32
	ds_read_b128 v[164:167], v211 offset:36896
	ds_read_b128 v[168:171], v211 offset:41504
	s_waitcnt lgkmcnt(1)
	v_mfma_f32_32x32x16_bf16 v[112:127], v[160:163], v[164:167], v[112:127]
	s_waitcnt lgkmcnt(0)
	v_mfma_f32_32x32x16_bf16 v[96:111], v[160:163], v[168:171], v[96:111]
	ds_read_b128 v[160:163], v205 offset:4640
	s_waitcnt lgkmcnt(0)
	v_mfma_f32_32x32x16_bf16 v[80:95], v[160:163], v[164:167], v[80:95]
	v_mfma_f32_32x32x16_bf16 v[64:79], v[160:163], v[168:171], v[64:79]
	ds_read_b128 v[160:163], v205 offset:9248
	s_waitcnt lgkmcnt(0)
	v_mfma_f32_32x32x16_bf16 v[48:63], v[160:163], v[164:167], v[48:63]
	v_mfma_f32_32x32x16_bf16 v[32:47], v[160:163], v[168:171], v[32:47]
	ds_read_b128 v[160:163], v203 offset:32
	s_waitcnt lgkmcnt(0)
	v_mfma_f32_32x32x16_bf16 v[16:31], v[160:163], v[164:167], v[16:31]
	v_mfma_f32_32x32x16_bf16 v[0:15], v[160:163], v[168:171], v[0:15]
	ds_read_b128 v[160:163], v205 offset:64
	ds_read_b128 v[164:167], v211 offset:36928
	ds_read_b128 v[168:171], v211 offset:41536
	s_waitcnt lgkmcnt(1)
	v_mfma_f32_32x32x16_bf16 v[112:127], v[160:163], v[164:167], v[112:127]
	s_waitcnt lgkmcnt(0)
	v_mfma_f32_32x32x16_bf16 v[96:111], v[160:163], v[168:171], v[96:111]
	ds_read_b128 v[160:163], v205 offset:4672
	s_waitcnt lgkmcnt(0)
	v_mfma_f32_32x32x16_bf16 v[80:95], v[160:163], v[164:167], v[80:95]
	v_mfma_f32_32x32x16_bf16 v[64:79], v[160:163], v[168:171], v[64:79]
	ds_read_b128 v[160:163], v205 offset:9280
	s_waitcnt lgkmcnt(0)
	v_mfma_f32_32x32x16_bf16 v[48:63], v[160:163], v[164:167], v[48:63]
	v_mfma_f32_32x32x16_bf16 v[32:47], v[160:163], v[168:171], v[32:47]
	ds_read_b128 v[160:163], v203 offset:64
	s_waitcnt lgkmcnt(0)
	v_mfma_f32_32x32x16_bf16 v[16:31], v[160:163], v[164:167], v[16:31]
	v_mfma_f32_32x32x16_bf16 v[0:15], v[160:163], v[168:171], v[0:15]
	ds_read_b128 v[168:171], v205 offset:96
	ds_read_b128 v[164:167], v211 offset:36960
	ds_read_b128 v[160:163], v211 offset:41568
	ds_read_b128 v[172:175], v205 offset:4704
	s_waitcnt lgkmcnt(2)
	v_mfma_f32_32x32x16_bf16 v[112:127], v[168:171], v[164:167], v[112:127]
	s_waitcnt lgkmcnt(1)
	v_mfma_f32_32x32x16_bf16 v[96:111], v[168:171], v[160:163], v[96:111]
	v_lshlrev_b32_e32 v168, 16, v156
	v_and_b32_e32 v156, 0xffff0000, v156
	v_mul_f32_e32 v156, v156, v156
	v_fmac_f32_e32 v156, v168, v168
	v_lshlrev_b32_e32 v168, 16, v157
	v_and_b32_e32 v157, 0xffff0000, v157
	v_mul_f32_e32 v157, v157, v157
	v_add_f32_e32 v156, v201, v156
	v_fmac_f32_e32 v157, v168, v168
	v_add_f32_e32 v156, v157, v156
	v_lshlrev_b32_e32 v157, 16, v158
	v_and_b32_e32 v158, 0xffff0000, v158
	v_mul_f32_e32 v158, v158, v158
	ds_read_b128 v[168:171], v205 offset:9312
	v_fmac_f32_e32 v158, v157, v157
	v_add_f32_e32 v156, v158, v156
	v_and_b32_e32 v158, 0xffff0000, v159
	v_lshlrev_b32_e32 v157, 16, v159
	v_mul_f32_e32 v158, v158, v158
	v_fmac_f32_e32 v158, v157, v157
	v_and_b32_e32 v157, 64, v227
	s_waitcnt lgkmcnt(1)
	v_mfma_f32_32x32x16_bf16 v[80:95], v[172:175], v[164:167], v[80:95]
	v_add_f32_e32 v158, v158, v156
	v_xor_b32_e32 v156, 1, v227
	v_add_u32_e32 v159, 64, v157
	v_cmp_lt_i32_e32 vcc, v156, v159
	v_xor_b32_e32 v157, 2, v227
	s_nop 0
	v_cndmask_b32_e32 v156, v227, v156, vcc
	v_mfma_f32_32x32x16_bf16 v[64:79], v[172:175], v[160:163], v[64:79]
	ds_read_b128 v[172:175], v203 offset:96
	v_lshlrev_b32_e32 v156, 2, v156
	v_cmp_lt_i32_e32 vcc, v157, v159
	s_nop 1
	v_cndmask_b32_e32 v157, v227, v157, vcc
	v_lshlrev_b32_e32 v157, 2, v157
	s_waitcnt lgkmcnt(1)
	v_mfma_f32_32x32x16_bf16 v[48:63], v[168:171], v[164:167], v[48:63]
	v_mfma_f32_32x32x16_bf16 v[32:47], v[168:171], v[160:163], v[32:47]
	ds_bpermute_b32 v168, v156, v158
	v_xor_b32_e32 v169, 4, v227
	v_cmp_lt_i32_e32 vcc, v169, v159
	s_waitcnt lgkmcnt(1)
	v_mfma_f32_32x32x16_bf16 v[16:31], v[172:175], v[164:167], v[16:31]
	s_waitcnt lgkmcnt(0)
	v_add_f32_e32 v164, v158, v168
	ds_bpermute_b32 v165, v157, v164
	v_cndmask_b32_e32 v158, v227, v169, vcc
	v_lshlrev_b32_e32 v159, 2, v158
	v_cmp_eq_u32_e32 vcc, 0, v210
	v_lshlrev_b32_e32 v158, 2, v193
	s_waitcnt lgkmcnt(0)
	v_add_f32_e32 v164, v164, v165
	v_mfma_f32_32x32x16_bf16 v[0:15], v[172:175], v[160:163], v[0:15]
	ds_bpermute_b32 v165, v159, v164
	s_and_saveexec_b64 s[4:5], vcc
	s_cbranch_execz .LBB0_785
	s_waitcnt lgkmcnt(0)
	v_add_f32_e32 v160, v164, v165
	v_fmamk_f32 v160, v160, 0x3a800000, v225
	s_mov_b32 s2, 0x800000
	v_mul_f32_e32 v161, 0x4b800000, v160
	v_cmp_gt_f32_e64 s[2:3], s2, v160
	s_nop 1
	v_cndmask_b32_e64 v160, v160, v161, s[2:3]
	v_rsq_f32_e32 v160, v160
	s_nop 0
	v_mul_f32_e32 v161, 0x45800000, v160
	v_cndmask_b32_e64 v160, v160, v161, s[2:3]
	ds_write_b32 v158, v160 offset:55296
